# conv epilogue: each lane's two 8-B pieces of a row written as one dwordx4 (8 stores per wave and tile instead of 16)
# speedup vs baseline: 1.0166x; 1.0018x over previous
.LBB0_381:
	v_cmp_eq_u32_e64 s[42:43], 0, v199
	v_cmp_eq_u32_e64 s[44:45], 15, v199
	s_movk_i32 s2, 0xb00
	s_waitcnt lgkmcnt(4)
	v_cndmask_b32_e64 v185, v236, v185, s[42:43]
	v_cndmask_b32_e64 v184, v238, v184, s[42:43]
	v_cndmask_b32_e64 v183, v251, v183, s[42:43]
	v_cndmask_b32_e64 v182, v247, v182, s[42:43]
	v_pk_mul_f32 v[184:185], v[172:173], v[184:185]
	v_cndmask_b32_e64 v215, v215, v222, s[44:45]
	v_cndmask_b32_e64 v214, v214, v229, s[44:45]
	v_pk_mul_f32 v[182:183], v[170:171], v[182:183]
	v_pk_fma_f32 v[152:153], v[152:153], v[168:169], v[184:185]
	v_cndmask_b32_e64 v213, v213, v224, s[44:45]
	v_cndmask_b32_e64 v212, v212, v231, s[44:45]
	v_pk_fma_f32 v[150:151], v[150:151], v[166:167], v[182:183]
	v_pk_fma_f32 v[152:153], v[164:165], v[214:215], v[152:153]
	v_pk_fma_f32 v[150:151], v[162:163], v[212:213], v[150:151]
	v_pk_add_f32 v[212:213], v[160:161], v[152:153]
	v_cndmask_b32_e64 v153, v248, v251, s[42:43]
	v_cndmask_b32_e64 v152, v245, v247, s[42:43]
	v_pk_add_f32 v[214:215], v[158:159], v[150:151]
	v_cndmask_b32_e64 v151, v235, v236, s[42:43]
	v_cndmask_b32_e64 v150, v252, v238, s[42:43]
	v_pk_mul_f32 v[152:153], v[170:171], v[152:153]
	v_cndmask_b32_e64 v185, v224, v237, s[44:45]
	v_cndmask_b32_e64 v184, v231, v250, s[44:45]
	v_pk_mul_f32 v[150:151], v[172:173], v[150:151]
	v_pk_fma_f32 v[152:153], v[220:221], v[166:167], v[152:153]
	v_cndmask_b32_e64 v183, v222, v230, s[44:45]
	v_cndmask_b32_e64 v182, v229, v234, s[44:45]
	v_pk_fma_f32 v[150:151], v[210:211], v[168:169], v[150:151]
	v_pk_fma_f32 v[152:153], v[162:163], v[184:185], v[152:153]
	v_pk_fma_f32 v[150:151], v[164:165], v[182:183], v[150:151]
	v_pk_add_f32 v[210:211], v[158:159], v[152:153]
	v_cndmask_b32_e64 v153, v201, v248, s[42:43]
	v_cndmask_b32_e64 v152, v0, v245, s[42:43]
	v_pk_add_f32 v[184:185], v[160:161], v[150:151]
	v_cndmask_b32_e64 v151, v244, v235, s[42:43]
	v_cndmask_b32_e64 v150, v242, v252, s[42:43]
	v_pk_mul_f32 v[152:153], v[170:171], v[152:153]
	v_cndmask_b32_e64 v221, v237, v243, s[44:45]
	v_cndmask_b32_e64 v220, v250, v241, s[44:45]
	v_pk_mul_f32 v[150:151], v[172:173], v[150:151]
	v_pk_fma_f32 v[152:153], v[218:219], v[166:167], v[152:153]
	v_cndmask_b32_e64 v183, v230, v249, s[44:45]
	v_cndmask_b32_e64 v182, v234, v246, s[44:45]
	v_pk_fma_f32 v[150:151], v[216:217], v[168:169], v[150:151]
	v_pk_fma_f32 v[216:217], v[162:163], v[220:221], v[152:153]
	v_pk_fma_f32 v[150:151], v[164:165], v[182:183], v[150:151]
	v_pk_add_f32 v[182:183], v[158:159], v[216:217]
	v_cndmask_b32_e64 v217, v228, v201, s[42:43]
	v_cndmask_b32_e64 v216, v253, v0, s[42:43]
	v_pk_add_f32 v[152:153], v[160:161], v[150:151]
	v_cndmask_b32_e64 v151, v233, v244, s[42:43]
	v_cndmask_b32_e64 v150, v232, v242, s[42:43]
	v_pk_mul_f32 v[170:171], v[170:171], v[216:217]
	v_cndmask_b32_e64 v175, v243, v175, s[44:45]
	v_cndmask_b32_e64 v174, v241, v174, s[44:45]
	v_pk_mul_f32 v[150:151], v[172:173], v[150:151]
	v_pk_fma_f32 v[142:143], v[142:143], v[166:167], v[170:171]
	v_cndmask_b32_e64 v177, v249, v177, s[44:45]
	v_cndmask_b32_e64 v176, v246, v176, s[44:45]
	v_pk_fma_f32 v[144:145], v[144:145], v[168:169], v[150:151]
	v_pk_fma_f32 v[150:151], v[162:163], v[174:175], v[142:143]
	v_or_b32_e32 v0, s52, v206
	v_pk_fma_f32 v[142:143], v[164:165], v[176:177], v[144:145]
	v_pk_add_f32 v[144:145], v[158:159], v[150:151]
	v_mad_u64_u32 v[150:151], s[2:3], v208, s2, v[0:1]
	v_mov_b32_e32 v158, v202
	v_mov_b32_e32 v159, v202
	v_mov_b32_e32 v203, v202
	v_pk_fma_f32 v[96:97], v[96:97], v[158:159], v[108:109]
	v_mov_b32_e32 v158, v204
	v_mov_b32_e32 v159, v204
	v_mov_b32_dpp v0, v146 row_ror:1 row_mask:0xf bank_mask:0xf
	v_mov_b32_dpp v151, v147 row_ror:1 row_mask:0xf bank_mask:0xf
	v_mov_b32_dpp v166, v148 row_ror:1 row_mask:0xf bank_mask:0xf
	v_mov_b32_dpp v167, v149 row_ror:1 row_mask:0xf bank_mask:0xf
	v_pk_add_f32 v[142:143], v[160:161], v[142:143]
	v_pk_fma_f32 v[94:95], v[94:95], v[202:203], v[106:107]
	v_pk_fma_f32 v[92:93], v[92:93], v[158:159], v[108:109]
	s_waitcnt lgkmcnt(0)
	v_cndmask_b32_e64 v159, v167, v181, s[42:43]
	v_cndmask_b32_e64 v158, v166, v180, s[42:43]
	v_cndmask_b32_e64 v161, v151, v179, s[42:43]
	v_cndmask_b32_e64 v160, v0, v178, s[42:43]
	v_mov_b32_dpp v164, v146 row_ror:15 row_mask:0xf bank_mask:0xf
	v_mov_b32_dpp v165, v147 row_ror:15 row_mask:0xf bank_mask:0xf
	v_mov_b32_dpp v162, v148 row_ror:15 row_mask:0xf bank_mask:0xf
	v_mov_b32_dpp v163, v149 row_ror:15 row_mask:0xf bank_mask:0xf
	v_mov_b32_dpp v168, v94 row_ror:15 row_mask:0xf bank_mask:0xf
	v_mov_b32_dpp v169, v95 row_ror:15 row_mask:0xf bank_mask:0xf
	v_mov_b32_dpp v170, v96 row_ror:15 row_mask:0xf bank_mask:0xf
	v_mov_b32_dpp v171, v97 row_ror:15 row_mask:0xf bank_mask:0xf
	v_pk_mul_f32 v[160:161], v[126:127], v[160:161]
	v_pk_mul_f32 v[158:159], v[128:129], v[158:159]
	v_cndmask_b32_e64 v163, v163, v171, s[44:45]
	v_cndmask_b32_e64 v162, v162, v170, s[44:45]
	v_cndmask_b32_e64 v165, v165, v169, s[44:45]
	v_cndmask_b32_e64 v164, v164, v168, s[44:45]
	v_pk_fma_f32 v[148:149], v[148:149], v[124:125], v[158:159]
	v_pk_fma_f32 v[146:147], v[146:147], v[122:123], v[160:161]
	v_mov_b32_e32 v205, v204
	v_pk_fma_f32 v[146:147], v[102:103], v[164:165], v[146:147]
	v_pk_fma_f32 v[148:149], v[104:105], v[162:163], v[148:149]
	v_mov_b32_dpp v172, v94 row_ror:1 row_mask:0xf bank_mask:0xf
	v_mov_b32_dpp v173, v95 row_ror:1 row_mask:0xf bank_mask:0xf
	v_mov_b32_dpp v174, v96 row_ror:1 row_mask:0xf bank_mask:0xf
	v_mov_b32_dpp v175, v97 row_ror:1 row_mask:0xf bank_mask:0xf
	v_pk_fma_f32 v[90:91], v[90:91], v[204:205], v[106:107]
	v_pk_add_f32 v[158:159], v[100:101], v[148:149]
	v_pk_add_f32 v[160:161], v[98:99], v[146:147]
	v_cndmask_b32_e64 v147, v175, v167, s[42:43]
	v_cndmask_b32_e64 v146, v174, v166, s[42:43]
	v_cndmask_b32_e64 v149, v173, v151, s[42:43]
	v_cndmask_b32_e64 v148, v172, v0, s[42:43]
	v_mov_b32_dpp v176, v90 row_ror:15 row_mask:0xf bank_mask:0xf
	v_mov_b32_dpp v177, v91 row_ror:15 row_mask:0xf bank_mask:0xf
	v_mov_b32_dpp v178, v92 row_ror:15 row_mask:0xf bank_mask:0xf
	v_mov_b32_dpp v179, v93 row_ror:15 row_mask:0xf bank_mask:0xf
	v_pk_mul_f32 v[146:147], v[128:129], v[146:147]
	v_pk_mul_f32 v[148:149], v[126:127], v[148:149]
	v_cndmask_b32_e64 v163, v171, v179, s[44:45]
	v_cndmask_b32_e64 v162, v170, v178, s[44:45]
	v_cndmask_b32_e64 v165, v169, v177, s[44:45]
	v_cndmask_b32_e64 v164, v168, v176, s[44:45]
	v_pk_fma_f32 v[96:97], v[96:97], v[124:125], v[146:147]
	v_pk_fma_f32 v[94:95], v[94:95], v[122:123], v[148:149]
	v_pk_fma_f32 v[96:97], v[104:105], v[162:163], v[96:97]
	v_pk_fma_f32 v[94:95], v[102:103], v[164:165], v[94:95]
	v_mov_b32_dpp v0, v90 row_ror:1 row_mask:0xf bank_mask:0xf
	v_mov_b32_dpp v151, v91 row_ror:1 row_mask:0xf bank_mask:0xf
	v_mov_b32_dpp v166, v92 row_ror:1 row_mask:0xf bank_mask:0xf
	v_mov_b32_dpp v167, v93 row_ror:1 row_mask:0xf bank_mask:0xf
	v_pk_add_f32 v[146:147], v[100:101], v[96:97]
	v_pk_add_f32 v[148:149], v[98:99], v[94:95]
	v_cndmask_b32_e64 v95, v167, v175, s[42:43]
	v_cndmask_b32_e64 v94, v166, v174, s[42:43]
	v_cndmask_b32_e64 v97, v151, v173, s[42:43]
	v_cndmask_b32_e64 v96, v0, v172, s[42:43]
	v_mov_b32_dpp v168, v134 row_ror:15 row_mask:0xf bank_mask:0xf
	v_mov_b32_dpp v169, v135 row_ror:15 row_mask:0xf bank_mask:0xf
	v_mov_b32_dpp v170, v136 row_ror:15 row_mask:0xf bank_mask:0xf
	v_mov_b32_dpp v171, v137 row_ror:15 row_mask:0xf bank_mask:0xf
	v_pk_mul_f32 v[94:95], v[128:129], v[94:95]
	v_pk_mul_f32 v[96:97], v[126:127], v[96:97]
	v_cndmask_b32_e64 v163, v179, v171, s[44:45]
	v_cndmask_b32_e64 v162, v178, v170, s[44:45]
	v_cndmask_b32_e64 v165, v177, v169, s[44:45]
	v_cndmask_b32_e64 v164, v176, v168, s[44:45]
	v_pk_fma_f32 v[92:93], v[92:93], v[124:125], v[94:95]
	v_pk_fma_f32 v[90:91], v[90:91], v[122:123], v[96:97]
	v_pk_fma_f32 v[92:93], v[104:105], v[162:163], v[92:93]
	v_pk_fma_f32 v[90:91], v[102:103], v[164:165], v[90:91]
	v_pk_add_f32 v[94:95], v[100:101], v[92:93]
	v_pk_add_f32 v[96:97], v[98:99], v[90:91]
	v_mov_b32_dpp v92, v134 row_ror:1 row_mask:0xf bank_mask:0xf
	v_mov_b32_dpp v93, v135 row_ror:1 row_mask:0xf bank_mask:0xf
	v_mov_b32_dpp v90, v136 row_ror:1 row_mask:0xf bank_mask:0xf
	v_mov_b32_dpp v91, v137 row_ror:1 row_mask:0xf bank_mask:0xf
	v_cndmask_b32_e64 v91, v91, v167, s[42:43]
	v_cndmask_b32_e64 v90, v90, v166, s[42:43]
	v_cndmask_b32_e64 v93, v93, v151, s[42:43]
	v_cndmask_b32_e64 v92, v92, v0, s[42:43]
	v_pk_mul_f32 v[90:91], v[128:129], v[90:91]
	v_pk_mul_f32 v[92:93], v[126:127], v[92:93]
	v_cndmask_b32_e64 v157, v171, v157, s[44:45]
	v_cndmask_b32_e64 v156, v170, v156, s[44:45]
	v_cndmask_b32_e64 v155, v169, v155, s[44:45]
	v_cndmask_b32_e64 v154, v168, v154, s[44:45]
	v_pk_fma_f32 v[90:91], v[136:137], v[124:125], v[90:91]
	v_pk_fma_f32 v[92:93], v[134:135], v[122:123], v[92:93]
	v_pk_fma_f32 v[90:91], v[104:105], v[156:157], v[90:91]
	v_pk_fma_f32 v[92:93], v[102:103], v[154:155], v[92:93]
	v_pk_add_f32 v[90:91], v[100:101], v[90:91]
	v_pk_add_f32 v[92:93], v[98:99], v[92:93]
	v_mul_f32_e32 v0, 0xbfb8aa3b, v214
	v_mul_f32_e32 v98, 0xbfb8aa3b, v215
	v_exp_f32_e32 v0, v0
	v_exp_f32_e32 v98, v98
	v_mul_f32_e32 v99, 0xbfb8aa3b, v212
	v_mul_f32_e32 v100, 0xbfb8aa3b, v213
	v_exp_f32_e32 v99, v99
	v_exp_f32_e32 v100, v100
	v_add_f32_e32 v0, 1.0, v0
	v_add_f32_e32 v98, 1.0, v98
	v_rcp_f32_e32 v0, v0
	v_rcp_f32_e32 v98, v98
	v_add_f32_e32 v99, 1.0, v99
	v_add_f32_e32 v100, 1.0, v100
	v_rcp_f32_e32 v99, v99
	v_rcp_f32_e32 v100, v100
	v_mul_f32_e32 v0, v214, v0
	v_mul_f32_e32 v98, v215, v98
	v_mul_f32_e32 v0, v0, v160
	v_mul_f32_e32 v98, v98, v161
	v_mul_f32_e32 v99, v212, v99
	v_mul_f32_e32 v100, v213, v100
	v_mul_f32_e32 v99, v99, v158
	v_mul_f32_e32 v100, v100, v159
	v_cvt_pk_bf16_f32 v218, v0, v98
	v_mov_b32_e32 v0, v150
	v_cvt_pk_bf16_f32 v219, v99, v100
	s_nop 0
	v_lshl_add_u64 v[100:101], v[0:1], 1, s[62:63]
	s_nop 0
	v_mul_f32_e32 v0, 0xbfb8aa3b, v210
	v_mul_f32_e32 v98, 0xbfb8aa3b, v211
	v_exp_f32_e32 v0, v0
	v_exp_f32_e32 v98, v98
	v_mul_f32_e32 v99, 0xbfb8aa3b, v184
	v_exp_f32_e32 v99, v99
	v_mul_f32_e32 v100, 0xbfb8aa3b, v185
	v_exp_f32_e32 v100, v100
	v_add_f32_e32 v0, 1.0, v0
	v_add_f32_e32 v98, 1.0, v98
	v_rcp_f32_e32 v0, v0
	v_rcp_f32_e32 v98, v98
	v_add_f32_e32 v99, 1.0, v99
	v_rcp_f32_e32 v99, v99
	v_add_f32_e32 v100, 1.0, v100
	v_rcp_f32_e32 v100, v100
	v_mul_f32_e32 v0, v210, v0
	v_mul_f32_e32 v98, v211, v98
	v_mul_f32_e32 v0, v0, v148
	v_mul_f32_e32 v98, v98, v149
	v_mul_f32_e32 v99, v184, v99
	v_mul_f32_e32 v99, v99, v146
	v_mul_f32_e32 v100, v185, v100
	v_cvt_pk_bf16_f32 v228, v0, v98
	v_mov_b32_e32 v0, v150
	v_mul_f32_e32 v100, v100, v147
	v_cvt_pk_bf16_f32 v229, v99, v100
	s_nop 0
	v_add_u32_e32 v0, 0xb000, v0
	v_lshl_add_u64 v[100:101], v[0:1], 1, s[62:63]
	v_mul_f32_e32 v0, 0xbfb8aa3b, v182
	v_exp_f32_e32 v0, v0
	s_nop 0
	v_add_f32_e32 v0, 1.0, v0
	v_rcp_f32_e32 v0, v0
	s_nop 0
	v_mul_f32_e32 v0, v182, v0
	v_mul_f32_e32 v0, v0, v96
	v_mul_f32_e32 v96, 0xbfb8aa3b, v183
	v_exp_f32_e32 v96, v96
	s_nop 0
	v_add_f32_e32 v96, 1.0, v96
	v_rcp_f32_e32 v96, v96
	s_nop 0
	v_mul_f32_e32 v96, v183, v96
	v_mul_f32_e32 v96, v96, v97
	v_mul_f32_e32 v97, 0xbfb8aa3b, v152
	v_exp_f32_e32 v97, v97
	s_nop 0
	v_add_f32_e32 v97, 1.0, v97
	v_rcp_f32_e32 v97, v97
	s_nop 0
	v_mul_f32_e32 v97, v152, v97
	v_mul_f32_e32 v97, v97, v94
	v_mul_f32_e32 v94, 0xbfb8aa3b, v153
	v_exp_f32_e32 v94, v94
	s_nop 0
	v_add_f32_e32 v94, 1.0, v94
	v_rcp_f32_e32 v94, v94
	s_nop 0
	v_mul_f32_e32 v94, v153, v94
	v_mul_f32_e32 v95, v94, v95
	v_cvt_pk_bf16_f32 v232, v0, v96
	v_mov_b32_e32 v0, v150
	v_cvt_pk_bf16_f32 v233, v97, v95
	s_nop 0
	v_add_u32_e32 v0, 0x16000, v0
	v_lshl_add_u64 v[96:97], v[0:1], 1, s[62:63]
	v_mul_f32_e32 v0, 0xbfb8aa3b, v144
	v_exp_f32_e32 v0, v0
	s_nop 0
	v_add_f32_e32 v0, 1.0, v0
	v_rcp_f32_e32 v0, v0
	s_nop 0
	v_mul_f32_e32 v0, v144, v0
	v_mul_f32_e32 v0, v0, v92
	v_mul_f32_e32 v92, 0xbfb8aa3b, v145
	v_exp_f32_e32 v92, v92
	s_nop 0
	v_add_f32_e32 v92, 1.0, v92
	v_rcp_f32_e32 v92, v92
	s_nop 0
	v_mul_f32_e32 v92, v145, v92
	v_mul_f32_e32 v92, v92, v93
	v_mul_f32_e32 v93, 0xbfb8aa3b, v142
	v_exp_f32_e32 v93, v93
	s_nop 0
	v_add_f32_e32 v93, 1.0, v93
	v_rcp_f32_e32 v93, v93
	s_nop 0
	v_mul_f32_e32 v93, v142, v93
	v_mul_f32_e32 v93, v93, v90
	v_mul_f32_e32 v90, 0xbfb8aa3b, v143
	v_exp_f32_e32 v90, v90
	s_nop 0
	v_add_f32_e32 v90, 1.0, v90
	v_rcp_f32_e32 v90, v90
	s_nop 0
	v_mul_f32_e32 v90, v143, v90
	v_mul_f32_e32 v91, v90, v91
	v_cvt_pk_bf16_f32 v242, v0, v92
	v_mov_b32_e32 v0, v150
	v_cvt_pk_bf16_f32 v243, v93, v91
	s_nop 0
	v_add_u32_e32 v0, 0x21000, v0
	v_lshl_add_u64 v[92:93], v[0:1], 1, s[62:63]
	s_nop 0
	ds_read_b128 v[134:137], v209
	ds_read_b128 v[126:129], v209 offset:512
	ds_read_b128 v[122:125], v209 offset:1024
	ds_read_b128 v[102:105], v209 offset:1536
	v_cndmask_b32_e64 v0, 0, 1, s[36:37]
	v_mov_b32_e32 v142, 0
	v_cmp_ne_u32_e64 s[50:51], 1, v0
	s_andn2_b64 vcc, exec, s[36:37]
	v_mov_b32_e32 v146, 0
	v_mov_b32_e32 v147, 0
	v_mov_b32_e32 v148, 0
	v_mov_b32_e32 v149, 0
	s_cbranch_vccnz .LBB0_383
	ds_read_b128 v[146:149], v240 offset:3072

.LBB0_389:
	s_waitcnt lgkmcnt(4)
	v_cndmask_b32_e64 v149, v182, v149, s[42:43]
	v_cndmask_b32_e64 v148, v178, v148, s[42:43]
	v_cndmask_b32_e64 v147, v174, v147, s[42:43]
	v_cndmask_b32_e64 v146, v170, v146, s[42:43]
	v_pk_mul_f32 v[148:149], v[136:137], v[148:149]
	v_cndmask_b32_e64 v155, v155, v211, s[44:45]
	v_cndmask_b32_e64 v154, v154, v210, s[44:45]
	v_pk_mul_f32 v[146:147], v[134:135], v[146:147]
	v_pk_fma_f32 v[132:133], v[132:133], v[128:129], v[148:149]
	v_cndmask_b32_e64 v153, v153, v208, s[44:45]
	v_cndmask_b32_e64 v152, v152, v185, s[44:45]
	v_pk_fma_f32 v[130:131], v[130:131], v[126:127], v[146:147]
	v_pk_fma_f32 v[132:133], v[124:125], v[154:155], v[132:133]
	v_pk_fma_f32 v[130:131], v[122:123], v[152:153], v[130:131]
	v_pk_add_f32 v[152:153], v[104:105], v[132:133]
	v_cndmask_b32_e64 v133, v171, v174, s[42:43]
	v_cndmask_b32_e64 v132, v168, v170, s[42:43]
	v_pk_add_f32 v[154:155], v[102:103], v[130:131]
	v_cndmask_b32_e64 v131, v179, v182, s[42:43]
	v_cndmask_b32_e64 v130, v175, v178, s[42:43]
	v_pk_mul_f32 v[132:133], v[134:135], v[132:133]
	v_cndmask_b32_e64 v149, v208, v177, s[44:45]
	v_cndmask_b32_e64 v148, v185, v173, s[44:45]
	v_pk_mul_f32 v[130:131], v[136:137], v[130:131]
	v_pk_fma_f32 v[132:133], v[162:163], v[126:127], v[132:133]
	v_cndmask_b32_e64 v147, v211, v184, s[44:45]
	v_cndmask_b32_e64 v146, v210, v181, s[44:45]
	v_pk_fma_f32 v[130:131], v[160:161], v[128:129], v[130:131]
	v_pk_fma_f32 v[132:133], v[122:123], v[148:149], v[132:133]
	v_pk_fma_f32 v[130:131], v[124:125], v[146:147], v[130:131]
	v_pk_add_f32 v[148:149], v[102:103], v[132:133]
	v_cndmask_b32_e64 v133, v151, v171, s[42:43]
	v_cndmask_b32_e64 v132, v0, v168, s[42:43]
	v_pk_add_f32 v[146:147], v[104:105], v[130:131]
	v_cndmask_b32_e64 v131, v167, v179, s[42:43]
	v_cndmask_b32_e64 v130, v165, v175, s[42:43]
	v_pk_mul_f32 v[132:133], v[134:135], v[132:133]
	v_pk_mul_f32 v[130:131], v[136:137], v[130:131]
	v_pk_fma_f32 v[132:133], v[158:159], v[126:127], v[132:133]
	v_cndmask_b32_e64 v159, v180, v151, s[42:43]
	v_cndmask_b32_e64 v158, v176, v0, s[42:43]
	v_pk_fma_f32 v[130:131], v[156:157], v[128:129], v[130:131]
	v_cndmask_b32_e64 v157, v206, v167, s[42:43]
	v_cndmask_b32_e64 v156, v183, v165, s[42:43]
	v_pk_mul_f32 v[134:135], v[134:135], v[158:159]
	v_cndmask_b32_e64 v163, v177, v166, s[44:45]
	v_cndmask_b32_e64 v162, v173, v164, s[44:45]
	v_cndmask_b32_e64 v143, v166, v143, s[44:45]
	v_cndmask_b32_e64 v142, v164, v142, s[44:45]
	v_pk_mul_f32 v[136:137], v[136:137], v[156:157]
	v_pk_fma_f32 v[118:119], v[118:119], v[126:127], v[134:135]
	v_cndmask_b32_e64 v161, v184, v172, s[44:45]
	v_cndmask_b32_e64 v160, v181, v169, s[44:45]
	v_pk_fma_f32 v[132:133], v[122:123], v[162:163], v[132:133]
	v_cndmask_b32_e64 v145, v172, v145, s[44:45]
	v_cndmask_b32_e64 v144, v169, v144, s[44:45]
	v_pk_fma_f32 v[120:121], v[120:121], v[128:129], v[136:137]
	v_pk_fma_f32 v[118:119], v[122:123], v[142:143], v[118:119]
	v_pk_fma_f32 v[130:131], v[124:125], v[160:161], v[130:131]
	v_pk_add_f32 v[132:133], v[102:103], v[132:133]
	v_pk_fma_f32 v[120:121], v[124:125], v[144:145], v[120:121]
	v_pk_add_f32 v[102:103], v[102:103], v[118:119]
	v_mov_b32_e32 v118, v198
	v_mov_b32_e32 v119, v198
	v_mov_b32_e32 v199, v198
	v_mov_b32_e32 v201, v200
	v_pk_fma_f32 v[64:65], v[64:65], v[118:119], v[108:109]
	v_mov_b32_e32 v118, v200
	v_mov_b32_e32 v119, v200
	v_mov_b32_dpp v0, v114 row_ror:1 row_mask:0xf bank_mask:0xf
	v_mov_b32_dpp v122, v115 row_ror:1 row_mask:0xf bank_mask:0xf
	v_mov_b32_dpp v123, v116 row_ror:1 row_mask:0xf bank_mask:0xf
	v_mov_b32_dpp v124, v117 row_ror:1 row_mask:0xf bank_mask:0xf
	v_pk_add_f32 v[130:131], v[104:105], v[130:131]
	v_pk_add_f32 v[104:105], v[104:105], v[120:121]
	v_pk_fma_f32 v[62:63], v[62:63], v[198:199], v[106:107]
	v_pk_fma_f32 v[60:61], v[60:61], v[118:119], v[108:109]
	v_pk_fma_f32 v[58:59], v[58:59], v[200:201], v[106:107]
	s_waitcnt lgkmcnt(0)
	v_cndmask_b32_e64 v107, v122, v139, s[42:43]
	v_cndmask_b32_e64 v106, v0, v138, s[42:43]
	v_cndmask_b32_e64 v109, v124, v141, s[42:43]
	v_cndmask_b32_e64 v108, v123, v140, s[42:43]
	v_mov_b32_dpp v120, v114 row_ror:15 row_mask:0xf bank_mask:0xf
	v_mov_b32_dpp v121, v115 row_ror:15 row_mask:0xf bank_mask:0xf
	v_mov_b32_dpp v118, v116 row_ror:15 row_mask:0xf bank_mask:0xf
	v_mov_b32_dpp v119, v117 row_ror:15 row_mask:0xf bank_mask:0xf
	v_mov_b32_dpp v125, v62 row_ror:15 row_mask:0xf bank_mask:0xf
	v_mov_b32_dpp v126, v63 row_ror:15 row_mask:0xf bank_mask:0xf
	v_mov_b32_dpp v127, v64 row_ror:15 row_mask:0xf bank_mask:0xf
	v_mov_b32_dpp v128, v65 row_ror:15 row_mask:0xf bank_mask:0xf
	v_pk_mul_f32 v[108:109], v[96:97], v[108:109]
	v_pk_mul_f32 v[106:107], v[94:95], v[106:107]
	v_cndmask_b32_e64 v119, v119, v128, s[44:45]
	v_cndmask_b32_e64 v118, v118, v127, s[44:45]
	v_cndmask_b32_e64 v121, v121, v126, s[44:45]
	v_cndmask_b32_e64 v120, v120, v125, s[44:45]
	v_pk_fma_f32 v[106:107], v[114:115], v[90:91], v[106:107]
	v_pk_fma_f32 v[108:109], v[116:117], v[92:93], v[108:109]
	v_pk_fma_f32 v[108:109], v[72:73], v[118:119], v[108:109]
	v_pk_fma_f32 v[106:107], v[70:71], v[120:121], v[106:107]
	v_mov_b32_dpp v129, v62 row_ror:1 row_mask:0xf bank_mask:0xf
	v_mov_b32_dpp v134, v63 row_ror:1 row_mask:0xf bank_mask:0xf
	v_mov_b32_dpp v135, v64 row_ror:1 row_mask:0xf bank_mask:0xf
	v_mov_b32_dpp v136, v65 row_ror:1 row_mask:0xf bank_mask:0xf
	v_pk_add_f32 v[114:115], v[68:69], v[108:109]
	v_pk_add_f32 v[116:117], v[66:67], v[106:107]
	v_cndmask_b32_e64 v107, v136, v124, s[42:43]
	v_cndmask_b32_e64 v106, v135, v123, s[42:43]
	v_cndmask_b32_e64 v109, v134, v122, s[42:43]
	v_cndmask_b32_e64 v108, v129, v0, s[42:43]
	v_mov_b32_dpp v137, v58 row_ror:15 row_mask:0xf bank_mask:0xf
	v_mov_b32_dpp v138, v59 row_ror:15 row_mask:0xf bank_mask:0xf
	v_mov_b32_dpp v139, v60 row_ror:15 row_mask:0xf bank_mask:0xf
	v_mov_b32_dpp v140, v61 row_ror:15 row_mask:0xf bank_mask:0xf
	v_pk_mul_f32 v[106:107], v[96:97], v[106:107]
	v_pk_mul_f32 v[108:109], v[94:95], v[108:109]
	v_cndmask_b32_e64 v119, v128, v140, s[44:45]
	v_cndmask_b32_e64 v118, v127, v139, s[44:45]
	v_cndmask_b32_e64 v121, v126, v138, s[44:45]
	v_cndmask_b32_e64 v120, v125, v137, s[44:45]
	v_pk_fma_f32 v[64:65], v[64:65], v[92:93], v[106:107]
	v_pk_fma_f32 v[62:63], v[62:63], v[90:91], v[108:109]
	v_pk_fma_f32 v[64:65], v[72:73], v[118:119], v[64:65]
	v_pk_fma_f32 v[62:63], v[70:71], v[120:121], v[62:63]
	v_mov_b32_dpp v0, v58 row_ror:1 row_mask:0xf bank_mask:0xf
	v_mov_b32_dpp v122, v59 row_ror:1 row_mask:0xf bank_mask:0xf
	v_mov_b32_dpp v123, v60 row_ror:1 row_mask:0xf bank_mask:0xf
	v_mov_b32_dpp v124, v61 row_ror:1 row_mask:0xf bank_mask:0xf
	v_pk_add_f32 v[106:107], v[68:69], v[64:65]
	v_pk_add_f32 v[108:109], v[66:67], v[62:63]
	v_cndmask_b32_e64 v63, v124, v136, s[42:43]
	v_cndmask_b32_e64 v62, v123, v135, s[42:43]
	v_cndmask_b32_e64 v65, v122, v134, s[42:43]
	v_cndmask_b32_e64 v64, v0, v129, s[42:43]
	v_mov_b32_dpp v125, v110 row_ror:15 row_mask:0xf bank_mask:0xf
	v_mov_b32_dpp v126, v111 row_ror:15 row_mask:0xf bank_mask:0xf
	v_mov_b32_dpp v127, v112 row_ror:15 row_mask:0xf bank_mask:0xf
	v_mov_b32_dpp v128, v113 row_ror:15 row_mask:0xf bank_mask:0xf
	v_pk_mul_f32 v[62:63], v[96:97], v[62:63]
	v_pk_mul_f32 v[64:65], v[94:95], v[64:65]
	v_cndmask_b32_e64 v119, v140, v128, s[44:45]
	v_cndmask_b32_e64 v118, v139, v127, s[44:45]
	v_cndmask_b32_e64 v121, v138, v126, s[44:45]
	v_cndmask_b32_e64 v120, v137, v125, s[44:45]
	v_pk_fma_f32 v[60:61], v[60:61], v[92:93], v[62:63]
	v_pk_fma_f32 v[58:59], v[58:59], v[90:91], v[64:65]
	v_pk_fma_f32 v[60:61], v[72:73], v[118:119], v[60:61]
	v_pk_fma_f32 v[58:59], v[70:71], v[120:121], v[58:59]
	v_pk_add_f32 v[62:63], v[68:69], v[60:61]
	v_pk_add_f32 v[64:65], v[66:67], v[58:59]
	v_mov_b32_dpp v60, v110 row_ror:1 row_mask:0xf bank_mask:0xf
	v_mov_b32_dpp v61, v111 row_ror:1 row_mask:0xf bank_mask:0xf
	v_mov_b32_dpp v58, v112 row_ror:1 row_mask:0xf bank_mask:0xf
	v_mov_b32_dpp v59, v113 row_ror:1 row_mask:0xf bank_mask:0xf
	v_cndmask_b32_e64 v59, v59, v124, s[42:43]
	v_cndmask_b32_e64 v58, v58, v123, s[42:43]
	v_cndmask_b32_e64 v61, v61, v122, s[42:43]
	v_cndmask_b32_e64 v60, v60, v0, s[42:43]
	v_pk_mul_f32 v[58:59], v[96:97], v[58:59]
	v_pk_mul_f32 v[60:61], v[94:95], v[60:61]
	v_cndmask_b32_e64 v99, v126, v99, s[44:45]
	v_cndmask_b32_e64 v98, v125, v98, s[44:45]
	v_cndmask_b32_e64 v101, v128, v101, s[44:45]
	v_cndmask_b32_e64 v100, v127, v100, s[44:45]
	v_pk_fma_f32 v[58:59], v[112:113], v[92:93], v[58:59]
	v_pk_fma_f32 v[60:61], v[110:111], v[90:91], v[60:61]
	v_pk_fma_f32 v[58:59], v[72:73], v[100:101], v[58:59]
	v_pk_fma_f32 v[60:61], v[70:71], v[98:99], v[60:61]
	v_pk_add_f32 v[58:59], v[68:69], v[58:59]
	v_pk_add_f32 v[60:61], v[66:67], v[60:61]
	v_mul_f32_e32 v0, 0xbfb8aa3b, v154
	v_mul_f32_e32 v66, 0xbfb8aa3b, v155
	v_exp_f32_e32 v0, v0
	v_exp_f32_e32 v66, v66
	v_mul_f32_e32 v67, 0xbfb8aa3b, v152
	v_exp_f32_e32 v67, v67
	v_mul_f32_e32 v68, 0xbfb8aa3b, v153
	v_exp_f32_e32 v68, v68
	v_add_f32_e32 v0, 1.0, v0
	v_add_f32_e32 v66, 1.0, v66
	v_rcp_f32_e32 v0, v0
	v_rcp_f32_e32 v66, v66
	v_add_f32_e32 v67, 1.0, v67
	v_rcp_f32_e32 v67, v67
	v_add_f32_e32 v68, 1.0, v68
	v_rcp_f32_e32 v68, v68
	v_mul_f32_e32 v0, v154, v0
	v_mul_f32_e32 v66, v155, v66
	v_mul_f32_e32 v0, v0, v116
	v_mul_f32_e32 v66, v66, v117
	v_mul_f32_e32 v67, v152, v67
	v_mul_f32_e32 v67, v67, v114
	v_mul_f32_e32 v68, v153, v68
	v_cvt_pk_bf16_f32 v156, v0, v66
	v_mov_b32_e32 v0, v150
	v_mul_f32_e32 v68, v68, v115
	v_cvt_pk_bf16_f32 v157, v67, v68
	s_nop 0
	v_add_u32_e32 v0, 0x58000, v0
	v_lshl_add_u64 v[68:69], v[0:1], 1, s[62:63]
	s_nop 0
	v_mul_f32_e32 v0, 0xbfb8aa3b, v148
	v_mul_f32_e32 v66, 0xbfb8aa3b, v149
	v_exp_f32_e32 v0, v0
	v_exp_f32_e32 v66, v66
	v_mul_f32_e32 v67, 0xbfb8aa3b, v146
	v_exp_f32_e32 v67, v67
	v_mul_f32_e32 v68, 0xbfb8aa3b, v147
	v_exp_f32_e32 v68, v68
	v_add_f32_e32 v0, 1.0, v0
	v_add_f32_e32 v66, 1.0, v66
	v_rcp_f32_e32 v0, v0
	v_rcp_f32_e32 v66, v66
	v_add_f32_e32 v67, 1.0, v67
	v_rcp_f32_e32 v67, v67
	v_add_f32_e32 v68, 1.0, v68
	v_rcp_f32_e32 v68, v68
	v_mul_f32_e32 v0, v148, v0
	v_mul_f32_e32 v66, v149, v66
	v_mul_f32_e32 v0, v0, v108
	v_mul_f32_e32 v66, v66, v109
	v_mul_f32_e32 v67, v146, v67
	v_mul_f32_e32 v67, v67, v106
	v_mul_f32_e32 v68, v147, v68
	v_cvt_pk_bf16_f32 v160, v0, v66
	v_mov_b32_e32 v0, v150
	v_mul_f32_e32 v68, v68, v107
	v_cvt_pk_bf16_f32 v161, v67, v68
	s_nop 0
	v_add_u32_e32 v0, 0x63000, v0
	v_lshl_add_u64 v[68:69], v[0:1], 1, s[62:63]
	v_mul_f32_e32 v0, 0xbfb8aa3b, v132
	v_exp_f32_e32 v0, v0
	s_nop 0
	v_add_f32_e32 v0, 1.0, v0
	v_rcp_f32_e32 v0, v0
	s_nop 0
	v_mul_f32_e32 v0, v132, v0
	v_mul_f32_e32 v0, v0, v64
	v_mul_f32_e32 v64, 0xbfb8aa3b, v133
	v_exp_f32_e32 v64, v64
	s_nop 0
	v_add_f32_e32 v64, 1.0, v64
	v_rcp_f32_e32 v64, v64
	s_nop 0
	v_mul_f32_e32 v64, v133, v64
	v_mul_f32_e32 v64, v64, v65
	v_mul_f32_e32 v65, 0xbfb8aa3b, v130
	v_exp_f32_e32 v65, v65
	s_nop 0
	v_add_f32_e32 v65, 1.0, v65
	v_rcp_f32_e32 v65, v65
	s_nop 0
	v_mul_f32_e32 v65, v130, v65
	v_mul_f32_e32 v65, v65, v62
	v_mul_f32_e32 v62, 0xbfb8aa3b, v131
	v_exp_f32_e32 v62, v62
	s_nop 0
	v_add_f32_e32 v62, 1.0, v62
	v_rcp_f32_e32 v62, v62
	s_nop 0
	v_mul_f32_e32 v62, v131, v62
	v_mul_f32_e32 v63, v62, v63
	v_cvt_pk_bf16_f32 v164, v0, v64
	v_mov_b32_e32 v0, v150
	v_cvt_pk_bf16_f32 v165, v65, v63
	s_nop 0
	v_add_u32_e32 v0, 0x6e000, v0
	v_lshl_add_u64 v[64:65], v[0:1], 1, s[62:63]
	v_mul_f32_e32 v0, 0xbfb8aa3b, v102
	v_exp_f32_e32 v0, v0
	s_nop 0
	v_add_f32_e32 v0, 1.0, v0
	v_rcp_f32_e32 v0, v0
	s_nop 0
	v_mul_f32_e32 v0, v102, v0
	v_mul_f32_e32 v0, v0, v60
	v_mul_f32_e32 v60, 0xbfb8aa3b, v103
	v_exp_f32_e32 v60, v60
	s_nop 0
	v_add_f32_e32 v60, 1.0, v60
	v_rcp_f32_e32 v60, v60
	s_nop 0
	v_mul_f32_e32 v60, v103, v60
	v_mul_f32_e32 v60, v60, v61
	v_mul_f32_e32 v61, 0xbfb8aa3b, v104
	v_exp_f32_e32 v61, v61
	s_nop 0
	v_add_f32_e32 v61, 1.0, v61
	v_rcp_f32_e32 v61, v61
	s_nop 0
	v_mul_f32_e32 v61, v104, v61
	v_mul_f32_e32 v61, v61, v58
	v_mul_f32_e32 v58, 0xbfb8aa3b, v105
	v_exp_f32_e32 v58, v58
	s_nop 0
	v_add_f32_e32 v58, 1.0, v58
	v_rcp_f32_e32 v58, v58
	s_nop 0
	v_mul_f32_e32 v58, v105, v58
	v_mul_f32_e32 v59, v58, v59
	v_cvt_pk_bf16_f32 v168, v0, v60
	v_mov_b32_e32 v0, v150
	v_cvt_pk_bf16_f32 v169, v61, v59
	s_nop 0
	v_add_u32_e32 v0, 0x79000, v0
	v_lshl_add_u64 v[60:61], v[0:1], 1, s[62:63]
	s_nop 0
	ds_read_b128 v[98:101], v209 offset:16
	ds_read_b128 v[94:97], v209 offset:528
	ds_read_b128 v[90:93], v209 offset:1040
	ds_read_b128 v[70:73], v209 offset:1552
	v_mov_b32_e32 v102, 0
	s_and_b64 vcc, exec, s[46:47]
	v_mov_b32_e32 v110, 0
	v_mov_b32_e32 v111, 0
	v_mov_b32_e32 v112, 0
	v_mov_b32_e32 v113, 0
	s_cbranch_vccnz .LBB0_391
	v_add_u32_e32 v0, 0xfffffc10, v240
	ds_read_b128 v[110:113], v0

.LBB0_397:
	s_waitcnt lgkmcnt(4)
	v_cndmask_b32_e64 v113, v145, v113, s[42:43]
	v_cndmask_b32_e64 v112, v141, v112, s[42:43]
	v_cndmask_b32_e64 v111, v137, v111, s[42:43]
	v_cndmask_b32_e64 v110, v133, v110, s[42:43]
	v_pk_mul_f32 v[112:113], v[100:101], v[112:113]
	v_cndmask_b32_e64 v117, v117, v153, s[44:45]
	v_cndmask_b32_e64 v116, v116, v152, s[44:45]
	v_pk_mul_f32 v[110:111], v[98:99], v[110:111]
	v_pk_fma_f32 v[88:89], v[88:89], v[96:97], v[112:113]
	v_cndmask_b32_e64 v115, v115, v151, s[44:45]
	v_cndmask_b32_e64 v114, v114, v148, s[44:45]
	v_pk_fma_f32 v[86:87], v[86:87], v[94:95], v[110:111]
	v_pk_fma_f32 v[88:89], v[92:93], v[116:117], v[88:89]
	v_pk_fma_f32 v[86:87], v[90:91], v[114:115], v[86:87]
	v_pk_add_f32 v[114:115], v[72:73], v[88:89]
	v_cndmask_b32_e64 v89, v134, v137, s[42:43]
	v_cndmask_b32_e64 v88, v131, v133, s[42:43]
	v_pk_mul_f32 v[88:89], v[98:99], v[88:89]
	v_pk_add_f32 v[116:117], v[70:71], v[86:87]
	v_cndmask_b32_e64 v87, v142, v145, s[42:43]
	v_cndmask_b32_e64 v86, v138, v141, s[42:43]
	v_cndmask_b32_e64 v113, v151, v140, s[44:45]
	v_cndmask_b32_e64 v112, v148, v136, s[44:45]
	v_pk_fma_f32 v[88:89], v[124:125], v[94:95], v[88:89]
	v_pk_mul_f32 v[86:87], v[100:101], v[86:87]
	v_pk_fma_f32 v[88:89], v[90:91], v[112:113], v[88:89]
	v_cndmask_b32_e64 v111, v153, v147, s[44:45]
	v_cndmask_b32_e64 v110, v152, v144, s[44:45]
	v_pk_fma_f32 v[86:87], v[122:123], v[96:97], v[86:87]
	v_pk_add_f32 v[112:113], v[70:71], v[88:89]
	v_cndmask_b32_e64 v89, v126, v134, s[42:43]
	v_cndmask_b32_e64 v88, v0, v131, s[42:43]
	v_pk_fma_f32 v[86:87], v[92:93], v[110:111], v[86:87]
	v_pk_mul_f32 v[88:89], v[98:99], v[88:89]
	v_pk_add_f32 v[110:111], v[72:73], v[86:87]
	v_cndmask_b32_e64 v87, v130, v142, s[42:43]
	v_cndmask_b32_e64 v86, v128, v138, s[42:43]
	v_pk_fma_f32 v[88:89], v[120:121], v[94:95], v[88:89]
	v_cndmask_b32_e64 v121, v143, v126, s[42:43]
	v_cndmask_b32_e64 v120, v139, v0, s[42:43]
	v_pk_mul_f32 v[86:87], v[100:101], v[86:87]
	v_pk_mul_f32 v[98:99], v[98:99], v[120:121]
	v_cndmask_b32_e64 v125, v140, v129, s[44:45]
	v_cndmask_b32_e64 v124, v136, v127, s[44:45]
	v_pk_fma_f32 v[86:87], v[118:119], v[96:97], v[86:87]
	v_cndmask_b32_e64 v119, v149, v130, s[42:43]
	v_cndmask_b32_e64 v118, v146, v128, s[42:43]
	v_cndmask_b32_e64 v103, v129, v103, s[44:45]
	v_cndmask_b32_e64 v102, v127, v102, s[44:45]
	v_pk_fma_f32 v[82:83], v[82:83], v[94:95], v[98:99]
	v_pk_fma_f32 v[88:89], v[90:91], v[124:125], v[88:89]
	v_pk_mul_f32 v[100:101], v[100:101], v[118:119]
	v_pk_fma_f32 v[82:83], v[90:91], v[102:103], v[82:83]
	v_cndmask_b32_e64 v123, v147, v135, s[44:45]
	v_cndmask_b32_e64 v122, v144, v132, s[44:45]
	v_pk_add_f32 v[88:89], v[70:71], v[88:89]
	v_cndmask_b32_e64 v105, v135, v105, s[44:45]
	v_cndmask_b32_e64 v104, v132, v104, s[44:45]
	v_pk_fma_f32 v[84:85], v[84:85], v[96:97], v[100:101]
	v_pk_add_f32 v[70:71], v[70:71], v[82:83]
	v_mov_b32_e32 v82, v202
	v_mov_b32_e32 v83, v202
	v_pk_fma_f32 v[86:87], v[92:93], v[122:123], v[86:87]
	v_pk_fma_f32 v[84:85], v[92:93], v[104:105], v[84:85]
	v_pk_fma_f32 v[24:25], v[24:25], v[82:83], v[36:37]
	v_mov_b32_e32 v82, v204
	v_mov_b32_e32 v83, v204
	v_mov_b32_dpp v0, v78 row_ror:1 row_mask:0xf bank_mask:0xf
	v_mov_b32_dpp v94, v79 row_ror:1 row_mask:0xf bank_mask:0xf
	v_mov_b32_dpp v95, v80 row_ror:1 row_mask:0xf bank_mask:0xf
	v_mov_b32_dpp v96, v81 row_ror:1 row_mask:0xf bank_mask:0xf
	v_pk_add_f32 v[86:87], v[72:73], v[86:87]
	v_pk_add_f32 v[72:73], v[72:73], v[84:85]
	v_pk_fma_f32 v[22:23], v[22:23], v[202:203], v[34:35]
	v_pk_fma_f32 v[20:21], v[20:21], v[82:83], v[36:37]
	s_waitcnt lgkmcnt(0)
	v_cndmask_b32_e64 v83, v94, v107, s[42:43]
	v_cndmask_b32_e64 v82, v0, v106, s[42:43]
	v_cndmask_b32_e64 v85, v96, v109, s[42:43]
	v_cndmask_b32_e64 v84, v95, v108, s[42:43]
	v_mov_b32_dpp v92, v78 row_ror:15 row_mask:0xf bank_mask:0xf
	v_mov_b32_dpp v93, v79 row_ror:15 row_mask:0xf bank_mask:0xf
	v_mov_b32_dpp v90, v80 row_ror:15 row_mask:0xf bank_mask:0xf
	v_mov_b32_dpp v91, v81 row_ror:15 row_mask:0xf bank_mask:0xf
	v_mov_b32_dpp v97, v22 row_ror:15 row_mask:0xf bank_mask:0xf
	v_mov_b32_dpp v98, v23 row_ror:15 row_mask:0xf bank_mask:0xf
	v_mov_b32_dpp v99, v24 row_ror:15 row_mask:0xf bank_mask:0xf
	v_mov_b32_dpp v100, v25 row_ror:15 row_mask:0xf bank_mask:0xf
	v_pk_mul_f32 v[84:85], v[64:65], v[84:85]
	v_pk_mul_f32 v[82:83], v[62:63], v[82:83]
	v_cndmask_b32_e64 v91, v91, v100, s[44:45]
	v_cndmask_b32_e64 v90, v90, v99, s[44:45]
	v_cndmask_b32_e64 v93, v93, v98, s[44:45]
	v_cndmask_b32_e64 v92, v92, v97, s[44:45]
	v_pk_fma_f32 v[78:79], v[78:79], v[58:59], v[82:83]
	v_pk_fma_f32 v[80:81], v[80:81], v[60:61], v[84:85]
	v_pk_fma_f32 v[80:81], v[32:33], v[90:91], v[80:81]
	v_pk_fma_f32 v[78:79], v[30:31], v[92:93], v[78:79]
	v_mov_b32_dpp v101, v22 row_ror:1 row_mask:0xf bank_mask:0xf
	v_mov_b32_dpp v102, v23 row_ror:1 row_mask:0xf bank_mask:0xf
	v_mov_b32_dpp v103, v24 row_ror:1 row_mask:0xf bank_mask:0xf
	v_mov_b32_dpp v104, v25 row_ror:1 row_mask:0xf bank_mask:0xf
	v_pk_fma_f32 v[18:19], v[18:19], v[204:205], v[34:35]
	v_pk_add_f32 v[82:83], v[28:29], v[80:81]
	v_pk_add_f32 v[84:85], v[26:27], v[78:79]
	v_cndmask_b32_e64 v79, v104, v96, s[42:43]
	v_cndmask_b32_e64 v78, v103, v95, s[42:43]
	v_cndmask_b32_e64 v81, v102, v94, s[42:43]
	v_cndmask_b32_e64 v80, v101, v0, s[42:43]
	v_mov_b32_dpp v105, v18 row_ror:15 row_mask:0xf bank_mask:0xf
	v_mov_b32_dpp v106, v19 row_ror:15 row_mask:0xf bank_mask:0xf
	v_mov_b32_dpp v107, v20 row_ror:15 row_mask:0xf bank_mask:0xf
	v_mov_b32_dpp v108, v21 row_ror:15 row_mask:0xf bank_mask:0xf
	v_pk_mul_f32 v[78:79], v[64:65], v[78:79]
	v_pk_mul_f32 v[80:81], v[62:63], v[80:81]
	v_cndmask_b32_e64 v91, v100, v108, s[44:45]
	v_cndmask_b32_e64 v90, v99, v107, s[44:45]
	v_cndmask_b32_e64 v93, v98, v106, s[44:45]
	v_cndmask_b32_e64 v92, v97, v105, s[44:45]
	v_pk_fma_f32 v[24:25], v[24:25], v[60:61], v[78:79]
	v_pk_fma_f32 v[22:23], v[22:23], v[58:59], v[80:81]
	v_pk_fma_f32 v[24:25], v[32:33], v[90:91], v[24:25]
	v_pk_fma_f32 v[22:23], v[30:31], v[92:93], v[22:23]
	v_mov_b32_dpp v0, v18 row_ror:1 row_mask:0xf bank_mask:0xf
	v_mov_b32_dpp v94, v19 row_ror:1 row_mask:0xf bank_mask:0xf
	v_mov_b32_dpp v95, v20 row_ror:1 row_mask:0xf bank_mask:0xf
	v_mov_b32_dpp v96, v21 row_ror:1 row_mask:0xf bank_mask:0xf
	v_pk_add_f32 v[78:79], v[28:29], v[24:25]
	v_pk_add_f32 v[80:81], v[26:27], v[22:23]
	v_cndmask_b32_e64 v23, v96, v104, s[42:43]
	v_cndmask_b32_e64 v22, v95, v103, s[42:43]
	v_cndmask_b32_e64 v25, v94, v102, s[42:43]
	v_cndmask_b32_e64 v24, v0, v101, s[42:43]
	v_mov_b32_dpp v97, v74 row_ror:15 row_mask:0xf bank_mask:0xf
	v_mov_b32_dpp v98, v75 row_ror:15 row_mask:0xf bank_mask:0xf
	v_mov_b32_dpp v99, v76 row_ror:15 row_mask:0xf bank_mask:0xf
	v_mov_b32_dpp v100, v77 row_ror:15 row_mask:0xf bank_mask:0xf
	v_pk_mul_f32 v[22:23], v[64:65], v[22:23]
	v_pk_mul_f32 v[24:25], v[62:63], v[24:25]
	v_cndmask_b32_e64 v91, v108, v100, s[44:45]
	v_cndmask_b32_e64 v90, v107, v99, s[44:45]
	v_cndmask_b32_e64 v93, v106, v98, s[44:45]
	v_cndmask_b32_e64 v92, v105, v97, s[44:45]
	v_pk_fma_f32 v[20:21], v[20:21], v[60:61], v[22:23]
	v_pk_fma_f32 v[18:19], v[18:19], v[58:59], v[24:25]
	v_pk_fma_f32 v[20:21], v[32:33], v[90:91], v[20:21]
	v_pk_fma_f32 v[18:19], v[30:31], v[92:93], v[18:19]
	v_pk_add_f32 v[22:23], v[28:29], v[20:21]
	v_pk_add_f32 v[24:25], v[26:27], v[18:19]
	v_mov_b32_dpp v20, v74 row_ror:1 row_mask:0xf bank_mask:0xf
	v_mov_b32_dpp v21, v75 row_ror:1 row_mask:0xf bank_mask:0xf
	v_mov_b32_dpp v18, v76 row_ror:1 row_mask:0xf bank_mask:0xf
	v_mov_b32_dpp v19, v77 row_ror:1 row_mask:0xf bank_mask:0xf
	v_cndmask_b32_e64 v19, v19, v96, s[42:43]
	v_cndmask_b32_e64 v18, v18, v95, s[42:43]
	v_cndmask_b32_e64 v21, v21, v94, s[42:43]
	v_cndmask_b32_e64 v20, v20, v0, s[42:43]
	v_pk_mul_f32 v[18:19], v[64:65], v[18:19]
	v_pk_mul_f32 v[20:21], v[62:63], v[20:21]
	v_cndmask_b32_e64 v67, v98, v67, s[44:45]
	v_cndmask_b32_e64 v66, v97, v66, s[44:45]
	v_cndmask_b32_e64 v69, v100, v69, s[44:45]
	v_cndmask_b32_e64 v68, v99, v68, s[44:45]
	v_pk_fma_f32 v[18:19], v[76:77], v[60:61], v[18:19]
	v_pk_fma_f32 v[20:21], v[74:75], v[58:59], v[20:21]
	v_pk_fma_f32 v[18:19], v[32:33], v[68:69], v[18:19]
	v_pk_fma_f32 v[20:21], v[30:31], v[66:67], v[20:21]
	v_pk_add_f32 v[18:19], v[28:29], v[18:19]
	v_pk_add_f32 v[20:21], v[26:27], v[20:21]
	v_mul_f32_e32 v0, 0xbfb8aa3b, v116
	v_mul_f32_e32 v26, 0xbfb8aa3b, v117
	v_exp_f32_e32 v0, v0
	v_exp_f32_e32 v26, v26
	v_mul_f32_e32 v27, 0xbfb8aa3b, v114
	v_exp_f32_e32 v27, v27
	v_mul_f32_e32 v28, 0xbfb8aa3b, v115
	v_exp_f32_e32 v28, v28
	v_add_f32_e32 v0, 1.0, v0
	v_add_f32_e32 v26, 1.0, v26
	v_rcp_f32_e32 v0, v0
	v_rcp_f32_e32 v26, v26
	v_add_f32_e32 v27, 1.0, v27
	v_rcp_f32_e32 v27, v27
	v_add_f32_e32 v28, 1.0, v28
	v_rcp_f32_e32 v28, v28
	v_mul_f32_e32 v0, v116, v0
	v_mul_f32_e32 v26, v117, v26
	v_mul_f32_e32 v0, v0, v84
	v_mul_f32_e32 v26, v26, v85
	v_mul_f32_e32 v27, v114, v27
	v_mul_f32_e32 v27, v27, v82
	v_mul_f32_e32 v28, v115, v28
	v_cvt_pk_bf16_f32 v220, v0, v26
	v_mov_b32_e32 v0, v150
	v_mul_f32_e32 v28, v28, v83
	v_cvt_pk_bf16_f32 v221, v27, v28
	s_nop 0
	s_nop 0
	v_lshl_add_u64 v[28:29], v[0:1], 1, s[62:63]
	global_store_dwordx4 v[28:29], v[218:221], off
	v_mul_f32_e32 v0, 0xbfb8aa3b, v112
	v_mul_f32_e32 v26, 0xbfb8aa3b, v113
	v_exp_f32_e32 v0, v0
	v_exp_f32_e32 v26, v26
	v_mul_f32_e32 v27, 0xbfb8aa3b, v110
	v_exp_f32_e32 v27, v27
	v_mul_f32_e32 v28, 0xbfb8aa3b, v111
	v_exp_f32_e32 v28, v28
	v_add_f32_e32 v0, 1.0, v0
	v_add_f32_e32 v26, 1.0, v26
	v_rcp_f32_e32 v0, v0
	v_rcp_f32_e32 v26, v26
	v_add_f32_e32 v27, 1.0, v27
	v_rcp_f32_e32 v27, v27
	v_add_f32_e32 v28, 1.0, v28
	v_rcp_f32_e32 v28, v28
	v_mul_f32_e32 v0, v112, v0
	v_mul_f32_e32 v26, v113, v26
	v_mul_f32_e32 v0, v0, v80
	v_mul_f32_e32 v26, v26, v81
	v_mul_f32_e32 v27, v110, v27
	v_mul_f32_e32 v27, v27, v78
	v_mul_f32_e32 v28, v111, v28
	v_cvt_pk_bf16_f32 v230, v0, v26
	v_mov_b32_e32 v0, v150
	v_mul_f32_e32 v28, v28, v79
	v_cvt_pk_bf16_f32 v231, v27, v28
	s_nop 0
	v_add_u32_e32 v0, 0xb000, v0
	v_lshl_add_u64 v[28:29], v[0:1], 1, s[62:63]
	v_mul_f32_e32 v0, 0xbfb8aa3b, v88
	v_exp_f32_e32 v0, v0
	global_store_dwordx4 v[28:29], v[228:231], off
	v_add_f32_e32 v0, 1.0, v0
	v_rcp_f32_e32 v0, v0
	s_nop 0
	v_mul_f32_e32 v0, v88, v0
	v_mul_f32_e32 v0, v0, v24
	v_mul_f32_e32 v24, 0xbfb8aa3b, v89
	v_exp_f32_e32 v24, v24
	s_nop 0
	v_add_f32_e32 v24, 1.0, v24
	v_rcp_f32_e32 v24, v24
	s_nop 0
	v_mul_f32_e32 v24, v89, v24
	v_mul_f32_e32 v24, v24, v25
	v_mul_f32_e32 v25, 0xbfb8aa3b, v86
	v_exp_f32_e32 v25, v25
	s_nop 0
	v_add_f32_e32 v25, 1.0, v25
	v_rcp_f32_e32 v25, v25
	s_nop 0
	v_mul_f32_e32 v25, v86, v25
	v_mul_f32_e32 v25, v25, v22
	v_mul_f32_e32 v22, 0xbfb8aa3b, v87
	v_exp_f32_e32 v22, v22
	s_nop 0
	v_add_f32_e32 v22, 1.0, v22
	v_rcp_f32_e32 v22, v22
	s_nop 0
	v_mul_f32_e32 v22, v87, v22
	v_mul_f32_e32 v23, v22, v23
	v_cvt_pk_bf16_f32 v234, v0, v24
	v_mov_b32_e32 v0, v150
	v_cvt_pk_bf16_f32 v235, v25, v23
	s_nop 0
	v_add_u32_e32 v0, 0x16000, v0
	v_lshl_add_u64 v[24:25], v[0:1], 1, s[62:63]
	v_mul_f32_e32 v0, 0xbfb8aa3b, v70
	v_exp_f32_e32 v0, v0
	global_store_dwordx4 v[24:25], v[232:235], off
	v_add_f32_e32 v0, 1.0, v0
	v_rcp_f32_e32 v0, v0
	s_nop 0
	v_mul_f32_e32 v0, v70, v0
	v_mul_f32_e32 v0, v0, v20
	v_mul_f32_e32 v20, 0xbfb8aa3b, v71
	v_exp_f32_e32 v20, v20
	s_nop 0
	v_add_f32_e32 v20, 1.0, v20
	v_rcp_f32_e32 v20, v20
	s_nop 0
	v_mul_f32_e32 v20, v71, v20
	v_mul_f32_e32 v20, v20, v21
	v_mul_f32_e32 v21, 0xbfb8aa3b, v72
	v_exp_f32_e32 v21, v21
	s_nop 0
	v_add_f32_e32 v21, 1.0, v21
	v_rcp_f32_e32 v21, v21
	s_nop 0
	v_mul_f32_e32 v21, v72, v21
	v_mul_f32_e32 v21, v21, v18
	v_mul_f32_e32 v18, 0xbfb8aa3b, v73
	v_exp_f32_e32 v18, v18
	s_nop 0
	v_add_f32_e32 v18, 1.0, v18
	v_rcp_f32_e32 v18, v18
	s_nop 0
	v_mul_f32_e32 v18, v73, v18
	v_mul_f32_e32 v19, v18, v19
	v_cvt_pk_bf16_f32 v244, v0, v20
	v_mov_b32_e32 v0, v150
	v_cvt_pk_bf16_f32 v245, v21, v19
	s_nop 0
	v_add_u32_e32 v0, 0x21000, v0
	v_lshl_add_u64 v[20:21], v[0:1], 1, s[62:63]
	global_store_dwordx4 v[20:21], v[242:245], off
	ds_read_b128 v[66:69], v209 offset:16
	ds_read_b128 v[62:65], v209 offset:528
	ds_read_b128 v[58:61], v209 offset:1040
	ds_read_b128 v[30:33], v209 offset:1552
	v_mov_b32_e32 v70, 0
	s_and_b64 vcc, exec, s[50:51]
	v_mov_b32_e32 v74, 0
	v_mov_b32_e32 v75, 0
	v_mov_b32_e32 v76, 0
	v_mov_b32_e32 v77, 0
	s_cbranch_vccnz .LBB0_399
	ds_read_b128 v[74:77], v240 offset:3088

.LBB0_405:
	s_waitcnt lgkmcnt(4)
	v_cndmask_b32_e64 v77, v109, v77, s[42:43]
	v_cndmask_b32_e64 v76, v105, v76, s[42:43]
	v_cndmask_b32_e64 v75, v101, v75, s[42:43]
	v_cndmask_b32_e64 v74, v97, v74, s[42:43]
	v_pk_mul_f32 v[76:77], v[68:69], v[76:77]
	v_cndmask_b32_e64 v81, v81, v116, s[44:45]
	v_cndmask_b32_e64 v80, v80, v115, s[44:45]
	v_pk_mul_f32 v[74:75], v[66:67], v[74:75]
	v_pk_fma_f32 v[52:53], v[52:53], v[64:65], v[76:77]
	v_cndmask_b32_e64 v79, v79, v114, s[44:45]
	v_cndmask_b32_e64 v78, v78, v112, s[44:45]
	v_pk_fma_f32 v[50:51], v[50:51], v[62:63], v[74:75]
	v_pk_fma_f32 v[52:53], v[60:61], v[80:81], v[52:53]
	v_pk_fma_f32 v[50:51], v[58:59], v[78:79], v[50:51]
	v_pk_add_f32 v[78:79], v[32:33], v[52:53]
	v_cndmask_b32_e64 v53, v98, v101, s[42:43]
	v_cndmask_b32_e64 v52, v95, v97, s[42:43]
	v_pk_add_f32 v[80:81], v[30:31], v[50:51]
	v_cndmask_b32_e64 v51, v106, v109, s[42:43]
	v_cndmask_b32_e64 v50, v102, v105, s[42:43]
	v_pk_mul_f32 v[52:53], v[66:67], v[52:53]
	v_cndmask_b32_e64 v77, v114, v104, s[44:45]
	v_cndmask_b32_e64 v76, v112, v100, s[44:45]
	v_pk_mul_f32 v[50:51], v[68:69], v[50:51]
	v_pk_fma_f32 v[52:53], v[88:89], v[62:63], v[52:53]
	v_cndmask_b32_e64 v75, v116, v111, s[44:45]
	v_cndmask_b32_e64 v74, v115, v108, s[44:45]
	v_pk_fma_f32 v[50:51], v[86:87], v[64:65], v[50:51]
	v_pk_fma_f32 v[52:53], v[58:59], v[76:77], v[52:53]
	v_pk_fma_f32 v[50:51], v[60:61], v[74:75], v[50:51]
	v_pk_add_f32 v[76:77], v[30:31], v[52:53]
	v_cndmask_b32_e64 v53, v90, v98, s[42:43]
	v_cndmask_b32_e64 v52, v0, v95, s[42:43]
	v_pk_add_f32 v[74:75], v[32:33], v[50:51]
	v_cndmask_b32_e64 v51, v94, v106, s[42:43]
	v_cndmask_b32_e64 v50, v92, v102, s[42:43]
	v_pk_mul_f32 v[52:53], v[66:67], v[52:53]
	v_pk_mul_f32 v[50:51], v[68:69], v[50:51]
	v_pk_fma_f32 v[52:53], v[84:85], v[62:63], v[52:53]
	v_cndmask_b32_e64 v85, v107, v90, s[42:43]
	v_cndmask_b32_e64 v84, v103, v0, s[42:43]
	v_pk_fma_f32 v[50:51], v[82:83], v[64:65], v[50:51]
	v_cndmask_b32_e64 v83, v113, v94, s[42:43]
	v_cndmask_b32_e64 v82, v110, v92, s[42:43]
	v_pk_mul_f32 v[66:67], v[66:67], v[84:85]
	v_cndmask_b32_e64 v89, v104, v93, s[44:45]
	v_cndmask_b32_e64 v88, v100, v91, s[44:45]
	v_cndmask_b32_e64 v71, v93, v71, s[44:45]
	v_cndmask_b32_e64 v70, v91, v70, s[44:45]
	v_pk_mul_f32 v[68:69], v[68:69], v[82:83]
	v_pk_fma_f32 v[46:47], v[46:47], v[62:63], v[66:67]
	v_cndmask_b32_e64 v87, v111, v99, s[44:45]
	v_cndmask_b32_e64 v86, v108, v96, s[44:45]
	v_pk_fma_f32 v[52:53], v[58:59], v[88:89], v[52:53]
	v_cndmask_b32_e64 v73, v99, v73, s[44:45]
	v_cndmask_b32_e64 v72, v96, v72, s[44:45]
	v_pk_fma_f32 v[48:49], v[48:49], v[64:65], v[68:69]
	v_pk_fma_f32 v[46:47], v[58:59], v[70:71], v[46:47]
	v_pk_fma_f32 v[50:51], v[60:61], v[86:87], v[50:51]
	v_pk_add_f32 v[52:53], v[30:31], v[52:53]
	v_pk_fma_f32 v[48:49], v[60:61], v[72:73], v[48:49]
	v_pk_add_f32 v[30:31], v[30:31], v[46:47]
	v_mov_b32_e32 v46, v198
	v_mov_b32_e32 v47, v198
	v_pk_fma_f32 v[8:9], v[8:9], v[46:47], v[36:37]
	v_mov_b32_e32 v46, v200
	v_mov_b32_e32 v47, v200
	v_mov_b32_dpp v0, v42 row_ror:1 row_mask:0xf bank_mask:0xf
	v_mov_b32_dpp v58, v43 row_ror:1 row_mask:0xf bank_mask:0xf
	v_mov_b32_dpp v59, v44 row_ror:1 row_mask:0xf bank_mask:0xf
	v_mov_b32_dpp v60, v45 row_ror:1 row_mask:0xf bank_mask:0xf
	v_pk_add_f32 v[50:51], v[32:33], v[50:51]
	v_pk_add_f32 v[32:33], v[32:33], v[48:49]
	v_pk_fma_f32 v[6:7], v[6:7], v[198:199], v[34:35]
	v_pk_fma_f32 v[4:5], v[4:5], v[46:47], v[36:37]
	v_pk_fma_f32 v[2:3], v[2:3], v[200:201], v[34:35]
	s_waitcnt lgkmcnt(0)
	v_cndmask_b32_e64 v35, v58, v55, s[42:43]
	v_cndmask_b32_e64 v34, v0, v54, s[42:43]
	v_cndmask_b32_e64 v37, v60, v57, s[42:43]
	v_cndmask_b32_e64 v36, v59, v56, s[42:43]
	v_mov_b32_dpp v48, v42 row_ror:15 row_mask:0xf bank_mask:0xf
	v_mov_b32_dpp v49, v43 row_ror:15 row_mask:0xf bank_mask:0xf
	v_mov_b32_dpp v46, v44 row_ror:15 row_mask:0xf bank_mask:0xf
	v_mov_b32_dpp v47, v45 row_ror:15 row_mask:0xf bank_mask:0xf
	v_mov_b32_dpp v61, v6 row_ror:15 row_mask:0xf bank_mask:0xf
	v_mov_b32_dpp v62, v7 row_ror:15 row_mask:0xf bank_mask:0xf
	v_mov_b32_dpp v63, v8 row_ror:15 row_mask:0xf bank_mask:0xf
	v_mov_b32_dpp v64, v9 row_ror:15 row_mask:0xf bank_mask:0xf
	v_pk_mul_f32 v[36:37], v[24:25], v[36:37]
	v_pk_mul_f32 v[34:35], v[22:23], v[34:35]
	v_cndmask_b32_e64 v47, v47, v64, s[44:45]
	v_cndmask_b32_e64 v46, v46, v63, s[44:45]
	v_cndmask_b32_e64 v49, v49, v62, s[44:45]
	v_cndmask_b32_e64 v48, v48, v61, s[44:45]
	v_pk_fma_f32 v[34:35], v[42:43], v[18:19], v[34:35]
	v_pk_fma_f32 v[36:37], v[44:45], v[20:21], v[36:37]
	v_pk_fma_f32 v[36:37], v[16:17], v[46:47], v[36:37]
	v_pk_fma_f32 v[34:35], v[14:15], v[48:49], v[34:35]
	v_mov_b32_dpp v54, v6 row_ror:1 row_mask:0xf bank_mask:0xf
	v_mov_b32_dpp v55, v7 row_ror:1 row_mask:0xf bank_mask:0xf
	v_mov_b32_dpp v56, v8 row_ror:1 row_mask:0xf bank_mask:0xf
	v_mov_b32_dpp v57, v9 row_ror:1 row_mask:0xf bank_mask:0xf
	v_pk_add_f32 v[42:43], v[12:13], v[36:37]
	v_pk_add_f32 v[44:45], v[10:11], v[34:35]
	v_cndmask_b32_e64 v35, v57, v60, s[42:43]
	v_cndmask_b32_e64 v34, v56, v59, s[42:43]
	v_cndmask_b32_e64 v37, v55, v58, s[42:43]
	v_cndmask_b32_e64 v36, v54, v0, s[42:43]
	v_mov_b32_dpp v65, v2 row_ror:15 row_mask:0xf bank_mask:0xf
	v_mov_b32_dpp v66, v3 row_ror:15 row_mask:0xf bank_mask:0xf
	v_mov_b32_dpp v67, v4 row_ror:15 row_mask:0xf bank_mask:0xf
	v_mov_b32_dpp v68, v5 row_ror:15 row_mask:0xf bank_mask:0xf
	v_pk_mul_f32 v[34:35], v[24:25], v[34:35]
	v_pk_mul_f32 v[36:37], v[22:23], v[36:37]
	v_cndmask_b32_e64 v47, v64, v68, s[44:45]
	v_cndmask_b32_e64 v46, v63, v67, s[44:45]
	v_cndmask_b32_e64 v49, v62, v66, s[44:45]
	v_cndmask_b32_e64 v48, v61, v65, s[44:45]
	v_pk_fma_f32 v[8:9], v[8:9], v[20:21], v[34:35]
	v_pk_fma_f32 v[6:7], v[6:7], v[18:19], v[36:37]
	v_pk_fma_f32 v[8:9], v[16:17], v[46:47], v[8:9]
	v_pk_fma_f32 v[6:7], v[14:15], v[48:49], v[6:7]
	v_mov_b32_dpp v0, v2 row_ror:1 row_mask:0xf bank_mask:0xf
	v_mov_b32_dpp v58, v3 row_ror:1 row_mask:0xf bank_mask:0xf
	v_mov_b32_dpp v59, v4 row_ror:1 row_mask:0xf bank_mask:0xf
	v_mov_b32_dpp v60, v5 row_ror:1 row_mask:0xf bank_mask:0xf
	v_pk_add_f32 v[34:35], v[12:13], v[8:9]
	v_pk_add_f32 v[36:37], v[10:11], v[6:7]
	v_cndmask_b32_e64 v7, v60, v57, s[42:43]
	v_cndmask_b32_e64 v6, v59, v56, s[42:43]
	v_cndmask_b32_e64 v9, v58, v55, s[42:43]
	v_cndmask_b32_e64 v8, v0, v54, s[42:43]
	v_mov_b32_dpp v61, v38 row_ror:15 row_mask:0xf bank_mask:0xf
	v_mov_b32_dpp v62, v39 row_ror:15 row_mask:0xf bank_mask:0xf
	v_mov_b32_dpp v63, v40 row_ror:15 row_mask:0xf bank_mask:0xf
	v_mov_b32_dpp v64, v41 row_ror:15 row_mask:0xf bank_mask:0xf
	v_pk_mul_f32 v[6:7], v[24:25], v[6:7]
	v_pk_mul_f32 v[8:9], v[22:23], v[8:9]
	v_cndmask_b32_e64 v47, v68, v64, s[44:45]
	v_cndmask_b32_e64 v46, v67, v63, s[44:45]
	v_cndmask_b32_e64 v49, v66, v62, s[44:45]
	v_cndmask_b32_e64 v48, v65, v61, s[44:45]
	v_pk_fma_f32 v[4:5], v[4:5], v[20:21], v[6:7]
	v_pk_fma_f32 v[2:3], v[2:3], v[18:19], v[8:9]
	v_pk_fma_f32 v[4:5], v[16:17], v[46:47], v[4:5]
	v_pk_fma_f32 v[2:3], v[14:15], v[48:49], v[2:3]
	v_pk_add_f32 v[6:7], v[12:13], v[4:5]
	v_pk_add_f32 v[8:9], v[10:11], v[2:3]
	v_mov_b32_dpp v4, v38 row_ror:1 row_mask:0xf bank_mask:0xf
	v_mov_b32_dpp v5, v39 row_ror:1 row_mask:0xf bank_mask:0xf
	v_mov_b32_dpp v2, v40 row_ror:1 row_mask:0xf bank_mask:0xf
	v_mov_b32_dpp v3, v41 row_ror:1 row_mask:0xf bank_mask:0xf
	v_cndmask_b32_e64 v3, v3, v60, s[42:43]
	v_cndmask_b32_e64 v2, v2, v59, s[42:43]
	v_cndmask_b32_e64 v5, v5, v58, s[42:43]
	v_cndmask_b32_e64 v4, v4, v0, s[42:43]
	v_pk_mul_f32 v[2:3], v[24:25], v[2:3]
	v_pk_mul_f32 v[4:5], v[22:23], v[4:5]
	v_cndmask_b32_e64 v27, v62, v27, s[44:45]
	v_cndmask_b32_e64 v26, v61, v26, s[44:45]
	v_cndmask_b32_e64 v29, v64, v29, s[44:45]
	v_cndmask_b32_e64 v28, v63, v28, s[44:45]
	v_pk_fma_f32 v[2:3], v[40:41], v[20:21], v[2:3]
	v_pk_fma_f32 v[4:5], v[38:39], v[18:19], v[4:5]
	v_pk_fma_f32 v[2:3], v[16:17], v[28:29], v[2:3]
	v_pk_fma_f32 v[4:5], v[14:15], v[26:27], v[4:5]
	v_pk_add_f32 v[2:3], v[12:13], v[2:3]
	v_pk_add_f32 v[4:5], v[10:11], v[4:5]
	v_mul_f32_e32 v0, 0xbfb8aa3b, v80
	v_mul_f32_e32 v10, 0xbfb8aa3b, v81
	v_exp_f32_e32 v0, v0
	v_exp_f32_e32 v10, v10
	v_mul_f32_e32 v11, 0xbfb8aa3b, v78
	v_exp_f32_e32 v11, v11
	v_mul_f32_e32 v12, 0xbfb8aa3b, v79
	v_exp_f32_e32 v12, v12
	v_add_f32_e32 v0, 1.0, v0
	v_add_f32_e32 v10, 1.0, v10
	v_rcp_f32_e32 v0, v0
	v_rcp_f32_e32 v10, v10
	v_add_f32_e32 v11, 1.0, v11
	v_rcp_f32_e32 v11, v11
	v_add_f32_e32 v12, 1.0, v12
	v_rcp_f32_e32 v12, v12
	v_mul_f32_e32 v0, v80, v0
	v_mul_f32_e32 v10, v81, v10
	v_mul_f32_e32 v0, v0, v44
	v_mul_f32_e32 v10, v10, v45
	v_mul_f32_e32 v11, v78, v11
	v_mul_f32_e32 v11, v11, v42
	v_mul_f32_e32 v12, v79, v12
	v_cvt_pk_bf16_f32 v158, v0, v10
	v_mov_b32_e32 v0, v150
	v_mul_f32_e32 v12, v12, v43
	v_cvt_pk_bf16_f32 v159, v11, v12
	s_nop 0
	v_add_u32_e32 v0, 0x58000, v0
	v_lshl_add_u64 v[12:13], v[0:1], 1, s[62:63]
	global_store_dwordx4 v[12:13], v[156:159], off
	v_mul_f32_e32 v0, 0xbfb8aa3b, v76
	v_mul_f32_e32 v10, 0xbfb8aa3b, v77
	v_exp_f32_e32 v0, v0
	v_exp_f32_e32 v10, v10
	v_mul_f32_e32 v11, 0xbfb8aa3b, v74
	v_exp_f32_e32 v11, v11
	v_mul_f32_e32 v12, 0xbfb8aa3b, v75
	v_exp_f32_e32 v12, v12
	v_add_f32_e32 v0, 1.0, v0
	v_add_f32_e32 v10, 1.0, v10
	v_rcp_f32_e32 v0, v0
	v_rcp_f32_e32 v10, v10
	v_add_f32_e32 v11, 1.0, v11
	v_rcp_f32_e32 v11, v11
	v_add_f32_e32 v12, 1.0, v12
	v_rcp_f32_e32 v12, v12
	v_mul_f32_e32 v0, v76, v0
	v_mul_f32_e32 v10, v77, v10
	v_mul_f32_e32 v0, v0, v36
	v_mul_f32_e32 v10, v10, v37
	v_mul_f32_e32 v11, v74, v11
	v_mul_f32_e32 v11, v11, v34
	v_mul_f32_e32 v12, v75, v12
	v_cvt_pk_bf16_f32 v162, v0, v10
	v_mov_b32_e32 v0, v150
	v_mul_f32_e32 v12, v12, v35
	v_cvt_pk_bf16_f32 v163, v11, v12
	s_nop 0
	v_add_u32_e32 v0, 0x63000, v0
	v_lshl_add_u64 v[12:13], v[0:1], 1, s[62:63]
	v_mul_f32_e32 v0, 0xbfb8aa3b, v52
	v_exp_f32_e32 v0, v0
	global_store_dwordx4 v[12:13], v[160:163], off
	v_add_f32_e32 v0, 1.0, v0
	v_rcp_f32_e32 v0, v0
	s_nop 0
	v_mul_f32_e32 v0, v52, v0
	v_mul_f32_e32 v0, v0, v8
	v_mul_f32_e32 v8, 0xbfb8aa3b, v53
	v_exp_f32_e32 v8, v8
	s_nop 0
	v_add_f32_e32 v8, 1.0, v8
	v_rcp_f32_e32 v8, v8
	s_nop 0
	v_mul_f32_e32 v8, v53, v8
	v_mul_f32_e32 v8, v8, v9
	v_mul_f32_e32 v9, 0xbfb8aa3b, v50
	v_exp_f32_e32 v9, v9
	s_nop 0
	v_add_f32_e32 v9, 1.0, v9
	v_rcp_f32_e32 v9, v9
	s_nop 0
	v_mul_f32_e32 v9, v50, v9
	v_mul_f32_e32 v9, v9, v6
	v_mul_f32_e32 v6, 0xbfb8aa3b, v51
	v_exp_f32_e32 v6, v6
	s_nop 0
	v_add_f32_e32 v6, 1.0, v6
	v_rcp_f32_e32 v6, v6
	s_nop 0
	v_mul_f32_e32 v6, v51, v6
	v_mul_f32_e32 v7, v6, v7
	v_cvt_pk_bf16_f32 v166, v0, v8
	v_mov_b32_e32 v0, v150
	v_cvt_pk_bf16_f32 v167, v9, v7
	s_nop 0
	v_add_u32_e32 v0, 0x6e000, v0
	v_lshl_add_u64 v[8:9], v[0:1], 1, s[62:63]
	v_mul_f32_e32 v0, 0xbfb8aa3b, v30
	v_exp_f32_e32 v0, v0
	global_store_dwordx4 v[8:9], v[164:167], off
	v_add_f32_e32 v0, 1.0, v0
	v_rcp_f32_e32 v0, v0
	s_nop 0
	v_mul_f32_e32 v0, v30, v0
	v_mul_f32_e32 v0, v0, v4
	v_mul_f32_e32 v4, 0xbfb8aa3b, v31
	v_exp_f32_e32 v4, v4
	s_nop 0
	v_add_f32_e32 v4, 1.0, v4
	v_rcp_f32_e32 v4, v4
	s_nop 0
	v_mul_f32_e32 v4, v31, v4
	v_mul_f32_e32 v4, v4, v5
	v_mul_f32_e32 v5, 0xbfb8aa3b, v32
	v_exp_f32_e32 v5, v5
	s_nop 0
	v_add_f32_e32 v5, 1.0, v5
	v_rcp_f32_e32 v5, v5
	s_nop 0
	v_mul_f32_e32 v5, v32, v5
	v_mul_f32_e32 v5, v5, v2
	v_mul_f32_e32 v2, 0xbfb8aa3b, v33
	v_exp_f32_e32 v2, v2
	s_nop 0
	v_add_f32_e32 v2, 1.0, v2
	v_rcp_f32_e32 v2, v2
	s_nop 0
	v_mul_f32_e32 v2, v33, v2
	v_mul_f32_e32 v3, v2, v3
	v_cvt_pk_bf16_f32 v170, v0, v4
	v_cvt_pk_bf16_f32 v171, v5, v3
	s_nop 0
	v_add_u32_e32 v0, 0x79000, v150
	v_lshl_add_u64 v[4:5], v[0:1], 1, s[62:63]
	global_store_dwordx4 v[4:5], v[168:171], off
	s_andn2_b64 vcc, exec, s[40:41]
	s_mov_b64 s[2:3], -1
	s_cbranch_vccnz .LBB0_319
	s_andn2_b64 vcc, exec, s[26:27]
	s_cbranch_vccnz .LBB0_318
	s_barrier
	s_branch .LBB0_318

.LBB0_602:
	s_cmp_lg_u32 s42, 2
	s_mov_b64 s[42:43], -1
	s_cbranch_scc0 .LBB0_604
	v_lshlrev_b64 v[130:131], 10, v[190:191]
	v_lshl_add_u64 v[130:131], s[34:35], 0, v[130:131]
	s_add_i32 s42, s6, 0xfffffd00
	s_mov_b32 s43, s55
	v_lshl_add_u64 v[130:131], s[42:43], 1, v[130:131]
	s_lshl_b32 s42, s76, 1
	v_lshl_add_u64 v[130:131], v[130:131], 0, s[42:43]
	v_lshlrev_b32_e32 v132, 1, v217
	v_mov_b32_e32 v133, v1
	v_lshl_add_u64 v[146:147], v[130:131], 0, v[132:133]
	global_load_dwordx4 v[130:133], v[188:189], off
	v_mov_b64_e32 v[164:165], 0
	v_mov_b64_e32 v[166:167], v[146:147]
	s_movk_i32 s5, 0x4000
	s_waitcnt vmcnt(0)
	v_mov_b32_e32 v134, v131
	v_mov_b32_e32 v135, v132
	v_mov_b32_e32 v131, v133
	v_pk_add_f32 v[130:131], v[134:135], v[130:131]
	s_nop 0
	v_add_f32_e32 v130, v130, v131
	v_fmamk_f32 v130, v130, 0x3a800000, v223
	v_rsq_f32_e32 v162, v130
	global_load_dwordx4 v[130:133], v[188:189], off offset:256
	s_waitcnt vmcnt(0)
	v_mov_b32_e32 v134, v131
	v_mov_b32_e32 v135, v132
	v_mov_b32_e32 v131, v133
	v_pk_add_f32 v[130:131], v[134:135], v[130:131]
	s_nop 0
	v_add_f32_e32 v130, v130, v131
	v_fmamk_f32 v130, v130, 0x3a800000, v223
	v_rsq_f32_e32 v160, v130
	global_load_dwordx4 v[130:133], v[188:189], off offset:512
	s_waitcnt vmcnt(0)
	v_mov_b32_e32 v134, v131
	v_mov_b32_e32 v135, v132
	v_mov_b32_e32 v131, v133
	v_pk_add_f32 v[130:131], v[134:135], v[130:131]
	s_nop 0
	v_add_f32_e32 v130, v130, v131
	v_fmamk_f32 v130, v130, 0x3a800000, v223
	v_rsq_f32_e32 v152, v130
	global_load_dwordx4 v[130:133], v[188:189], off offset:768
	s_waitcnt vmcnt(0)
	v_mov_b32_e32 v134, v131
	v_mov_b32_e32 v135, v132
	v_mov_b32_e32 v131, v133
	v_pk_add_f32 v[130:131], v[134:135], v[130:131]
	s_nop 0
	v_add_f32_e32 v130, v130, v131
	v_fmamk_f32 v130, v130, 0x3a800000, v223
	v_rsq_f32_e32 v158, v130
	global_load_dwordx4 v[130:133], v[188:189], off offset:2048
	s_waitcnt vmcnt(0)
	v_mov_b32_e32 v134, v131
	v_mov_b32_e32 v135, v132
	v_mov_b32_e32 v131, v133
	v_pk_add_f32 v[130:131], v[134:135], v[130:131]
	s_nop 0
	v_add_f32_e32 v130, v130, v131
	v_fmamk_f32 v130, v130, 0x3a800000, v223
	v_rsq_f32_e32 v154, v130
	global_load_dwordx4 v[130:133], v[188:189], off offset:2304
	s_waitcnt vmcnt(0)
	v_mov_b32_e32 v134, v131
	v_mov_b32_e32 v135, v132
	v_mov_b32_e32 v131, v133
	v_pk_add_f32 v[130:131], v[134:135], v[130:131]
	s_nop 0
	v_add_f32_e32 v130, v130, v131
	v_fmamk_f32 v130, v130, 0x3a800000, v223
	v_rsq_f32_e32 v150, v130
	global_load_dwordx4 v[130:133], v[188:189], off offset:2560
	s_waitcnt vmcnt(0)
	v_mov_b32_e32 v134, v131
	v_mov_b32_e32 v135, v132
	v_mov_b32_e32 v131, v133
	v_pk_add_f32 v[130:131], v[134:135], v[130:131]
	s_nop 0
	v_add_f32_e32 v130, v130, v131
	v_fmamk_f32 v130, v130, 0x3a800000, v223
	v_rsq_f32_e32 v148, v130
	global_load_dwordx4 v[130:133], v[188:189], off offset:2816
	s_waitcnt vmcnt(0)
	v_mov_b32_e32 v134, v131
	v_mov_b32_e32 v135, v132
	v_mov_b32_e32 v131, v133
	v_pk_add_f32 v[130:131], v[134:135], v[130:131]
	s_nop 0
	v_add_f32_e32 v130, v130, v131
	v_fmamk_f32 v130, v130, 0x3a800000, v223
	v_rsq_f32_e32 v156, v130
	global_load_dwordx4 v[142:145], v[186:187], off
	global_load_dwordx4 v[138:141], v[186:187], off offset:64
	global_load_dwordx4 v[134:137], v[186:187], off offset:512
	global_load_dwordx4 v[130:133], v[186:187], off offset:576
	s_waitcnt vmcnt(3)
	v_pk_fma_f32 v[168:169], v[126:127], v[162:163], v[142:143] op_sel_hi:[1,0,1]
	v_pk_fma_f32 v[164:165], v[128:129], v[162:163], v[144:145] op_sel_hi:[1,0,1]
	s_waitcnt vmcnt(2)
	v_pk_fma_f32 v[170:171], v[124:125], v[162:163], v[140:141] op_sel_hi:[1,0,1]
	v_pk_fma_f32 v[172:173], v[122:123], v[162:163], v[138:139] op_sel_hi:[1,0,1]
	s_waitcnt vmcnt(1)
	v_pk_fma_f32 v[174:175], v[120:121], v[162:163], v[136:137] op_sel_hi:[1,0,1]
	v_pk_fma_f32 v[176:177], v[118:119], v[162:163], v[134:135] op_sel_hi:[1,0,1]
	s_waitcnt vmcnt(0)
	v_pk_fma_f32 v[192:193], v[116:117], v[162:163], v[132:133] op_sel_hi:[1,0,1]
	v_pk_fma_f32 v[162:163], v[114:115], v[162:163], v[130:131] op_sel_hi:[1,0,1]
	v_cvt_pk_bf16_f32 v240, v168, v169
	v_cvt_pk_bf16_f32 v241, v164, v165
	v_mbcnt_lo_u32_b32 v0, -1, 0
	v_mbcnt_hi_u32_b32 v0, -1, v0
	v_bfe_u32 v0, v0, 4, 1
	v_mul_u32_u24_e32 v0, 24, v0
	v_lshl_add_u64 v[248:249], v[166:167], 0, v[0:1]
	v_cvt_pk_bf16_f32 v242, v172, v173
	v_cvt_pk_bf16_f32 v243, v170, v171
	s_nop 1
	v_permlane16_swap_b32_e32 v240, v242
	v_permlane16_swap_b32_e32 v241, v243
	global_store_dwordx4 v[248:249], v[240:243], off
	v_cvt_pk_bf16_f32 v244, v176, v177
	v_cvt_pk_bf16_f32 v245, v174, v175
	s_nop 0
	v_cvt_pk_bf16_f32 v246, v162, v163
	v_cvt_pk_bf16_f32 v247, v192, v193
	s_nop 1
	v_permlane16_swap_b32_e32 v244, v246
	v_permlane16_swap_b32_e32 v245, v247
	global_store_dwordx4 v[248:249], v[244:247], off offset:64
	v_mov_b64_e32 v[162:163], 0
	v_mov_b64_e32 v[164:165], v[146:147]
	v_pk_fma_f32 v[166:167], v[110:111], v[160:161], v[142:143] op_sel_hi:[1,0,1]
	v_pk_fma_f32 v[162:163], v[112:113], v[160:161], v[144:145] op_sel_hi:[1,0,1]
	v_cvt_pk_bf16_f32 v240, v166, v167
	v_pk_fma_f32 v[168:169], v[108:109], v[160:161], v[140:141] op_sel_hi:[1,0,1]
	v_cvt_pk_bf16_f32 v241, v162, v163
	v_add_co_u32_e32 v162, vcc, s5, v164
	v_pk_fma_f32 v[170:171], v[106:107], v[160:161], v[138:139] op_sel_hi:[1,0,1]
	s_nop 0
	v_addc_co_u32_e32 v163, vcc, 0, v165, vcc
	v_pk_fma_f32 v[172:173], v[104:105], v[160:161], v[136:137] op_sel_hi:[1,0,1]
	v_pk_fma_f32 v[174:175], v[102:103], v[160:161], v[134:135] op_sel_hi:[1,0,1]
	v_pk_fma_f32 v[176:177], v[100:101], v[160:161], v[132:133] op_sel_hi:[1,0,1]
	v_pk_fma_f32 v[160:161], v[98:99], v[160:161], v[130:131] op_sel_hi:[1,0,1]
	v_mbcnt_lo_u32_b32 v0, -1, 0
	v_mbcnt_hi_u32_b32 v0, -1, v0
	v_bfe_u32 v0, v0, 4, 1
	v_mul_u32_u24_e32 v0, 24, v0
	v_lshl_add_u64 v[248:249], v[162:163], 0, v[0:1]
	v_cvt_pk_bf16_f32 v242, v170, v171
	v_cvt_pk_bf16_f32 v243, v168, v169
	s_nop 1
	v_permlane16_swap_b32_e32 v240, v242
	v_permlane16_swap_b32_e32 v241, v243
	global_store_dwordx4 v[248:249], v[240:243], off
	v_cvt_pk_bf16_f32 v244, v174, v175
	v_cvt_pk_bf16_f32 v245, v172, v173
	s_nop 0
	v_cvt_pk_bf16_f32 v246, v160, v161
	v_cvt_pk_bf16_f32 v247, v176, v177
	s_nop 1
	v_permlane16_swap_b32_e32 v244, v246
	v_permlane16_swap_b32_e32 v245, v247
	global_store_dwordx4 v[248:249], v[244:247], off offset:64
	v_mov_b64_e32 v[160:161], 0
	v_mov_b64_e32 v[162:163], v[146:147]
	v_pk_fma_f32 v[164:165], v[94:95], v[152:153], v[142:143] op_sel_hi:[1,0,1]
	v_pk_fma_f32 v[160:161], v[96:97], v[152:153], v[144:145] op_sel_hi:[1,0,1]
	s_mov_b32 s5, 0x8000
	v_cvt_pk_bf16_f32 v240, v164, v165
	v_cvt_pk_bf16_f32 v241, v160, v161
	v_add_co_u32_e32 v160, vcc, s5, v162
	v_pk_fma_f32 v[166:167], v[92:93], v[152:153], v[140:141] op_sel_hi:[1,0,1]
	s_nop 0
	v_addc_co_u32_e32 v161, vcc, 0, v163, vcc
	v_pk_fma_f32 v[168:169], v[90:91], v[152:153], v[138:139] op_sel_hi:[1,0,1]
	v_pk_fma_f32 v[170:171], v[88:89], v[152:153], v[136:137] op_sel_hi:[1,0,1]
	v_pk_fma_f32 v[172:173], v[86:87], v[152:153], v[134:135] op_sel_hi:[1,0,1]
	v_pk_fma_f32 v[174:175], v[84:85], v[152:153], v[132:133] op_sel_hi:[1,0,1]
	v_pk_fma_f32 v[152:153], v[82:83], v[152:153], v[130:131] op_sel_hi:[1,0,1]
	v_mbcnt_lo_u32_b32 v0, -1, 0
	v_mbcnt_hi_u32_b32 v0, -1, v0
	v_bfe_u32 v0, v0, 4, 1
	v_mul_u32_u24_e32 v0, 24, v0
	v_lshl_add_u64 v[248:249], v[160:161], 0, v[0:1]
	v_cvt_pk_bf16_f32 v242, v168, v169
	v_cvt_pk_bf16_f32 v243, v166, v167
	s_nop 1
	v_permlane16_swap_b32_e32 v240, v242
	v_permlane16_swap_b32_e32 v241, v243
	global_store_dwordx4 v[248:249], v[240:243], off
	v_cvt_pk_bf16_f32 v244, v172, v173
	v_cvt_pk_bf16_f32 v245, v170, v171
	s_nop 0
	v_cvt_pk_bf16_f32 v246, v152, v153
	v_cvt_pk_bf16_f32 v247, v174, v175
	s_nop 1
	v_permlane16_swap_b32_e32 v244, v246
	v_permlane16_swap_b32_e32 v245, v247
	global_store_dwordx4 v[248:249], v[244:247], off offset:64
	v_mov_b64_e32 v[152:153], 0
	v_mov_b64_e32 v[160:161], v[146:147]
	v_pk_fma_f32 v[162:163], v[78:79], v[158:159], v[142:143] op_sel_hi:[1,0,1]
	v_pk_fma_f32 v[152:153], v[80:81], v[158:159], v[144:145] op_sel_hi:[1,0,1]
	s_mov_b32 s5, 0xc000
	v_cvt_pk_bf16_f32 v240, v162, v163
	v_cvt_pk_bf16_f32 v241, v152, v153
	v_add_co_u32_e32 v152, vcc, s5, v160
	v_pk_fma_f32 v[164:165], v[76:77], v[158:159], v[140:141] op_sel_hi:[1,0,1]
	s_nop 0
	v_addc_co_u32_e32 v153, vcc, 0, v161, vcc
	v_pk_fma_f32 v[166:167], v[74:75], v[158:159], v[138:139] op_sel_hi:[1,0,1]
	v_pk_fma_f32 v[168:169], v[72:73], v[158:159], v[136:137] op_sel_hi:[1,0,1]
	v_pk_fma_f32 v[170:171], v[70:71], v[158:159], v[134:135] op_sel_hi:[1,0,1]
	v_pk_fma_f32 v[172:173], v[68:69], v[158:159], v[132:133] op_sel_hi:[1,0,1]
	v_pk_fma_f32 v[158:159], v[66:67], v[158:159], v[130:131] op_sel_hi:[1,0,1]
	v_mbcnt_lo_u32_b32 v0, -1, 0
	v_mbcnt_hi_u32_b32 v0, -1, v0
	v_bfe_u32 v0, v0, 4, 1
	v_mul_u32_u24_e32 v0, 24, v0
	v_lshl_add_u64 v[248:249], v[152:153], 0, v[0:1]
	v_cvt_pk_bf16_f32 v242, v166, v167
	v_cvt_pk_bf16_f32 v243, v164, v165
	s_nop 1
	v_permlane16_swap_b32_e32 v240, v242
	v_permlane16_swap_b32_e32 v241, v243
	global_store_dwordx4 v[248:249], v[240:243], off
	v_cvt_pk_bf16_f32 v244, v170, v171
	v_cvt_pk_bf16_f32 v245, v168, v169
	s_nop 0
	v_cvt_pk_bf16_f32 v246, v158, v159
	v_cvt_pk_bf16_f32 v247, v172, v173
	s_nop 1
	v_permlane16_swap_b32_e32 v244, v246
	v_permlane16_swap_b32_e32 v245, v247
	global_store_dwordx4 v[248:249], v[244:247], off offset:64
	v_mov_b64_e32 v[152:153], 0
	v_mov_b64_e32 v[158:159], v[146:147]
	v_pk_fma_f32 v[160:161], v[62:63], v[154:155], v[142:143] op_sel_hi:[1,0,1]
	v_pk_fma_f32 v[152:153], v[64:65], v[154:155], v[144:145] op_sel_hi:[1,0,1]
	s_mov_b32 s5, 0x20000
	v_cvt_pk_bf16_f32 v240, v160, v161
	v_cvt_pk_bf16_f32 v241, v152, v153
	v_add_co_u32_e32 v152, vcc, s5, v158
	v_pk_fma_f32 v[162:163], v[60:61], v[154:155], v[140:141] op_sel_hi:[1,0,1]
	s_nop 0
	v_addc_co_u32_e32 v153, vcc, 0, v159, vcc
	v_pk_fma_f32 v[164:165], v[58:59], v[154:155], v[138:139] op_sel_hi:[1,0,1]
	v_pk_fma_f32 v[166:167], v[56:57], v[154:155], v[136:137] op_sel_hi:[1,0,1]
	v_pk_fma_f32 v[168:169], v[54:55], v[154:155], v[134:135] op_sel_hi:[1,0,1]
	v_pk_fma_f32 v[170:171], v[52:53], v[154:155], v[132:133] op_sel_hi:[1,0,1]
	v_pk_fma_f32 v[154:155], v[50:51], v[154:155], v[130:131] op_sel_hi:[1,0,1]
	v_mbcnt_lo_u32_b32 v0, -1, 0
	v_mbcnt_hi_u32_b32 v0, -1, v0
	v_bfe_u32 v0, v0, 4, 1
	v_mul_u32_u24_e32 v0, 24, v0
	v_lshl_add_u64 v[248:249], v[152:153], 0, v[0:1]
	v_cvt_pk_bf16_f32 v242, v164, v165
	v_cvt_pk_bf16_f32 v243, v162, v163
	s_nop 1
	v_permlane16_swap_b32_e32 v240, v242
	v_permlane16_swap_b32_e32 v241, v243
	global_store_dwordx4 v[248:249], v[240:243], off
	v_cvt_pk_bf16_f32 v244, v168, v169
	v_cvt_pk_bf16_f32 v245, v166, v167
	s_nop 0
	v_cvt_pk_bf16_f32 v246, v154, v155
	v_cvt_pk_bf16_f32 v247, v170, v171
	s_nop 1
	v_permlane16_swap_b32_e32 v244, v246
	v_permlane16_swap_b32_e32 v245, v247
	global_store_dwordx4 v[248:249], v[244:247], off offset:64
	v_mov_b64_e32 v[152:153], 0
	v_mov_b64_e32 v[154:155], v[146:147]
	v_pk_fma_f32 v[158:159], v[46:47], v[150:151], v[142:143] op_sel_hi:[1,0,1]
	v_pk_fma_f32 v[152:153], v[48:49], v[150:151], v[144:145] op_sel_hi:[1,0,1]
	s_mov_b32 s5, 0x24000
	v_cvt_pk_bf16_f32 v240, v158, v159
	v_cvt_pk_bf16_f32 v241, v152, v153
	v_add_co_u32_e32 v152, vcc, s5, v154
	v_pk_fma_f32 v[160:161], v[44:45], v[150:151], v[140:141] op_sel_hi:[1,0,1]
	s_nop 0
	v_addc_co_u32_e32 v153, vcc, 0, v155, vcc
	v_pk_fma_f32 v[162:163], v[42:43], v[150:151], v[138:139] op_sel_hi:[1,0,1]
	v_pk_fma_f32 v[164:165], v[40:41], v[150:151], v[136:137] op_sel_hi:[1,0,1]
	v_pk_fma_f32 v[166:167], v[38:39], v[150:151], v[134:135] op_sel_hi:[1,0,1]
	v_pk_fma_f32 v[168:169], v[36:37], v[150:151], v[132:133] op_sel_hi:[1,0,1]
	v_pk_fma_f32 v[150:151], v[34:35], v[150:151], v[130:131] op_sel_hi:[1,0,1]
	v_mbcnt_lo_u32_b32 v0, -1, 0
	v_mbcnt_hi_u32_b32 v0, -1, v0
	v_bfe_u32 v0, v0, 4, 1
	v_mul_u32_u24_e32 v0, 24, v0
	v_lshl_add_u64 v[248:249], v[152:153], 0, v[0:1]
	v_cvt_pk_bf16_f32 v242, v162, v163
	v_cvt_pk_bf16_f32 v243, v160, v161
	s_nop 1
	v_permlane16_swap_b32_e32 v240, v242
	v_permlane16_swap_b32_e32 v241, v243
	global_store_dwordx4 v[248:249], v[240:243], off
	v_cvt_pk_bf16_f32 v244, v166, v167
	v_cvt_pk_bf16_f32 v245, v164, v165
	s_nop 0
	v_cvt_pk_bf16_f32 v246, v150, v151
	v_cvt_pk_bf16_f32 v247, v168, v169
	s_nop 1
	v_permlane16_swap_b32_e32 v244, v246
	v_permlane16_swap_b32_e32 v245, v247
	global_store_dwordx4 v[248:249], v[244:247], off offset:64
	v_mov_b64_e32 v[150:151], 0
	v_mov_b64_e32 v[152:153], v[146:147]
	v_pk_fma_f32 v[154:155], v[30:31], v[148:149], v[142:143] op_sel_hi:[1,0,1]
	v_pk_fma_f32 v[150:151], v[32:33], v[148:149], v[144:145] op_sel_hi:[1,0,1]
	s_mov_b32 s5, 0x28000
	v_cvt_pk_bf16_f32 v240, v154, v155
	v_cvt_pk_bf16_f32 v241, v150, v151
	v_add_co_u32_e32 v150, vcc, s5, v152
	v_pk_fma_f32 v[158:159], v[28:29], v[148:149], v[140:141] op_sel_hi:[1,0,1]
	s_nop 0
	v_addc_co_u32_e32 v151, vcc, 0, v153, vcc
	v_pk_fma_f32 v[160:161], v[26:27], v[148:149], v[138:139] op_sel_hi:[1,0,1]
	v_mbcnt_lo_u32_b32 v0, -1, 0
	v_mbcnt_hi_u32_b32 v0, -1, v0
	v_bfe_u32 v0, v0, 4, 1
	v_mul_u32_u24_e32 v0, 24, v0
	v_lshl_add_u64 v[248:249], v[150:151], 0, v[0:1]
	v_cvt_pk_bf16_f32 v242, v160, v161
	v_cvt_pk_bf16_f32 v243, v158, v159
	v_pk_fma_f32 v[162:163], v[24:25], v[148:149], v[136:137] op_sel_hi:[1,0,1]
	v_pk_fma_f32 v[164:165], v[22:23], v[148:149], v[134:135] op_sel_hi:[1,0,1]
	s_nop 1
	v_permlane16_swap_b32_e32 v240, v242
	v_permlane16_swap_b32_e32 v241, v243
	global_store_dwordx4 v[248:249], v[240:243], off
	v_cvt_pk_bf16_f32 v244, v164, v165
	v_cvt_pk_bf16_f32 v245, v162, v163
	v_pk_fma_f32 v[166:167], v[20:21], v[148:149], v[132:133] op_sel_hi:[1,0,1]
	v_pk_fma_f32 v[168:169], v[18:19], v[148:149], v[130:131] op_sel_hi:[1,0,1]
	s_nop 0
	v_cvt_pk_bf16_f32 v246, v168, v169
	v_cvt_pk_bf16_f32 v247, v166, v167
	s_nop 1
	v_permlane16_swap_b32_e32 v244, v246
	v_permlane16_swap_b32_e32 v245, v247
	global_store_dwordx4 v[248:249], v[244:247], off offset:64
	v_mov_b64_e32 v[150:151], 0
	v_pk_fma_f32 v[144:145], v[16:17], v[156:157], v[144:145] op_sel_hi:[1,0,1]
	v_pk_fma_f32 v[142:143], v[14:15], v[156:157], v[142:143] op_sel_hi:[1,0,1]
	s_mov_b32 s5, 0x2c000
	v_cvt_pk_bf16_f32 v240, v142, v143
	v_cvt_pk_bf16_f32 v241, v144, v145
	v_pk_fma_f32 v[138:139], v[10:11], v[156:157], v[138:139] op_sel_hi:[1,0,1]
	v_add_co_u32_e32 v144, vcc, s5, v146
	v_pk_fma_f32 v[134:135], v[6:7], v[156:157], v[134:135] op_sel_hi:[1,0,1]
	v_pk_fma_f32 v[130:131], v[2:3], v[156:157], v[130:131] op_sel_hi:[1,0,1]
	v_addc_co_u32_e32 v145, vcc, 0, v147, vcc
	v_pk_fma_f32 v[140:141], v[12:13], v[156:157], v[140:141] op_sel_hi:[1,0,1]
	v_pk_fma_f32 v[136:137], v[8:9], v[156:157], v[136:137] op_sel_hi:[1,0,1]
	v_pk_fma_f32 v[132:133], v[4:5], v[156:157], v[132:133] op_sel_hi:[1,0,1]
	v_mbcnt_lo_u32_b32 v0, -1, 0
	v_mbcnt_hi_u32_b32 v0, -1, v0
	v_bfe_u32 v0, v0, 4, 1
	v_mul_u32_u24_e32 v0, 24, v0
	v_lshl_add_u64 v[248:249], v[144:145], 0, v[0:1]
	v_cvt_pk_bf16_f32 v242, v138, v139
	v_cvt_pk_bf16_f32 v243, v140, v141
	s_nop 1
	v_permlane16_swap_b32_e32 v240, v242
	v_permlane16_swap_b32_e32 v241, v243
	global_store_dwordx4 v[248:249], v[240:243], off
	v_cvt_pk_bf16_f32 v244, v134, v135
	v_cvt_pk_bf16_f32 v245, v136, v137
	s_nop 0
	v_cvt_pk_bf16_f32 v246, v130, v131
	v_cvt_pk_bf16_f32 v247, v132, v133
	s_nop 1
	v_permlane16_swap_b32_e32 v244, v246
	v_permlane16_swap_b32_e32 v245, v247
	global_store_dwordx4 v[248:249], v[244:247], off offset:64
	s_mov_b64 s[42:43], 0

.LBB0_610:
	v_cvt_pk_bf16_f32 v240, v158, v159
	v_cvt_pk_bf16_f32 v241, v160, v161
	v_mbcnt_lo_u32_b32 v0, -1, 0
	v_mbcnt_hi_u32_b32 v0, -1, v0
	v_bfe_u32 v0, v0, 4, 1
	v_mul_u32_u24_e32 v0, 24, v0
	v_lshl_add_u64 v[248:249], v[176:177], 0, v[0:1]
	v_cvt_pk_bf16_f32 v242, v154, v155
	v_cvt_pk_bf16_f32 v243, v156, v157
	s_nop 1
	v_permlane16_swap_b32_e32 v240, v242
	v_permlane16_swap_b32_e32 v241, v243
	global_store_dwordx4 v[248:249], v[240:243], off
	v_cvt_pk_bf16_f32 v244, v150, v151
	v_cvt_pk_bf16_f32 v245, v152, v153
	s_nop 0
	v_cvt_pk_bf16_f32 v246, v146, v147
	v_cvt_pk_bf16_f32 v247, v148, v149
	s_nop 1
	v_permlane16_swap_b32_e32 v244, v246
	v_permlane16_swap_b32_e32 v245, v247
	global_store_dwordx4 v[248:249], v[244:247], off offset:64
	v_mov_b64_e32 v[176:177], v[192:193]
	v_mov_b64_e32 v[196:197], v[194:195]
	v_pk_fma_f32 v[160:161], v[112:113], v[174:175], v[144:145] op_sel_hi:[1,0,1]
	v_pk_fma_f32 v[158:159], v[110:111], v[174:175], v[142:143] op_sel_hi:[1,0,1]
	v_pk_fma_f32 v[156:157], v[108:109], v[174:175], v[140:141] op_sel_hi:[1,0,1]
	v_pk_fma_f32 v[154:155], v[106:107], v[174:175], v[138:139] op_sel_hi:[1,0,1]
	v_pk_fma_f32 v[152:153], v[104:105], v[174:175], v[136:137] op_sel_hi:[1,0,1]
	v_pk_fma_f32 v[150:151], v[102:103], v[174:175], v[134:135] op_sel_hi:[1,0,1]
	v_pk_fma_f32 v[148:149], v[100:101], v[174:175], v[132:133] op_sel_hi:[1,0,1]
	s_and_b64 vcc, exec, s[42:43]
	v_pk_fma_f32 v[146:147], v[98:99], v[174:175], v[130:131] op_sel_hi:[1,0,1]
	s_cbranch_vccnz .LBB0_612
	v_add_co_u32_e32 v174, vcc, 0x2000, v196
	s_nop 1
	v_addc_co_u32_e32 v175, vcc, 0, v197, vcc
	global_store_dwordx4 v[174:175], v[158:161], off
	global_store_dwordx4 v[174:175], v[154:157], off offset:64
	global_store_dwordx4 v[174:175], v[150:153], off offset:128
	global_store_dwordx4 v[174:175], v[146:149], off offset:192
.LBB0_612:
	v_cvt_pk_bf16_f32 v240, v158, v159
	v_cvt_pk_bf16_f32 v241, v160, v161
	v_add_co_u32_e32 v160, vcc, 0x1000, v176
	s_nop 1
	v_addc_co_u32_e32 v161, vcc, 0, v177, vcc
	v_mbcnt_lo_u32_b32 v0, -1, 0
	v_mbcnt_hi_u32_b32 v0, -1, v0
	v_bfe_u32 v0, v0, 4, 1
	v_mul_u32_u24_e32 v0, 24, v0
	v_lshl_add_u64 v[248:249], v[160:161], 0, v[0:1]
	v_cvt_pk_bf16_f32 v242, v154, v155
	v_cvt_pk_bf16_f32 v243, v156, v157
	s_nop 1
	v_permlane16_swap_b32_e32 v240, v242
	v_permlane16_swap_b32_e32 v241, v243
	global_store_dwordx4 v[248:249], v[240:243], off
	v_cvt_pk_bf16_f32 v244, v150, v151
	v_cvt_pk_bf16_f32 v245, v152, v153
	s_nop 0
	v_cvt_pk_bf16_f32 v246, v146, v147
	v_cvt_pk_bf16_f32 v247, v148, v149
	s_nop 1
	v_permlane16_swap_b32_e32 v244, v246
	v_permlane16_swap_b32_e32 v245, v247
	global_store_dwordx4 v[248:249], v[244:247], off offset:64
	v_mov_b64_e32 v[176:177], v[194:195]
	v_mov_b64_e32 v[174:175], v[192:193]
	v_pk_fma_f32 v[160:161], v[96:97], v[172:173], v[144:145] op_sel_hi:[1,0,1]
	v_pk_fma_f32 v[158:159], v[94:95], v[172:173], v[142:143] op_sel_hi:[1,0,1]
	v_pk_fma_f32 v[148:149], v[92:93], v[172:173], v[140:141] op_sel_hi:[1,0,1]
	v_pk_fma_f32 v[146:147], v[90:91], v[172:173], v[138:139] op_sel_hi:[1,0,1]
	v_pk_fma_f32 v[152:153], v[88:89], v[172:173], v[136:137] op_sel_hi:[1,0,1]
	v_pk_fma_f32 v[150:151], v[86:87], v[172:173], v[134:135] op_sel_hi:[1,0,1]
	v_pk_fma_f32 v[156:157], v[84:85], v[172:173], v[132:133] op_sel_hi:[1,0,1]
	s_and_b64 vcc, exec, s[42:43]
	v_pk_fma_f32 v[154:155], v[82:83], v[172:173], v[130:131] op_sel_hi:[1,0,1]
	s_cbranch_vccnz .LBB0_614
	v_add_co_u32_e32 v172, vcc, 0x4000, v176
	s_nop 1
	v_addc_co_u32_e32 v173, vcc, 0, v177, vcc
	global_store_dwordx4 v[172:173], v[158:161], off
	global_store_dwordx4 v[172:173], v[146:149], off offset:64
	global_store_dwordx4 v[172:173], v[150:153], off offset:128
	global_store_dwordx4 v[172:173], v[154:157], off offset:192
.LBB0_614:
	v_cvt_pk_bf16_f32 v240, v158, v159
	v_cvt_pk_bf16_f32 v241, v160, v161
	v_add_co_u32_e32 v160, vcc, 0x2000, v174
	v_mov_b64_e32 v[172:173], v[192:193]
	s_nop 0
	v_addc_co_u32_e32 v161, vcc, 0, v175, vcc
	v_mbcnt_lo_u32_b32 v0, -1, 0
	v_mbcnt_hi_u32_b32 v0, -1, v0
	v_bfe_u32 v0, v0, 4, 1
	v_mul_u32_u24_e32 v0, 24, v0
	v_lshl_add_u64 v[248:249], v[160:161], 0, v[0:1]
	v_cvt_pk_bf16_f32 v242, v146, v147
	v_cvt_pk_bf16_f32 v243, v148, v149
	s_nop 1
	v_permlane16_swap_b32_e32 v240, v242
	v_permlane16_swap_b32_e32 v241, v243
	global_store_dwordx4 v[248:249], v[240:243], off
	v_cvt_pk_bf16_f32 v244, v150, v151
	v_cvt_pk_bf16_f32 v245, v152, v153
	s_nop 0
	v_cvt_pk_bf16_f32 v246, v154, v155
	v_cvt_pk_bf16_f32 v247, v156, v157
	s_nop 1
	v_permlane16_swap_b32_e32 v244, v246
	v_permlane16_swap_b32_e32 v245, v247
	global_store_dwordx4 v[248:249], v[244:247], off offset:64
	v_mov_b64_e32 v[174:175], v[194:195]
	v_pk_fma_f32 v[160:161], v[80:81], v[170:171], v[144:145] op_sel_hi:[1,0,1]
	v_pk_fma_f32 v[158:159], v[78:79], v[170:171], v[142:143] op_sel_hi:[1,0,1]
	v_pk_fma_f32 v[156:157], v[76:77], v[170:171], v[140:141] op_sel_hi:[1,0,1]
	v_pk_fma_f32 v[154:155], v[74:75], v[170:171], v[138:139] op_sel_hi:[1,0,1]
	v_pk_fma_f32 v[152:153], v[72:73], v[170:171], v[136:137] op_sel_hi:[1,0,1]
	v_pk_fma_f32 v[150:151], v[70:71], v[170:171], v[134:135] op_sel_hi:[1,0,1]
	v_pk_fma_f32 v[148:149], v[68:69], v[170:171], v[132:133] op_sel_hi:[1,0,1]
	s_and_b64 vcc, exec, s[42:43]
	v_pk_fma_f32 v[146:147], v[66:67], v[170:171], v[130:131] op_sel_hi:[1,0,1]
	s_cbranch_vccnz .LBB0_616
	v_add_co_u32_e32 v170, vcc, 0x6000, v174
	s_nop 1
	v_addc_co_u32_e32 v171, vcc, 0, v175, vcc
	global_store_dwordx4 v[170:171], v[158:161], off
	global_store_dwordx4 v[170:171], v[154:157], off offset:64
	global_store_dwordx4 v[170:171], v[150:153], off offset:128
	global_store_dwordx4 v[170:171], v[146:149], off offset:192
.LBB0_616:
	v_cvt_pk_bf16_f32 v240, v158, v159
	v_cvt_pk_bf16_f32 v241, v160, v161
	v_add_co_u32_e32 v160, vcc, 0x3000, v172
	s_nop 1
	v_addc_co_u32_e32 v161, vcc, 0, v173, vcc
	v_mbcnt_lo_u32_b32 v0, -1, 0
	v_mbcnt_hi_u32_b32 v0, -1, v0
	v_bfe_u32 v0, v0, 4, 1
	v_mul_u32_u24_e32 v0, 24, v0
	v_lshl_add_u64 v[248:249], v[160:161], 0, v[0:1]
	v_cvt_pk_bf16_f32 v242, v154, v155
	v_cvt_pk_bf16_f32 v243, v156, v157
	s_nop 1
	v_permlane16_swap_b32_e32 v240, v242
	v_permlane16_swap_b32_e32 v241, v243
	global_store_dwordx4 v[248:249], v[240:243], off
	v_cvt_pk_bf16_f32 v244, v150, v151
	v_cvt_pk_bf16_f32 v245, v152, v153
	s_nop 0
	v_cvt_pk_bf16_f32 v246, v146, v147
	v_cvt_pk_bf16_f32 v247, v148, v149
	s_nop 1
	v_permlane16_swap_b32_e32 v244, v246
	v_permlane16_swap_b32_e32 v245, v247
	global_store_dwordx4 v[248:249], v[244:247], off offset:64
	v_mov_b64_e32 v[170:171], v[192:193]
	v_mov_b64_e32 v[172:173], v[194:195]
	v_pk_fma_f32 v[160:161], v[64:65], v[168:169], v[144:145] op_sel_hi:[1,0,1]
	v_pk_fma_f32 v[158:159], v[62:63], v[168:169], v[142:143] op_sel_hi:[1,0,1]
	v_pk_fma_f32 v[148:149], v[60:61], v[168:169], v[140:141] op_sel_hi:[1,0,1]
	v_pk_fma_f32 v[146:147], v[58:59], v[168:169], v[138:139] op_sel_hi:[1,0,1]
	v_pk_fma_f32 v[152:153], v[56:57], v[168:169], v[136:137] op_sel_hi:[1,0,1]
	v_pk_fma_f32 v[150:151], v[54:55], v[168:169], v[134:135] op_sel_hi:[1,0,1]
	v_pk_fma_f32 v[156:157], v[52:53], v[168:169], v[132:133] op_sel_hi:[1,0,1]
	s_and_b64 vcc, exec, s[42:43]
	v_pk_fma_f32 v[154:155], v[50:51], v[168:169], v[130:131] op_sel_hi:[1,0,1]
	s_cbranch_vccnz .LBB0_618
	v_add_co_u32_e32 v168, vcc, 0x10000, v172
	s_nop 1
	v_addc_co_u32_e32 v169, vcc, 0, v173, vcc
	global_store_dwordx4 v[168:169], v[158:161], off
	global_store_dwordx4 v[168:169], v[146:149], off offset:64
	global_store_dwordx4 v[168:169], v[150:153], off offset:128
	global_store_dwordx4 v[168:169], v[154:157], off offset:192
.LBB0_618:
	v_cvt_pk_bf16_f32 v240, v158, v159
	v_cvt_pk_bf16_f32 v241, v160, v161
	v_add_co_u32_e32 v160, vcc, 0x8000, v170
	v_mov_b64_e32 v[168:169], v[192:193]
	s_nop 0
	v_addc_co_u32_e32 v161, vcc, 0, v171, vcc
	v_mbcnt_lo_u32_b32 v0, -1, 0
	v_mbcnt_hi_u32_b32 v0, -1, v0
	v_bfe_u32 v0, v0, 4, 1
	v_mul_u32_u24_e32 v0, 24, v0
	v_lshl_add_u64 v[248:249], v[160:161], 0, v[0:1]
	v_cvt_pk_bf16_f32 v242, v146, v147
	v_cvt_pk_bf16_f32 v243, v148, v149
	s_nop 1
	v_permlane16_swap_b32_e32 v240, v242
	v_permlane16_swap_b32_e32 v241, v243
	global_store_dwordx4 v[248:249], v[240:243], off
	v_cvt_pk_bf16_f32 v244, v150, v151
	v_cvt_pk_bf16_f32 v245, v152, v153
	s_nop 0
	v_cvt_pk_bf16_f32 v246, v154, v155
	v_cvt_pk_bf16_f32 v247, v156, v157
	s_nop 1
	v_permlane16_swap_b32_e32 v244, v246
	v_permlane16_swap_b32_e32 v245, v247
	global_store_dwordx4 v[248:249], v[244:247], off offset:64
	v_mov_b64_e32 v[170:171], v[194:195]
	v_pk_fma_f32 v[160:161], v[48:49], v[166:167], v[144:145] op_sel_hi:[1,0,1]
	v_pk_fma_f32 v[158:159], v[46:47], v[166:167], v[142:143] op_sel_hi:[1,0,1]
	v_pk_fma_f32 v[156:157], v[44:45], v[166:167], v[140:141] op_sel_hi:[1,0,1]
	v_pk_fma_f32 v[154:155], v[42:43], v[166:167], v[138:139] op_sel_hi:[1,0,1]
	v_pk_fma_f32 v[152:153], v[40:41], v[166:167], v[136:137] op_sel_hi:[1,0,1]
	v_pk_fma_f32 v[150:151], v[38:39], v[166:167], v[134:135] op_sel_hi:[1,0,1]
	v_pk_fma_f32 v[148:149], v[36:37], v[166:167], v[132:133] op_sel_hi:[1,0,1]
	s_and_b64 vcc, exec, s[42:43]
	v_pk_fma_f32 v[146:147], v[34:35], v[166:167], v[130:131] op_sel_hi:[1,0,1]
	s_cbranch_vccnz .LBB0_620
	v_add_co_u32_e32 v166, vcc, 0x12000, v170
	s_nop 1
	v_addc_co_u32_e32 v167, vcc, 0, v171, vcc
	global_store_dwordx4 v[166:167], v[158:161], off
	global_store_dwordx4 v[166:167], v[154:157], off offset:64
	global_store_dwordx4 v[166:167], v[150:153], off offset:128
	global_store_dwordx4 v[166:167], v[146:149], off offset:192
.LBB0_620:
	v_cvt_pk_bf16_f32 v240, v158, v159
	v_cvt_pk_bf16_f32 v241, v160, v161
	v_add_co_u32_e32 v160, vcc, 0x9000, v168
	s_nop 1
	v_addc_co_u32_e32 v161, vcc, 0, v169, vcc
	v_mbcnt_lo_u32_b32 v0, -1, 0
	v_mbcnt_hi_u32_b32 v0, -1, v0
	v_bfe_u32 v0, v0, 4, 1
	v_mul_u32_u24_e32 v0, 24, v0
	v_lshl_add_u64 v[248:249], v[160:161], 0, v[0:1]
	v_cvt_pk_bf16_f32 v242, v154, v155
	v_cvt_pk_bf16_f32 v243, v156, v157
	s_nop 1
	v_permlane16_swap_b32_e32 v240, v242
	v_permlane16_swap_b32_e32 v241, v243
	global_store_dwordx4 v[248:249], v[240:243], off
	v_cvt_pk_bf16_f32 v244, v150, v151
	v_cvt_pk_bf16_f32 v245, v152, v153
	s_nop 0
	v_cvt_pk_bf16_f32 v246, v146, v147
	v_cvt_pk_bf16_f32 v247, v148, v149
	s_nop 1
	v_permlane16_swap_b32_e32 v244, v246
	v_permlane16_swap_b32_e32 v245, v247
	global_store_dwordx4 v[248:249], v[244:247], off offset:64
	v_mov_b64_e32 v[168:169], v[194:195]
	v_mov_b64_e32 v[166:167], v[192:193]
	v_pk_fma_f32 v[160:161], v[32:33], v[164:165], v[144:145] op_sel_hi:[1,0,1]
	v_pk_fma_f32 v[158:159], v[30:31], v[164:165], v[142:143] op_sel_hi:[1,0,1]
	v_pk_fma_f32 v[148:149], v[28:29], v[164:165], v[140:141] op_sel_hi:[1,0,1]
	v_pk_fma_f32 v[146:147], v[26:27], v[164:165], v[138:139] op_sel_hi:[1,0,1]
	v_pk_fma_f32 v[152:153], v[24:25], v[164:165], v[136:137] op_sel_hi:[1,0,1]
	v_pk_fma_f32 v[150:151], v[22:23], v[164:165], v[134:135] op_sel_hi:[1,0,1]
	v_pk_fma_f32 v[156:157], v[20:21], v[164:165], v[132:133] op_sel_hi:[1,0,1]
	s_and_b64 vcc, exec, s[42:43]
	v_pk_fma_f32 v[154:155], v[18:19], v[164:165], v[130:131] op_sel_hi:[1,0,1]
	s_cbranch_vccnz .LBB0_622
	v_add_co_u32_e32 v164, vcc, 0x14000, v168
	s_nop 1
	v_addc_co_u32_e32 v165, vcc, 0, v169, vcc
	global_store_dwordx4 v[164:165], v[158:161], off
	global_store_dwordx4 v[164:165], v[146:149], off offset:64
	global_store_dwordx4 v[164:165], v[150:153], off offset:128
	global_store_dwordx4 v[164:165], v[154:157], off offset:192
.LBB0_622:
	v_cvt_pk_bf16_f32 v240, v158, v159
	v_cvt_pk_bf16_f32 v241, v160, v161
	v_add_co_u32_e32 v160, vcc, 0xa000, v166
	v_pk_fma_f32 v[144:145], v[16:17], v[162:163], v[144:145] op_sel_hi:[1,0,1]
	s_nop 0
	v_addc_co_u32_e32 v161, vcc, 0, v167, vcc
	v_mbcnt_lo_u32_b32 v0, -1, 0
	v_mbcnt_hi_u32_b32 v0, -1, v0
	v_bfe_u32 v0, v0, 4, 1
	v_mul_u32_u24_e32 v0, 24, v0
	v_lshl_add_u64 v[248:249], v[160:161], 0, v[0:1]
	v_cvt_pk_bf16_f32 v242, v146, v147
	v_cvt_pk_bf16_f32 v243, v148, v149
	s_nop 1
	v_permlane16_swap_b32_e32 v240, v242
	v_permlane16_swap_b32_e32 v241, v243
	global_store_dwordx4 v[248:249], v[240:243], off
	v_cvt_pk_bf16_f32 v244, v150, v151
	v_cvt_pk_bf16_f32 v245, v152, v153
	s_nop 0
	v_cvt_pk_bf16_f32 v246, v154, v155
	v_cvt_pk_bf16_f32 v247, v156, v157
	s_nop 1
	v_permlane16_swap_b32_e32 v244, v246
	v_permlane16_swap_b32_e32 v245, v247
	global_store_dwordx4 v[248:249], v[244:247], off offset:64
	v_mov_b64_e32 v[148:149], v[194:195]
	v_mov_b64_e32 v[146:147], v[192:193]
	v_pk_fma_f32 v[142:143], v[14:15], v[162:163], v[142:143] op_sel_hi:[1,0,1]
	v_pk_fma_f32 v[140:141], v[12:13], v[162:163], v[140:141] op_sel_hi:[1,0,1]
	v_pk_fma_f32 v[138:139], v[10:11], v[162:163], v[138:139] op_sel_hi:[1,0,1]
	v_pk_fma_f32 v[136:137], v[8:9], v[162:163], v[136:137] op_sel_hi:[1,0,1]
	v_pk_fma_f32 v[134:135], v[6:7], v[162:163], v[134:135] op_sel_hi:[1,0,1]
	v_pk_fma_f32 v[132:133], v[4:5], v[162:163], v[132:133] op_sel_hi:[1,0,1]
	s_and_b64 vcc, exec, s[42:43]
	v_pk_fma_f32 v[130:131], v[2:3], v[162:163], v[130:131] op_sel_hi:[1,0,1]
	s_cbranch_vccnz .LBB0_624
	v_add_co_u32_e32 v148, vcc, 0x16000, v148
	s_nop 1
	v_addc_co_u32_e32 v149, vcc, 0, v149, vcc
	global_store_dwordx4 v[148:149], v[142:145], off
	global_store_dwordx4 v[148:149], v[138:141], off offset:64
	global_store_dwordx4 v[148:149], v[134:137], off offset:128
	global_store_dwordx4 v[148:149], v[130:133], off offset:192
.LBB0_624:
	v_cvt_pk_bf16_f32 v240, v142, v143
	v_cvt_pk_bf16_f32 v241, v144, v145
	v_add_co_u32_e32 v144, vcc, 0xb000, v146
	s_nop 1
	v_addc_co_u32_e32 v145, vcc, 0, v147, vcc
	v_mbcnt_lo_u32_b32 v0, -1, 0
	v_mbcnt_hi_u32_b32 v0, -1, v0
	v_bfe_u32 v0, v0, 4, 1
	v_mul_u32_u24_e32 v0, 24, v0
	v_lshl_add_u64 v[248:249], v[144:145], 0, v[0:1]
	v_cvt_pk_bf16_f32 v242, v138, v139
	v_cvt_pk_bf16_f32 v243, v140, v141
	s_nop 1
	v_permlane16_swap_b32_e32 v240, v242
	v_permlane16_swap_b32_e32 v241, v243
	global_store_dwordx4 v[248:249], v[240:243], off
	v_cvt_pk_bf16_f32 v244, v134, v135
	v_cvt_pk_bf16_f32 v245, v136, v137
	s_nop 0
	v_cvt_pk_bf16_f32 v246, v130, v131
	v_cvt_pk_bf16_f32 v247, v132, v133
	s_nop 1
	v_permlane16_swap_b32_e32 v244, v246
	v_permlane16_swap_b32_e32 v245, v247
	global_store_dwordx4 v[248:249], v[244:247], off offset:64
	s_mov_b64 s[56:57], 0

.LBB0_630:
	v_cvt_pk_bf16_f32 v228, v170, v171
	v_cvt_pk_bf16_f32 v229, v172, v173
	v_mbcnt_lo_u32_b32 v0, -1, 0
	v_mbcnt_hi_u32_b32 v0, -1, v0
	v_bfe_u32 v0, v0, 4, 1
	v_mul_u32_u24_e32 v0, 24, v0
	v_lshl_add_u64 v[236:237], v[210:211], 0, v[0:1]
	v_cvt_pk_bf16_f32 v230, v174, v175
	v_cvt_pk_bf16_f32 v231, v176, v177
	s_nop 1
	v_permlane16_swap_b32_e32 v228, v230
	v_permlane16_swap_b32_e32 v229, v231
	global_store_dwordx4 v[236:237], v[228:231], off
	v_cvt_pk_bf16_f32 v232, v162, v163
	v_cvt_pk_bf16_f32 v233, v164, v165
	s_nop 0
	v_cvt_pk_bf16_f32 v234, v166, v167
	v_cvt_pk_bf16_f32 v235, v168, v169
	s_nop 1
	v_permlane16_swap_b32_e32 v232, v234
	v_permlane16_swap_b32_e32 v233, v235
	global_store_dwordx4 v[236:237], v[232:235], off offset:64
	v_pk_fma_f32 v[162:163], v[112:113], v[208:209], v[160:161] op_sel_hi:[1,0,1]
	v_pk_fma_f32 v[164:165], v[110:111], v[208:209], v[158:159] op_sel_hi:[1,0,1]
	v_mul_f32_e32 v171, v163, v163
	v_mul_f32_e32 v170, v165, v165
	v_pk_fma_f32 v[166:167], v[108:109], v[208:209], v[156:157] op_sel_hi:[1,0,1]
	v_pk_fma_f32 v[168:169], v[106:107], v[208:209], v[154:155] op_sel_hi:[1,0,1]
	v_fmac_f32_e32 v170, v164, v164
	v_fmac_f32_e32 v171, v162, v162
	v_add_f32_e32 v170, v170, v171
	v_mul_f32_e32 v171, v169, v169
	v_mul_f32_e32 v172, v167, v167
	v_fmac_f32_e32 v171, v168, v168
	v_fmac_f32_e32 v172, v166, v166
	v_pk_fma_f32 v[174:175], v[104:105], v[208:209], v[152:153] op_sel_hi:[1,0,1]
	v_pk_fma_f32 v[176:177], v[102:103], v[208:209], v[150:151] op_sel_hi:[1,0,1]
	v_add_f32_e32 v171, v171, v172
	v_add_f32_e32 v170, v170, v171
	v_mul_f32_e32 v171, v177, v177
	v_mul_f32_e32 v172, v175, v175
	v_fmac_f32_e32 v171, v176, v176
	v_fmac_f32_e32 v172, v174, v174
	v_pk_fma_f32 v[212:213], v[100:101], v[208:209], v[148:149] op_sel_hi:[1,0,1]
	v_pk_fma_f32 v[228:229], v[98:99], v[208:209], v[146:147] op_sel_hi:[1,0,1]
	v_add_f32_e32 v171, v171, v172
	v_add_f32_e32 v170, v170, v171
	v_mul_f32_e32 v171, v229, v229
	v_mul_f32_e32 v172, v213, v213
	v_fmac_f32_e32 v171, v228, v228
	v_fmac_f32_e32 v172, v212, v212
	v_add_f32_e32 v171, v171, v172
	v_add_f32_e32 v170, v170, v171
	v_mov_b32_e32 v171, v170
	s_nop 1
	v_permlane16_swap_b32_e32 v170, v171
	v_add_f32_e32 v170, v170, v171
	v_mov_b32_e32 v171, v170
	s_nop 1
	v_permlane32_swap_b32_e32 v170, v171
	v_add_f32_e32 v170, v170, v171
	v_fmamk_f32 v170, v170, 0x3c800000, v223
	v_rsq_f32_e32 v222, v170
	v_add_u32_e32 v205, 16, v216
	v_and_b32_e32 v207, 63, v205
	v_mov_b64_e32 v[210:211], v[194:195]
	v_pk_mul_f32 v[164:165], v[164:165], v[222:223] op_sel_hi:[1,0]
	v_pk_mul_f32 v[162:163], v[162:163], v[222:223] op_sel_hi:[1,0]
	v_pk_mul_f32 v[170:171], v[130:131], v[164:165]
	v_pk_mul_f32 v[172:173], v[132:133], v[162:163]
	v_pk_mul_f32 v[162:163], v[168:169], v[222:223] op_sel_hi:[1,0]
	v_pk_mul_f32 v[164:165], v[166:167], v[222:223] op_sel_hi:[1,0]
	v_pk_mul_f32 v[166:167], v[134:135], v[162:163]
	v_pk_mul_f32 v[168:169], v[136:137], v[164:165]
	v_pk_mul_f32 v[162:163], v[176:177], v[222:223] op_sel_hi:[1,0]
	v_pk_mul_f32 v[164:165], v[174:175], v[222:223] op_sel_hi:[1,0]
	v_pk_mul_f32 v[174:175], v[228:229], v[222:223] op_sel_hi:[1,0]
	v_pk_mul_f32 v[176:177], v[212:213], v[222:223] op_sel_hi:[1,0]
	v_cvt_f32_ubyte0_e32 v212, v207
	v_mov_b64_e32 v[208:209], v[192:193]
	v_pk_mul_f32 v[164:165], v[140:141], v[164:165]
	v_pk_mul_f32 v[162:163], v[138:139], v[162:163]
	v_pk_mul_f32 v[176:177], v[144:145], v[176:177]
	v_pk_mul_f32 v[174:175], v[142:143], v[174:175]
	s_and_b64 vcc, exec, s[44:45]
	v_mul_f32_e32 v245, v220, v212
	v_mul_f32_e32 v243, v219, v212
	v_mul_f32_e32 v241, v218, v212
	v_mul_f32_e32 v213, v197, v212
	s_cbranch_vccnz .LBB0_632
	v_ashrrev_i32_e32 v205, 6, v205
	v_cvt_f32_i32_e32 v205, v205
	v_mul_f32_e32 v207, v220, v205
	v_mul_f32_e32 v222, v219, v205
	v_floor_f32_e32 v207, v207
	v_floor_f32_e32 v222, v222
	v_fma_f32 v207, v220, v205, -v207
	v_sin_f32_e32 v228, v207
	v_cos_f32_e32 v230, v207
	v_fma_f32 v207, v219, v205, -v222
	v_sin_f32_e32 v229, v207
	v_cos_f32_e32 v231, v207
	v_mul_f32_e32 v207, v218, v205
	v_floor_f32_e32 v207, v207
	v_pk_mul_f32 v[232:233], v[228:229], v[166:167]
	v_pk_mul_f32 v[166:167], v[230:231], v[166:167]
	v_mul_f32_e32 v224, v197, v205
	v_fma_f32 v207, v218, v205, -v207
	v_floor_f32_e32 v224, v224
	v_pk_fma_f32 v[230:231], v[230:231], v[170:171], v[232:233] neg_lo:[0,0,1] neg_hi:[0,0,1]
	v_pk_fma_f32 v[166:167], v[228:229], v[170:171], v[166:167]
	v_floor_f32_e32 v170, v245
	v_cos_f32_e32 v222, v207
	v_sin_f32_e32 v207, v207
	v_fma_f32 v205, v197, v205, -v224
	v_fma_f32 v171, v220, v212, -v170
	v_sin_f32_e32 v247, v205
	v_cos_f32_e32 v246, v205
	v_sin_f32_e32 v170, v171
	v_cos_f32_e32 v228, v171
	v_floor_f32_e32 v171, v243
	v_fma_f32 v205, v219, v212, -v171
	v_sin_f32_e32 v171, v205
	v_cos_f32_e32 v229, v205
	v_floor_f32_e32 v205, v241
	v_mul_f32_e32 v234, v222, v172
	v_mul_f32_e32 v236, v207, v168
	v_mul_f32_e32 v250, v222, v168
	v_mov_b32_e32 v168, v173
	v_fma_f32 v205, v218, v212, -v205
	v_floor_f32_e32 v222, v213
	v_mul_f32_e32 v248, v207, v172
	v_pk_mul_f32 v[172:173], v[246:247], v[168:169]
	v_cos_f32_e32 v207, v205
	v_sin_f32_e32 v205, v205
	v_fma_f32 v222, v197, v212, -v222
	v_mov_b32_e32 v235, v172
	v_mov_b32_e32 v237, v173
	v_mov_b32_e32 v172, v247
	v_mov_b32_e32 v173, v246
	v_sin_f32_e32 v247, v222
	v_cos_f32_e32 v246, v222
	v_pk_mul_f32 v[168:169], v[172:173], v[168:169]
	v_pk_add_f32 v[172:173], v[234:235], v[236:237] neg_lo:[0,1] neg_hi:[0,1]
	v_mov_b32_e32 v249, v168
	v_mov_b32_e32 v251, v169
	v_pk_add_f32 v[168:169], v[248:249], v[250:251]
	v_mul_f32_e32 v236, v205, v176
	v_mul_f32_e32 v250, v207, v176
	v_mov_b32_e32 v176, v165
	v_mul_f32_e32 v234, v207, v164
	v_mul_f32_e32 v248, v205, v164
	v_pk_mul_f32 v[164:165], v[246:247], v[176:177]
	v_pk_mul_f32 v[232:233], v[170:171], v[174:175]
	v_mov_b32_e32 v235, v164
	v_mov_b32_e32 v237, v165
	v_mov_b32_e32 v164, v247
	v_mov_b32_e32 v165, v246
	v_pk_mul_f32 v[164:165], v[164:165], v[176:177]
	v_pk_mul_f32 v[174:175], v[228:229], v[174:175]
	v_mov_b32_e32 v249, v164
	v_mov_b32_e32 v251, v165
	v_pk_fma_f32 v[228:229], v[228:229], v[162:163], v[232:233] neg_lo:[0,0,1] neg_hi:[0,0,1]
	v_pk_add_f32 v[164:165], v[234:235], v[236:237] neg_lo:[0,1] neg_hi:[0,1]
	v_pk_fma_f32 v[174:175], v[170:171], v[162:163], v[174:175]
	v_pk_add_f32 v[176:177], v[248:249], v[250:251]
	v_mov_b32_e32 v170, v230
	v_mov_b32_e32 v171, v231
	v_mov_b32_e32 v162, v228
	v_mov_b32_e32 v163, v229

.LBB0_634:
	v_cvt_pk_bf16_f32 v228, v170, v171
	v_cvt_pk_bf16_f32 v229, v172, v173
	v_add_co_u32_e32 v172, vcc, 0x1000, v208
	v_xor_b32_e32 v203, 32, v203
	s_nop 0
	v_addc_co_u32_e32 v173, vcc, 0, v209, vcc
	v_mbcnt_lo_u32_b32 v0, -1, 0
	v_mbcnt_hi_u32_b32 v0, -1, v0
	v_bfe_u32 v0, v0, 4, 1
	v_mul_u32_u24_e32 v0, 24, v0
	v_lshl_add_u64 v[236:237], v[172:173], 0, v[0:1]
	v_cvt_pk_bf16_f32 v230, v166, v167
	v_cvt_pk_bf16_f32 v231, v168, v169
	s_nop 1
	v_permlane16_swap_b32_e32 v228, v230
	v_permlane16_swap_b32_e32 v229, v231
	global_store_dwordx4 v[236:237], v[228:231], off
	v_cvt_pk_bf16_f32 v232, v162, v163
	v_cvt_pk_bf16_f32 v233, v164, v165
	s_nop 0
	v_cvt_pk_bf16_f32 v234, v174, v175
	v_cvt_pk_bf16_f32 v235, v176, v177
	s_nop 1
	v_permlane16_swap_b32_e32 v232, v234
	v_permlane16_swap_b32_e32 v233, v235
	global_store_dwordx4 v[236:237], v[232:235], off offset:64
	v_pk_fma_f32 v[162:163], v[96:97], v[206:207], v[160:161] op_sel_hi:[1,0,1]
	v_pk_fma_f32 v[164:165], v[94:95], v[206:207], v[158:159] op_sel_hi:[1,0,1]
	v_mul_f32_e32 v171, v163, v163
	v_mul_f32_e32 v170, v165, v165
	v_pk_fma_f32 v[166:167], v[92:93], v[206:207], v[156:157] op_sel_hi:[1,0,1]
	v_pk_fma_f32 v[168:169], v[90:91], v[206:207], v[154:155] op_sel_hi:[1,0,1]
	v_fmac_f32_e32 v170, v164, v164
	v_fmac_f32_e32 v171, v162, v162
	v_add_f32_e32 v170, v170, v171
	v_mul_f32_e32 v171, v169, v169
	v_mul_f32_e32 v172, v167, v167
	v_fmac_f32_e32 v171, v168, v168
	v_fmac_f32_e32 v172, v166, v166
	v_pk_fma_f32 v[174:175], v[88:89], v[206:207], v[152:153] op_sel_hi:[1,0,1]
	v_pk_fma_f32 v[176:177], v[86:87], v[206:207], v[150:151] op_sel_hi:[1,0,1]
	v_add_f32_e32 v171, v171, v172
	v_add_f32_e32 v170, v170, v171
	v_mul_f32_e32 v171, v177, v177
	v_mul_f32_e32 v172, v175, v175
	v_fmac_f32_e32 v171, v176, v176
	v_fmac_f32_e32 v172, v174, v174
	v_pk_fma_f32 v[210:211], v[84:85], v[206:207], v[148:149] op_sel_hi:[1,0,1]
	v_pk_fma_f32 v[228:229], v[82:83], v[206:207], v[146:147] op_sel_hi:[1,0,1]
	v_add_f32_e32 v171, v171, v172
	v_add_f32_e32 v170, v170, v171
	v_mul_f32_e32 v171, v229, v229
	v_mul_f32_e32 v172, v211, v211
	v_fmac_f32_e32 v171, v228, v228
	v_fmac_f32_e32 v172, v210, v210
	v_add_f32_e32 v171, v171, v172
	v_add_f32_e32 v170, v170, v171
	v_mov_b32_e32 v171, v170
	s_nop 1
	v_permlane16_swap_b32_e32 v170, v171
	v_add_f32_e32 v170, v170, v171
	v_mov_b32_e32 v171, v170
	s_nop 1
	v_permlane32_swap_b32_e32 v170, v171
	v_add_f32_e32 v170, v170, v171
	v_fmamk_f32 v170, v170, 0x3c800000, v223
	v_rsq_f32_e32 v222, v170
	v_mov_b64_e32 v[208:209], v[194:195]
	v_mov_b64_e32 v[206:207], v[192:193]
	s_and_b64 vcc, exec, s[44:45]
	v_pk_mul_f32 v[164:165], v[164:165], v[222:223] op_sel_hi:[1,0]
	v_pk_mul_f32 v[162:163], v[162:163], v[222:223] op_sel_hi:[1,0]
	v_pk_mul_f32 v[170:171], v[130:131], v[164:165]
	v_pk_mul_f32 v[172:173], v[132:133], v[162:163]
	v_pk_mul_f32 v[162:163], v[168:169], v[222:223] op_sel_hi:[1,0]
	v_pk_mul_f32 v[164:165], v[166:167], v[222:223] op_sel_hi:[1,0]
	v_pk_mul_f32 v[166:167], v[134:135], v[162:163]
	v_pk_mul_f32 v[168:169], v[136:137], v[164:165]
	v_pk_mul_f32 v[162:163], v[176:177], v[222:223] op_sel_hi:[1,0]
	v_pk_mul_f32 v[164:165], v[174:175], v[222:223] op_sel_hi:[1,0]
	v_pk_mul_f32 v[174:175], v[228:229], v[222:223] op_sel_hi:[1,0]
	v_pk_mul_f32 v[176:177], v[210:211], v[222:223] op_sel_hi:[1,0]
	v_cvt_f32_ubyte0_e32 v210, v203
	v_pk_mul_f32 v[164:165], v[140:141], v[164:165]
	v_pk_mul_f32 v[162:163], v[138:139], v[162:163]
	v_pk_mul_f32 v[176:177], v[144:145], v[176:177]
	v_pk_mul_f32 v[174:175], v[142:143], v[174:175]
	v_mul_f32_e32 v247, v220, v210
	v_mul_f32_e32 v246, v219, v210
	v_mul_f32_e32 v242, v218, v210
	v_mul_f32_e32 v211, v197, v210
	s_cbranch_vccnz .LBB0_636
	v_add_u32_e32 v203, 32, v216
	v_ashrrev_i32_e32 v203, 6, v203
	v_cvt_f32_i32_e32 v203, v203
	v_mul_f32_e32 v205, v220, v203
	v_mul_f32_e32 v222, v219, v203
	v_floor_f32_e32 v205, v205
	v_floor_f32_e32 v222, v222
	v_fma_f32 v205, v220, v203, -v205
	v_sin_f32_e32 v228, v205
	v_cos_f32_e32 v230, v205
	v_fma_f32 v205, v219, v203, -v222
	v_sin_f32_e32 v229, v205
	v_cos_f32_e32 v231, v205
	v_mul_f32_e32 v205, v218, v203
	v_floor_f32_e32 v205, v205
	v_pk_mul_f32 v[232:233], v[228:229], v[166:167]
	v_pk_mul_f32 v[166:167], v[230:231], v[166:167]
	v_mul_f32_e32 v224, v197, v203
	v_fma_f32 v205, v218, v203, -v205
	v_floor_f32_e32 v224, v224
	v_pk_fma_f32 v[230:231], v[230:231], v[170:171], v[232:233] neg_lo:[0,0,1] neg_hi:[0,0,1]
	v_pk_fma_f32 v[166:167], v[228:229], v[170:171], v[166:167]
	v_floor_f32_e32 v170, v247
	v_cos_f32_e32 v222, v205
	v_sin_f32_e32 v205, v205
	v_fma_f32 v203, v197, v203, -v224
	v_fma_f32 v171, v220, v210, -v170
	v_sin_f32_e32 v249, v203
	v_cos_f32_e32 v248, v203
	v_sin_f32_e32 v170, v171
	v_cos_f32_e32 v228, v171
	v_floor_f32_e32 v171, v246
	v_fma_f32 v203, v219, v210, -v171
	v_sin_f32_e32 v171, v203
	v_cos_f32_e32 v229, v203
	v_floor_f32_e32 v203, v242
	v_mul_f32_e32 v234, v222, v172
	v_mul_f32_e32 v236, v205, v168
	v_mul_f32_e32 v252, v222, v168
	v_mov_b32_e32 v168, v173
	v_fma_f32 v203, v218, v210, -v203
	v_floor_f32_e32 v222, v211
	v_mul_f32_e32 v250, v205, v172
	v_pk_mul_f32 v[172:173], v[248:249], v[168:169]
	v_cos_f32_e32 v205, v203
	v_sin_f32_e32 v203, v203
	v_fma_f32 v222, v197, v210, -v222
	v_mov_b32_e32 v235, v172
	v_mov_b32_e32 v237, v173
	v_mov_b32_e32 v172, v249
	v_mov_b32_e32 v173, v248
	v_sin_f32_e32 v249, v222
	v_cos_f32_e32 v248, v222
	v_pk_mul_f32 v[168:169], v[172:173], v[168:169]
	v_pk_add_f32 v[172:173], v[234:235], v[236:237] neg_lo:[0,1] neg_hi:[0,1]
	v_mov_b32_e32 v251, v168
	v_mov_b32_e32 v253, v169
	v_pk_add_f32 v[168:169], v[250:251], v[252:253]
	v_mul_f32_e32 v236, v203, v176
	v_mul_f32_e32 v252, v205, v176
	v_mov_b32_e32 v176, v165
	v_mul_f32_e32 v234, v205, v164
	v_mul_f32_e32 v250, v203, v164
	v_pk_mul_f32 v[164:165], v[248:249], v[176:177]
	v_pk_mul_f32 v[232:233], v[170:171], v[174:175]
	v_mov_b32_e32 v235, v164
	v_mov_b32_e32 v237, v165
	v_mov_b32_e32 v164, v249
	v_mov_b32_e32 v165, v248
	v_pk_mul_f32 v[164:165], v[164:165], v[176:177]
	v_pk_mul_f32 v[174:175], v[228:229], v[174:175]
	v_mov_b32_e32 v251, v164
	v_mov_b32_e32 v253, v165
	v_pk_fma_f32 v[228:229], v[228:229], v[162:163], v[232:233] neg_lo:[0,0,1] neg_hi:[0,0,1]
	v_pk_add_f32 v[164:165], v[234:235], v[236:237] neg_lo:[0,1] neg_hi:[0,1]
	v_pk_fma_f32 v[174:175], v[170:171], v[162:163], v[174:175]
	v_pk_add_f32 v[176:177], v[250:251], v[252:253]
	v_mov_b32_e32 v170, v230
	v_mov_b32_e32 v171, v231
	v_mov_b32_e32 v162, v228
	v_mov_b32_e32 v163, v229

.LBB0_638:
	v_cvt_pk_bf16_f32 v228, v170, v171
	v_cvt_pk_bf16_f32 v229, v172, v173
	v_add_co_u32_e32 v172, vcc, 0x2000, v206
	v_pk_fma_f32 v[208:209], v[68:69], v[204:205], v[148:149] op_sel_hi:[1,0,1]
	s_nop 0
	v_addc_co_u32_e32 v173, vcc, 0, v207, vcc
	v_mbcnt_lo_u32_b32 v0, -1, 0
	v_mbcnt_hi_u32_b32 v0, -1, v0
	v_bfe_u32 v0, v0, 4, 1
	v_mul_u32_u24_e32 v0, 24, v0
	v_lshl_add_u64 v[236:237], v[172:173], 0, v[0:1]
	v_cvt_pk_bf16_f32 v230, v166, v167
	v_cvt_pk_bf16_f32 v231, v168, v169
	s_nop 1
	v_permlane16_swap_b32_e32 v228, v230
	v_permlane16_swap_b32_e32 v229, v231
	global_store_dwordx4 v[236:237], v[228:231], off
	v_cvt_pk_bf16_f32 v232, v162, v163
	v_cvt_pk_bf16_f32 v233, v164, v165
	s_nop 0
	v_cvt_pk_bf16_f32 v234, v174, v175
	v_cvt_pk_bf16_f32 v235, v176, v177
	s_nop 1
	v_permlane16_swap_b32_e32 v232, v234
	v_permlane16_swap_b32_e32 v233, v235
	global_store_dwordx4 v[236:237], v[232:235], off offset:64
	v_pk_fma_f32 v[162:163], v[80:81], v[204:205], v[160:161] op_sel_hi:[1,0,1]
	v_pk_fma_f32 v[164:165], v[78:79], v[204:205], v[158:159] op_sel_hi:[1,0,1]
	v_mul_f32_e32 v171, v163, v163
	v_mul_f32_e32 v170, v165, v165
	v_pk_fma_f32 v[166:167], v[76:77], v[204:205], v[156:157] op_sel_hi:[1,0,1]
	v_pk_fma_f32 v[168:169], v[74:75], v[204:205], v[154:155] op_sel_hi:[1,0,1]
	v_fmac_f32_e32 v170, v164, v164
	v_fmac_f32_e32 v171, v162, v162
	v_add_f32_e32 v170, v170, v171
	v_mul_f32_e32 v171, v169, v169
	v_mul_f32_e32 v172, v167, v167
	v_fmac_f32_e32 v171, v168, v168
	v_fmac_f32_e32 v172, v166, v166
	v_pk_fma_f32 v[174:175], v[72:73], v[204:205], v[152:153] op_sel_hi:[1,0,1]
	v_pk_fma_f32 v[176:177], v[70:71], v[204:205], v[150:151] op_sel_hi:[1,0,1]
	v_add_f32_e32 v171, v171, v172
	v_add_f32_e32 v170, v170, v171
	v_mul_f32_e32 v171, v177, v177
	v_mul_f32_e32 v172, v175, v175
	v_fmac_f32_e32 v171, v176, v176
	v_fmac_f32_e32 v172, v174, v174
	v_pk_fma_f32 v[228:229], v[66:67], v[204:205], v[146:147] op_sel_hi:[1,0,1]
	v_add_f32_e32 v171, v171, v172
	v_add_f32_e32 v170, v170, v171
	v_mul_f32_e32 v171, v229, v229
	v_mul_f32_e32 v172, v209, v209
	v_fmac_f32_e32 v171, v228, v228
	v_fmac_f32_e32 v172, v208, v208
	v_add_f32_e32 v171, v171, v172
	v_add_f32_e32 v170, v170, v171
	v_mov_b32_e32 v171, v170
	s_nop 1
	v_permlane16_swap_b32_e32 v170, v171
	v_add_f32_e32 v170, v170, v171
	v_mov_b32_e32 v171, v170
	s_nop 1
	v_permlane32_swap_b32_e32 v170, v171
	v_add_f32_e32 v170, v170, v171
	v_fmamk_f32 v170, v170, 0x3c800000, v223
	v_rsq_f32_e32 v222, v170
	v_add_u32_e32 v203, 48, v216
	v_and_b32_e32 v224, 63, v203
	v_mov_b64_e32 v[206:207], v[194:195]
	v_pk_mul_f32 v[164:165], v[164:165], v[222:223] op_sel_hi:[1,0]
	v_pk_mul_f32 v[162:163], v[162:163], v[222:223] op_sel_hi:[1,0]
	v_pk_mul_f32 v[170:171], v[130:131], v[164:165]
	v_pk_mul_f32 v[172:173], v[132:133], v[162:163]
	v_pk_mul_f32 v[162:163], v[168:169], v[222:223] op_sel_hi:[1,0]
	v_pk_mul_f32 v[164:165], v[166:167], v[222:223] op_sel_hi:[1,0]
	v_pk_mul_f32 v[166:167], v[134:135], v[162:163]
	v_pk_mul_f32 v[168:169], v[136:137], v[164:165]
	v_pk_mul_f32 v[162:163], v[176:177], v[222:223] op_sel_hi:[1,0]
	v_pk_mul_f32 v[164:165], v[174:175], v[222:223] op_sel_hi:[1,0]
	v_pk_mul_f32 v[174:175], v[228:229], v[222:223] op_sel_hi:[1,0]
	v_pk_mul_f32 v[176:177], v[208:209], v[222:223] op_sel_hi:[1,0]
	v_cvt_f32_ubyte0_e32 v208, v224
	v_mov_b64_e32 v[204:205], v[192:193]
	v_pk_mul_f32 v[164:165], v[140:141], v[164:165]
	v_pk_mul_f32 v[162:163], v[138:139], v[162:163]
	v_pk_mul_f32 v[176:177], v[144:145], v[176:177]
	v_pk_mul_f32 v[174:175], v[142:143], v[174:175]
	s_and_b64 vcc, exec, s[44:45]
	v_mul_f32_e32 v249, v220, v208
	v_mul_f32_e32 v248, v219, v208
	v_mul_f32_e32 v244, v218, v208
	v_mul_f32_e32 v209, v197, v208
	s_cbranch_vccnz .LBB0_640
	v_ashrrev_i32_e32 v203, 6, v203
	v_cvt_f32_i32_e32 v203, v203
	v_mul_f32_e32 v222, v220, v203
	v_mul_f32_e32 v224, v219, v203
	v_floor_f32_e32 v222, v222
	v_floor_f32_e32 v224, v224
	v_fma_f32 v222, v220, v203, -v222
	v_sin_f32_e32 v228, v222
	v_cos_f32_e32 v230, v222
	v_fma_f32 v222, v219, v203, -v224
	v_sin_f32_e32 v229, v222
	v_cos_f32_e32 v231, v222
	v_mul_f32_e32 v222, v218, v203
	v_floor_f32_e32 v222, v222
	v_mul_f32_e32 v225, v197, v203
	v_fma_f32 v222, v218, v203, -v222
	v_floor_f32_e32 v225, v225
	v_cos_f32_e32 v224, v222
	v_sin_f32_e32 v222, v222
	v_fma_f32 v203, v197, v203, -v225
	v_sin_f32_e32 v251, v203
	v_cos_f32_e32 v250, v203
	v_mul_f32_e32 v234, v224, v172
	v_mul_f32_e32 v236, v222, v168
	v_mul_f32_e32 v224, v224, v168
	v_mov_b32_e32 v168, v173
	v_mul_f32_e32 v252, v222, v172
	v_pk_mul_f32 v[172:173], v[250:251], v[168:169]
	v_pk_mul_f32 v[232:233], v[228:229], v[166:167]
	v_pk_mul_f32 v[166:167], v[230:231], v[166:167]
	v_mov_b32_e32 v235, v172
	v_mov_b32_e32 v237, v173
	v_mov_b32_e32 v172, v251
	v_mov_b32_e32 v173, v250
	v_pk_mul_f32 v[168:169], v[172:173], v[168:169]
	v_pk_fma_f32 v[230:231], v[230:231], v[170:171], v[232:233] neg_lo:[0,0,1] neg_hi:[0,0,1]
	v_pk_fma_f32 v[166:167], v[228:229], v[170:171], v[166:167]
	v_floor_f32_e32 v170, v249
	v_mov_b32_e32 v253, v168
	v_mov_b32_e32 v225, v169
	v_fma_f32 v171, v220, v208, -v170
	v_pk_add_f32 v[168:169], v[252:253], v[224:225]
	v_sin_f32_e32 v170, v171
	v_cos_f32_e32 v224, v171
	v_floor_f32_e32 v171, v248
	v_fma_f32 v203, v219, v208, -v171
	v_sin_f32_e32 v171, v203
	v_cos_f32_e32 v225, v203
	v_floor_f32_e32 v203, v244
	v_fma_f32 v203, v218, v208, -v203
	v_floor_f32_e32 v233, v209
	v_cos_f32_e32 v222, v203
	v_sin_f32_e32 v203, v203
	v_fma_f32 v233, v197, v208, -v233
	v_pk_add_f32 v[172:173], v[234:235], v[236:237] neg_lo:[0,1] neg_hi:[0,1]
	v_sin_f32_e32 v237, v233
	v_cos_f32_e32 v236, v233
	v_mul_f32_e32 v234, v203, v176
	v_mul_f32_e32 v252, v222, v176
	v_mov_b32_e32 v176, v165
	v_mul_f32_e32 v232, v222, v164
	v_mul_f32_e32 v250, v203, v164
	v_pk_mul_f32 v[164:165], v[236:237], v[176:177]
	v_pk_mul_f32 v[228:229], v[170:171], v[174:175]
	v_mov_b32_e32 v233, v164
	v_mov_b32_e32 v235, v165
	v_mov_b32_e32 v164, v237
	v_mov_b32_e32 v165, v236
	v_pk_mul_f32 v[164:165], v[164:165], v[176:177]
	v_pk_mul_f32 v[174:175], v[224:225], v[174:175]
	v_mov_b32_e32 v251, v164
	v_mov_b32_e32 v253, v165
	v_pk_fma_f32 v[224:225], v[224:225], v[162:163], v[228:229] neg_lo:[0,0,1] neg_hi:[0,0,1]
	v_pk_add_f32 v[164:165], v[232:233], v[234:235] neg_lo:[0,1] neg_hi:[0,1]
	v_pk_fma_f32 v[174:175], v[170:171], v[162:163], v[174:175]
	v_pk_add_f32 v[176:177], v[250:251], v[252:253]
	v_mov_b32_e32 v170, v230
	v_mov_b32_e32 v171, v231
	v_mov_b32_e32 v162, v224
	v_mov_b32_e32 v163, v225

.LBB0_642:
	v_cvt_pk_bf16_f32 v228, v170, v171
	v_cvt_pk_bf16_f32 v229, v172, v173
	v_add_co_u32_e32 v172, vcc, 0x3000, v204
	s_nop 1
	v_addc_co_u32_e32 v173, vcc, 0, v205, vcc
	v_mbcnt_lo_u32_b32 v0, -1, 0
	v_mbcnt_hi_u32_b32 v0, -1, v0
	v_bfe_u32 v0, v0, 4, 1
	v_mul_u32_u24_e32 v0, 24, v0
	v_lshl_add_u64 v[236:237], v[172:173], 0, v[0:1]
	v_cvt_pk_bf16_f32 v230, v166, v167
	v_cvt_pk_bf16_f32 v231, v168, v169
	s_nop 1
	v_permlane16_swap_b32_e32 v228, v230
	v_permlane16_swap_b32_e32 v229, v231
	global_store_dwordx4 v[236:237], v[228:231], off
	v_cvt_pk_bf16_f32 v232, v162, v163
	v_cvt_pk_bf16_f32 v233, v164, v165
	s_nop 0
	v_cvt_pk_bf16_f32 v234, v174, v175
	v_cvt_pk_bf16_f32 v235, v176, v177
	s_nop 1
	v_permlane16_swap_b32_e32 v232, v234
	v_permlane16_swap_b32_e32 v233, v235
	global_store_dwordx4 v[236:237], v[232:235], off offset:64
	v_pk_fma_f32 v[162:163], v[64:65], v[202:203], v[160:161] op_sel_hi:[1,0,1]
	v_pk_fma_f32 v[164:165], v[62:63], v[202:203], v[158:159] op_sel_hi:[1,0,1]
	v_mul_f32_e32 v171, v163, v163
	v_mul_f32_e32 v170, v165, v165
	v_pk_fma_f32 v[166:167], v[60:61], v[202:203], v[156:157] op_sel_hi:[1,0,1]
	v_pk_fma_f32 v[168:169], v[58:59], v[202:203], v[154:155] op_sel_hi:[1,0,1]
	v_fmac_f32_e32 v170, v164, v164
	v_fmac_f32_e32 v171, v162, v162
	v_add_f32_e32 v170, v170, v171
	v_mul_f32_e32 v171, v169, v169
	v_mul_f32_e32 v172, v167, v167
	v_fmac_f32_e32 v171, v168, v168
	v_fmac_f32_e32 v172, v166, v166
	v_pk_fma_f32 v[174:175], v[56:57], v[202:203], v[152:153] op_sel_hi:[1,0,1]
	v_pk_fma_f32 v[176:177], v[54:55], v[202:203], v[150:151] op_sel_hi:[1,0,1]
	v_add_f32_e32 v171, v171, v172
	v_add_f32_e32 v170, v170, v171
	v_mul_f32_e32 v171, v177, v177
	v_mul_f32_e32 v172, v175, v175
	v_fmac_f32_e32 v171, v176, v176
	v_fmac_f32_e32 v172, v174, v174
	v_pk_fma_f32 v[206:207], v[52:53], v[202:203], v[148:149] op_sel_hi:[1,0,1]
	v_pk_fma_f32 v[224:225], v[50:51], v[202:203], v[146:147] op_sel_hi:[1,0,1]
	v_add_f32_e32 v171, v171, v172
	v_add_f32_e32 v170, v171, v170
	v_mul_f32_e32 v171, v225, v225
	v_mul_f32_e32 v172, v207, v207
	v_fmac_f32_e32 v171, v224, v224
	v_fmac_f32_e32 v172, v206, v206
	v_add_f32_e32 v171, v171, v172
	v_add_f32_e32 v170, v171, v170
	v_mov_b32_e32 v171, v170
	s_nop 1
	v_permlane16_swap_b32_e32 v170, v171
	v_add_f32_e32 v170, v170, v171
	v_mov_b32_e32 v171, v170
	s_nop 1
	v_permlane32_swap_b32_e32 v170, v171
	v_add_f32_e32 v170, v170, v171
	v_fmamk_f32 v170, v170, 0x3c800000, v223
	v_rsq_f32_e32 v222, v170
	v_mov_b64_e32 v[202:203], v[192:193]
	v_mov_b64_e32 v[204:205], v[194:195]
	s_and_b64 vcc, exec, s[44:45]
	v_pk_mul_f32 v[164:165], v[164:165], v[222:223] op_sel_hi:[1,0]
	v_pk_mul_f32 v[162:163], v[162:163], v[222:223] op_sel_hi:[1,0]
	v_pk_mul_f32 v[170:171], v[130:131], v[164:165]
	v_pk_mul_f32 v[172:173], v[132:133], v[162:163]
	v_pk_mul_f32 v[162:163], v[168:169], v[222:223] op_sel_hi:[1,0]
	v_pk_mul_f32 v[164:165], v[166:167], v[222:223] op_sel_hi:[1,0]
	v_pk_mul_f32 v[166:167], v[134:135], v[162:163]
	v_pk_mul_f32 v[168:169], v[136:137], v[164:165]
	v_pk_mul_f32 v[162:163], v[176:177], v[222:223] op_sel_hi:[1,0]
	v_pk_mul_f32 v[164:165], v[174:175], v[222:223] op_sel_hi:[1,0]
	v_pk_mul_f32 v[174:175], v[224:225], v[222:223] op_sel_hi:[1,0]
	v_pk_mul_f32 v[176:177], v[206:207], v[222:223] op_sel_hi:[1,0]
	v_pk_mul_f32 v[164:165], v[140:141], v[164:165]
	v_pk_mul_f32 v[162:163], v[138:139], v[162:163]
	v_pk_mul_f32 v[176:177], v[144:145], v[176:177]
	v_pk_mul_f32 v[174:175], v[142:143], v[174:175]
	s_cbranch_vccnz .LBB0_644
	v_add_u32_e32 v206, 0x80, v216
	v_ashrrev_i32_e32 v206, 6, v206
	v_cvt_f32_i32_e32 v222, v206
	v_mul_f32_e32 v206, v220, v222
	v_mul_f32_e32 v207, v219, v222
	v_floor_f32_e32 v206, v206
	v_floor_f32_e32 v207, v207
	v_fma_f32 v224, v220, v222, -v206
	v_fma_f32 v225, v219, v222, -v207
	v_sin_f32_e32 v206, v224
	v_cos_f32_e32 v224, v224
	v_sin_f32_e32 v207, v225
	v_cos_f32_e32 v225, v225
	v_mul_f32_e32 v228, v218, v222
	v_floor_f32_e32 v228, v228
	v_fma_f32 v228, v218, v222, -v228
	v_cos_f32_e32 v231, v228
	v_sin_f32_e32 v233, v228
	v_pk_mul_f32 v[228:229], v[206:207], v[166:167]
	v_pk_mul_f32 v[166:167], v[224:225], v[166:167]
	v_mul_f32_e32 v234, v197, v222
	v_floor_f32_e32 v234, v234
	v_pk_fma_f32 v[224:225], v[224:225], v[170:171], v[228:229] neg_lo:[0,0,1] neg_hi:[0,0,1]
	v_pk_fma_f32 v[166:167], v[206:207], v[170:171], v[166:167]
	v_floor_f32_e32 v170, v201
	v_fma_f32 v222, v197, v222, -v234
	v_fma_f32 v171, v220, v199, -v170
	v_sin_f32_e32 v235, v222
	v_cos_f32_e32 v234, v222
	v_sin_f32_e32 v170, v171
	v_cos_f32_e32 v206, v171
	v_floor_f32_e32 v171, v239
	v_fma_f32 v201, v219, v199, -v171
	v_sin_f32_e32 v171, v201
	v_cos_f32_e32 v207, v201
	v_floor_f32_e32 v201, v221
	v_mul_f32_e32 v232, v233, v168
	v_mul_f32_e32 v250, v231, v168
	v_mov_b32_e32 v168, v173
	v_fma_f32 v201, v218, v199, -v201
	v_floor_f32_e32 v222, v240
	v_mul_f32_e32 v230, v231, v172
	v_mul_f32_e32 v236, v233, v172
	v_pk_mul_f32 v[172:173], v[234:235], v[168:169]
	v_cos_f32_e32 v221, v201
	v_sin_f32_e32 v201, v201
	v_fma_f32 v199, v197, v199, -v222
	v_mov_b32_e32 v231, v172
	v_mov_b32_e32 v233, v173
	v_mov_b32_e32 v172, v235
	v_mov_b32_e32 v173, v234
	v_sin_f32_e32 v235, v199
	v_cos_f32_e32 v234, v199
	v_pk_mul_f32 v[168:169], v[172:173], v[168:169]
	v_pk_add_f32 v[172:173], v[230:231], v[232:233] neg_lo:[0,1] neg_hi:[0,1]
	v_mov_b32_e32 v237, v168
	v_mov_b32_e32 v251, v169
	v_mul_f32_e32 v232, v201, v176
	v_mul_f32_e32 v238, v221, v176
	v_mov_b32_e32 v176, v165
	v_pk_add_f32 v[168:169], v[236:237], v[250:251]
	v_mul_f32_e32 v230, v221, v164
	v_mul_f32_e32 v236, v201, v164
	v_pk_mul_f32 v[164:165], v[234:235], v[176:177]
	v_pk_mul_f32 v[228:229], v[170:171], v[174:175]
	v_mov_b32_e32 v231, v164
	v_mov_b32_e32 v233, v165
	v_mov_b32_e32 v164, v235
	v_mov_b32_e32 v165, v234
	v_pk_mul_f32 v[164:165], v[164:165], v[176:177]
	v_pk_mul_f32 v[174:175], v[206:207], v[174:175]
	v_mov_b32_e32 v237, v164
	v_mov_b32_e32 v239, v165
	v_pk_fma_f32 v[206:207], v[206:207], v[162:163], v[228:229] neg_lo:[0,0,1] neg_hi:[0,0,1]
	v_pk_add_f32 v[164:165], v[230:231], v[232:233] neg_lo:[0,1] neg_hi:[0,1]
	v_pk_fma_f32 v[174:175], v[170:171], v[162:163], v[174:175]
	v_pk_add_f32 v[176:177], v[236:237], v[238:239]
	v_mov_b32_e32 v170, v224
	v_mov_b32_e32 v171, v225
	v_mov_b32_e32 v162, v206
	v_mov_b32_e32 v163, v207

.LBB0_646:
	v_cvt_pk_bf16_f32 v228, v170, v171
	v_cvt_pk_bf16_f32 v229, v172, v173
	v_add_co_u32_e32 v172, vcc, 0x8000, v202
	v_pk_fma_f32 v[204:205], v[36:37], v[200:201], v[148:149] op_sel_hi:[1,0,1]
	s_nop 0
	v_addc_co_u32_e32 v173, vcc, 0, v203, vcc
	v_mbcnt_lo_u32_b32 v0, -1, 0
	v_mbcnt_hi_u32_b32 v0, -1, v0
	v_bfe_u32 v0, v0, 4, 1
	v_mul_u32_u24_e32 v0, 24, v0
	v_lshl_add_u64 v[236:237], v[172:173], 0, v[0:1]
	v_cvt_pk_bf16_f32 v230, v166, v167
	v_cvt_pk_bf16_f32 v231, v168, v169
	s_nop 1
	v_permlane16_swap_b32_e32 v228, v230
	v_permlane16_swap_b32_e32 v229, v231
	global_store_dwordx4 v[236:237], v[228:231], off
	v_cvt_pk_bf16_f32 v232, v162, v163
	v_cvt_pk_bf16_f32 v233, v164, v165
	s_nop 0
	v_cvt_pk_bf16_f32 v234, v174, v175
	v_cvt_pk_bf16_f32 v235, v176, v177
	s_nop 1
	v_permlane16_swap_b32_e32 v232, v234
	v_permlane16_swap_b32_e32 v233, v235
	global_store_dwordx4 v[236:237], v[232:235], off offset:64
	v_pk_fma_f32 v[162:163], v[48:49], v[200:201], v[160:161] op_sel_hi:[1,0,1]
	v_pk_fma_f32 v[164:165], v[46:47], v[200:201], v[158:159] op_sel_hi:[1,0,1]
	v_mul_f32_e32 v171, v163, v163
	v_mul_f32_e32 v170, v165, v165
	v_pk_fma_f32 v[166:167], v[44:45], v[200:201], v[156:157] op_sel_hi:[1,0,1]
	v_pk_fma_f32 v[168:169], v[42:43], v[200:201], v[154:155] op_sel_hi:[1,0,1]
	v_fmac_f32_e32 v170, v164, v164
	v_fmac_f32_e32 v171, v162, v162
	v_add_f32_e32 v170, v170, v171
	v_mul_f32_e32 v171, v169, v169
	v_mul_f32_e32 v172, v167, v167
	v_fmac_f32_e32 v171, v168, v168
	v_fmac_f32_e32 v172, v166, v166
	v_pk_fma_f32 v[174:175], v[40:41], v[200:201], v[152:153] op_sel_hi:[1,0,1]
	v_pk_fma_f32 v[176:177], v[38:39], v[200:201], v[150:151] op_sel_hi:[1,0,1]
	v_add_f32_e32 v171, v171, v172
	v_add_f32_e32 v170, v170, v171
	v_mul_f32_e32 v171, v177, v177
	v_mul_f32_e32 v172, v175, v175
	v_fmac_f32_e32 v171, v176, v176
	v_fmac_f32_e32 v172, v174, v174
	v_pk_fma_f32 v[206:207], v[34:35], v[200:201], v[146:147] op_sel_hi:[1,0,1]
	v_add_f32_e32 v171, v171, v172
	v_add_f32_e32 v170, v171, v170
	v_mul_f32_e32 v171, v207, v207
	v_mul_f32_e32 v172, v205, v205
	v_fmac_f32_e32 v171, v206, v206
	v_fmac_f32_e32 v172, v204, v204
	v_add_f32_e32 v171, v171, v172
	v_add_f32_e32 v170, v171, v170
	v_mov_b32_e32 v171, v170
	s_nop 1
	v_permlane16_swap_b32_e32 v170, v171
	v_add_f32_e32 v170, v170, v171
	v_mov_b32_e32 v171, v170
	s_nop 1
	v_permlane32_swap_b32_e32 v170, v171
	v_add_f32_e32 v170, v170, v171
	v_fmamk_f32 v170, v170, 0x3c800000, v223
	v_rsq_f32_e32 v222, v170
	v_mov_b64_e32 v[202:203], v[194:195]
	v_mov_b64_e32 v[200:201], v[192:193]
	s_and_b64 vcc, exec, s[44:45]
	v_pk_mul_f32 v[164:165], v[164:165], v[222:223] op_sel_hi:[1,0]
	v_pk_mul_f32 v[162:163], v[162:163], v[222:223] op_sel_hi:[1,0]
	v_pk_mul_f32 v[170:171], v[130:131], v[164:165]
	v_pk_mul_f32 v[172:173], v[132:133], v[162:163]
	v_pk_mul_f32 v[162:163], v[168:169], v[222:223] op_sel_hi:[1,0]
	v_pk_mul_f32 v[164:165], v[166:167], v[222:223] op_sel_hi:[1,0]
	v_pk_mul_f32 v[166:167], v[134:135], v[162:163]
	v_pk_mul_f32 v[168:169], v[136:137], v[164:165]
	v_pk_mul_f32 v[162:163], v[176:177], v[222:223] op_sel_hi:[1,0]
	v_pk_mul_f32 v[164:165], v[174:175], v[222:223] op_sel_hi:[1,0]
	v_pk_mul_f32 v[174:175], v[206:207], v[222:223] op_sel_hi:[1,0]
	v_pk_mul_f32 v[176:177], v[204:205], v[222:223] op_sel_hi:[1,0]
	v_pk_mul_f32 v[164:165], v[140:141], v[164:165]
	v_pk_mul_f32 v[162:163], v[138:139], v[162:163]
	v_pk_mul_f32 v[176:177], v[144:145], v[176:177]
	v_pk_mul_f32 v[174:175], v[142:143], v[174:175]
	v_mov_b32_e32 v238, 0xd00000
	v_mov_b32_e32 v239, 0xd05000
	s_cbranch_vccnz .LBB0_648
	v_add_u32_e32 v199, 0x90, v216
	v_ashrrev_i32_e32 v199, 6, v199
	v_cvt_f32_i32_e32 v199, v199
	v_floor_f32_e32 v213, v213
	v_mul_f32_e32 v204, v220, v199
	v_mul_f32_e32 v205, v219, v199
	v_floor_f32_e32 v204, v204
	v_floor_f32_e32 v205, v205
	v_fma_f32 v206, v220, v199, -v204
	v_fma_f32 v207, v219, v199, -v205
	v_sin_f32_e32 v204, v206
	v_cos_f32_e32 v206, v206
	v_sin_f32_e32 v205, v207
	v_cos_f32_e32 v207, v207
	v_mul_f32_e32 v221, v218, v199
	v_floor_f32_e32 v221, v221
	v_pk_mul_f32 v[224:225], v[204:205], v[166:167]
	v_pk_mul_f32 v[166:167], v[206:207], v[166:167]
	v_mul_f32_e32 v229, v197, v199
	v_fma_f32 v221, v218, v199, -v221
	v_floor_f32_e32 v229, v229
	v_pk_fma_f32 v[206:207], v[206:207], v[170:171], v[224:225] neg_lo:[0,0,1] neg_hi:[0,0,1]
	v_pk_fma_f32 v[166:167], v[204:205], v[170:171], v[166:167]
	v_floor_f32_e32 v170, v245
	v_cos_f32_e32 v222, v221
	v_sin_f32_e32 v221, v221
	v_fma_f32 v199, v197, v199, -v229
	v_fma_f32 v171, v220, v212, -v170
	v_sin_f32_e32 v233, v199
	v_cos_f32_e32 v232, v199
	v_sin_f32_e32 v170, v171
	v_cos_f32_e32 v204, v171
	v_floor_f32_e32 v171, v243
	v_fma_f32 v199, v219, v212, -v171
	v_sin_f32_e32 v171, v199
	v_cos_f32_e32 v205, v199
	v_floor_f32_e32 v199, v241
	v_mul_f32_e32 v230, v221, v168
	v_mul_f32_e32 v236, v222, v168
	v_mov_b32_e32 v168, v173
	v_fma_f32 v199, v218, v212, -v199
	v_mul_f32_e32 v228, v222, v172
	v_mul_f32_e32 v234, v221, v172
	v_pk_mul_f32 v[172:173], v[232:233], v[168:169]
	v_cos_f32_e32 v221, v199
	v_sin_f32_e32 v199, v199
	v_fma_f32 v212, v197, v212, -v213
	v_mov_b32_e32 v229, v172
	v_mov_b32_e32 v231, v173
	v_mov_b32_e32 v172, v233
	v_mov_b32_e32 v173, v232
	v_sin_f32_e32 v213, v212
	v_cos_f32_e32 v212, v212
	v_pk_mul_f32 v[168:169], v[172:173], v[168:169]
	v_pk_add_f32 v[172:173], v[228:229], v[230:231] neg_lo:[0,1] neg_hi:[0,1]
	v_mov_b32_e32 v235, v168
	v_mov_b32_e32 v237, v169
	v_pk_add_f32 v[168:169], v[234:235], v[236:237]
	v_mul_f32_e32 v230, v199, v176
	v_mul_f32_e32 v234, v221, v176
	v_mov_b32_e32 v176, v165
	v_mul_f32_e32 v228, v221, v164
	v_mul_f32_e32 v232, v199, v164
	v_pk_mul_f32 v[164:165], v[212:213], v[176:177]
	v_pk_mul_f32 v[224:225], v[170:171], v[174:175]
	v_mov_b32_e32 v229, v164
	v_mov_b32_e32 v231, v165
	v_mov_b32_e32 v164, v213
	v_mov_b32_e32 v165, v212
	v_pk_mul_f32 v[164:165], v[164:165], v[176:177]
	v_pk_mul_f32 v[174:175], v[204:205], v[174:175]
	v_mov_b32_e32 v233, v164
	v_mov_b32_e32 v235, v165
	v_pk_fma_f32 v[204:205], v[204:205], v[162:163], v[224:225] neg_lo:[0,0,1] neg_hi:[0,0,1]
	v_pk_add_f32 v[164:165], v[228:229], v[230:231] neg_lo:[0,1] neg_hi:[0,1]
	v_pk_fma_f32 v[174:175], v[170:171], v[162:163], v[174:175]
	v_pk_add_f32 v[176:177], v[232:233], v[234:235]
	v_mov_b32_e32 v170, v206
	v_mov_b32_e32 v171, v207
	v_mov_b32_e32 v162, v204
	v_mov_b32_e32 v163, v205

.LBB0_650:
	v_cvt_pk_bf16_f32 v228, v170, v171
	v_cvt_pk_bf16_f32 v229, v172, v173
	v_add_co_u32_e32 v172, vcc, 0x9000, v200
	s_nop 1
	v_addc_co_u32_e32 v173, vcc, 0, v201, vcc
	v_mbcnt_lo_u32_b32 v0, -1, 0
	v_mbcnt_hi_u32_b32 v0, -1, v0
	v_bfe_u32 v0, v0, 4, 1
	v_mul_u32_u24_e32 v0, 24, v0
	v_lshl_add_u64 v[236:237], v[172:173], 0, v[0:1]
	v_cvt_pk_bf16_f32 v230, v166, v167
	v_cvt_pk_bf16_f32 v231, v168, v169
	s_nop 1
	v_permlane16_swap_b32_e32 v228, v230
	v_permlane16_swap_b32_e32 v229, v231
	global_store_dwordx4 v[236:237], v[228:231], off
	v_cvt_pk_bf16_f32 v232, v162, v163
	v_cvt_pk_bf16_f32 v233, v164, v165
	s_nop 0
	v_cvt_pk_bf16_f32 v234, v174, v175
	v_cvt_pk_bf16_f32 v235, v176, v177
	s_nop 1
	v_permlane16_swap_b32_e32 v232, v234
	v_permlane16_swap_b32_e32 v233, v235
	global_store_dwordx4 v[236:237], v[232:235], off offset:64
	v_pk_fma_f32 v[162:163], v[32:33], v[198:199], v[160:161] op_sel_hi:[1,0,1]
	v_pk_fma_f32 v[164:165], v[30:31], v[198:199], v[158:159] op_sel_hi:[1,0,1]
	v_mul_f32_e32 v171, v163, v163
	v_mul_f32_e32 v170, v165, v165
	v_pk_fma_f32 v[166:167], v[28:29], v[198:199], v[156:157] op_sel_hi:[1,0,1]
	v_pk_fma_f32 v[168:169], v[26:27], v[198:199], v[154:155] op_sel_hi:[1,0,1]
	v_fmac_f32_e32 v170, v164, v164
	v_fmac_f32_e32 v171, v162, v162
	v_add_f32_e32 v170, v170, v171
	v_mul_f32_e32 v171, v169, v169
	v_mul_f32_e32 v172, v167, v167
	v_fmac_f32_e32 v171, v168, v168
	v_fmac_f32_e32 v172, v166, v166
	v_pk_fma_f32 v[202:203], v[24:25], v[198:199], v[152:153] op_sel_hi:[1,0,1]
	v_pk_fma_f32 v[204:205], v[22:23], v[198:199], v[150:151] op_sel_hi:[1,0,1]
	v_add_f32_e32 v171, v171, v172
	v_add_f32_e32 v170, v170, v171
	v_mul_f32_e32 v171, v205, v205
	v_mul_f32_e32 v172, v203, v203
	v_fmac_f32_e32 v171, v204, v204
	v_fmac_f32_e32 v172, v202, v202
	v_pk_fma_f32 v[206:207], v[20:21], v[198:199], v[148:149] op_sel_hi:[1,0,1]
	v_pk_fma_f32 v[212:213], v[18:19], v[198:199], v[146:147] op_sel_hi:[1,0,1]
	v_add_f32_e32 v171, v171, v172
	v_add_f32_e32 v170, v171, v170
	v_mul_f32_e32 v171, v213, v213
	v_mul_f32_e32 v172, v207, v207
	v_fmac_f32_e32 v171, v212, v212
	v_fmac_f32_e32 v172, v206, v206
	v_add_f32_e32 v171, v171, v172
	v_add_f32_e32 v170, v171, v170
	v_mov_b32_e32 v171, v170
	s_nop 1
	v_permlane16_swap_b32_e32 v170, v171
	v_add_f32_e32 v170, v170, v171
	v_mov_b32_e32 v171, v170
	s_nop 1
	v_permlane32_swap_b32_e32 v170, v171
	v_add_f32_e32 v170, v170, v171
	v_fmamk_f32 v170, v170, 0x3c800000, v223
	v_rsq_f32_e32 v222, v170
	v_mov_b64_e32 v[200:201], v[194:195]
	v_mov_b64_e32 v[198:199], v[192:193]
	s_and_b64 vcc, exec, s[44:45]
	v_pk_mul_f32 v[164:165], v[164:165], v[222:223] op_sel_hi:[1,0]
	v_pk_mul_f32 v[162:163], v[162:163], v[222:223] op_sel_hi:[1,0]
	v_pk_mul_f32 v[174:175], v[130:131], v[164:165]
	v_pk_mul_f32 v[176:177], v[132:133], v[162:163]
	v_pk_mul_f32 v[162:163], v[168:169], v[222:223] op_sel_hi:[1,0]
	v_pk_mul_f32 v[164:165], v[166:167], v[222:223] op_sel_hi:[1,0]
	v_pk_mul_f32 v[170:171], v[134:135], v[162:163]
	v_pk_mul_f32 v[172:173], v[136:137], v[164:165]
	v_pk_mul_f32 v[162:163], v[204:205], v[222:223] op_sel_hi:[1,0]
	v_pk_mul_f32 v[164:165], v[202:203], v[222:223] op_sel_hi:[1,0]
	v_pk_mul_f32 v[166:167], v[138:139], v[162:163]
	v_pk_mul_f32 v[168:169], v[140:141], v[164:165]
	v_pk_mul_f32 v[162:163], v[212:213], v[222:223] op_sel_hi:[1,0]
	v_pk_mul_f32 v[164:165], v[206:207], v[222:223] op_sel_hi:[1,0]
	v_pk_mul_f32 v[162:163], v[142:143], v[162:163]
	v_pk_mul_f32 v[164:165], v[144:145], v[164:165]
	s_cbranch_vccnz .LBB0_652
	v_add_u32_e32 v202, 0xa0, v216
	v_ashrrev_i32_e32 v202, 6, v202
	v_cvt_f32_i32_e32 v213, v202
	v_floor_f32_e32 v211, v211
	v_mul_f32_e32 v202, v220, v213
	v_mul_f32_e32 v203, v219, v213
	v_floor_f32_e32 v202, v202
	v_floor_f32_e32 v203, v203
	v_mul_f32_e32 v206, v218, v213
	v_fma_f32 v204, v220, v213, -v202
	v_fma_f32 v205, v219, v213, -v203
	v_floor_f32_e32 v206, v206
	v_mul_f32_e32 v225, v197, v213
	v_sin_f32_e32 v202, v204
	v_cos_f32_e32 v204, v204
	v_sin_f32_e32 v203, v205
	v_cos_f32_e32 v205, v205
	v_fma_f32 v206, v218, v213, -v206
	v_floor_f32_e32 v225, v225
	v_cos_f32_e32 v221, v206
	v_sin_f32_e32 v222, v206
	v_fma_f32 v213, v197, v213, -v225
	v_sin_f32_e32 v229, v213
	v_cos_f32_e32 v228, v213
	v_pk_mul_f32 v[206:207], v[202:203], v[170:171]
	v_pk_mul_f32 v[170:171], v[204:205], v[170:171]
	v_mul_f32_e32 v224, v222, v172
	v_mul_f32_e32 v232, v221, v172
	v_mov_b32_e32 v172, v177
	v_pk_fma_f32 v[204:205], v[204:205], v[174:175], v[206:207] neg_lo:[0,0,1] neg_hi:[0,0,1]
	v_pk_fma_f32 v[170:171], v[202:203], v[174:175], v[170:171]
	v_floor_f32_e32 v174, v247
	v_mul_f32_e32 v212, v221, v176
	v_mul_f32_e32 v230, v222, v176
	v_pk_mul_f32 v[176:177], v[228:229], v[172:173]
	v_fma_f32 v175, v220, v210, -v174
	v_floor_f32_e32 v206, v242
	v_mov_b32_e32 v213, v176
	v_mov_b32_e32 v225, v177
	v_mov_b32_e32 v176, v229
	v_mov_b32_e32 v177, v228
	v_sin_f32_e32 v174, v175
	v_cos_f32_e32 v202, v175
	v_floor_f32_e32 v175, v246
	v_fma_f32 v206, v218, v210, -v206
	v_pk_mul_f32 v[172:173], v[176:177], v[172:173]
	v_pk_add_f32 v[176:177], v[212:213], v[224:225] neg_lo:[0,1] neg_hi:[0,1]
	v_fma_f32 v203, v219, v210, -v175
	v_cos_f32_e32 v213, v206
	v_sin_f32_e32 v221, v206
	v_fma_f32 v210, v197, v210, -v211
	v_sin_f32_e32 v211, v210
	v_cos_f32_e32 v210, v210
	v_mov_b32_e32 v231, v172
	v_mov_b32_e32 v233, v173
	v_sin_f32_e32 v175, v203
	v_pk_add_f32 v[172:173], v[230:231], v[232:233]
	v_cos_f32_e32 v203, v203
	v_mul_f32_e32 v224, v221, v164
	v_mul_f32_e32 v230, v213, v164
	v_mov_b32_e32 v164, v169
	v_mul_f32_e32 v212, v213, v168
	v_mul_f32_e32 v228, v221, v168
	v_pk_mul_f32 v[168:169], v[210:211], v[164:165]
	v_pk_mul_f32 v[206:207], v[174:175], v[162:163]
	v_mov_b32_e32 v213, v168
	v_mov_b32_e32 v225, v169
	v_mov_b32_e32 v168, v211
	v_mov_b32_e32 v169, v210
	v_pk_mul_f32 v[164:165], v[168:169], v[164:165]
	v_pk_mul_f32 v[162:163], v[202:203], v[162:163]
	v_mov_b32_e32 v229, v164
	v_mov_b32_e32 v231, v165
	v_pk_fma_f32 v[202:203], v[202:203], v[166:167], v[206:207] neg_lo:[0,0,1] neg_hi:[0,0,1]
	v_pk_add_f32 v[168:169], v[212:213], v[224:225] neg_lo:[0,1] neg_hi:[0,1]
	v_pk_fma_f32 v[162:163], v[174:175], v[166:167], v[162:163]
	v_pk_add_f32 v[164:165], v[228:229], v[230:231]
	v_mov_b32_e32 v174, v204
	v_mov_b32_e32 v175, v205
	v_mov_b32_e32 v166, v202
	v_mov_b32_e32 v167, v203

.LBB0_654:
	v_cvt_pk_bf16_f32 v228, v174, v175
	v_cvt_pk_bf16_f32 v229, v176, v177
	v_add_co_u32_e32 v176, vcc, 0xa000, v198
	v_pk_fma_f32 v[160:161], v[16:17], v[196:197], v[160:161] op_sel_hi:[1,0,1]
	s_nop 0
	v_addc_co_u32_e32 v177, vcc, 0, v199, vcc
	v_pk_fma_f32 v[158:159], v[14:15], v[196:197], v[158:159] op_sel_hi:[1,0,1]
	v_mbcnt_lo_u32_b32 v0, -1, 0
	v_mbcnt_hi_u32_b32 v0, -1, v0
	v_bfe_u32 v0, v0, 4, 1
	v_mul_u32_u24_e32 v0, 24, v0
	v_lshl_add_u64 v[236:237], v[176:177], 0, v[0:1]
	v_cvt_pk_bf16_f32 v230, v170, v171
	v_cvt_pk_bf16_f32 v231, v172, v173
	s_nop 1
	v_permlane16_swap_b32_e32 v228, v230
	v_permlane16_swap_b32_e32 v229, v231
	global_store_dwordx4 v[236:237], v[228:231], off
	v_cvt_pk_bf16_f32 v232, v166, v167
	v_cvt_pk_bf16_f32 v233, v168, v169
	v_pk_fma_f32 v[168:169], v[2:3], v[196:197], v[146:147] op_sel_hi:[1,0,1]
	v_mul_f32_e32 v146, v159, v159
	v_mul_f32_e32 v147, v161, v161
	v_pk_fma_f32 v[156:157], v[12:13], v[196:197], v[156:157] op_sel_hi:[1,0,1]
	v_pk_fma_f32 v[154:155], v[10:11], v[196:197], v[154:155] op_sel_hi:[1,0,1]
	v_fmac_f32_e32 v146, v158, v158
	v_fmac_f32_e32 v147, v160, v160
	s_nop 0
	v_pk_fma_f32 v[166:167], v[4:5], v[196:197], v[148:149] op_sel_hi:[1,0,1]
	v_add_f32_e32 v146, v146, v147
	v_mul_f32_e32 v147, v155, v155
	v_mul_f32_e32 v148, v157, v157
	v_fmac_f32_e32 v147, v154, v154
	v_fmac_f32_e32 v148, v156, v156
	v_pk_fma_f32 v[152:153], v[8:9], v[196:197], v[152:153] op_sel_hi:[1,0,1]
	v_pk_fma_f32 v[150:151], v[6:7], v[196:197], v[150:151] op_sel_hi:[1,0,1]
	v_add_f32_e32 v147, v147, v148
	v_add_f32_e32 v146, v146, v147
	v_mul_f32_e32 v147, v151, v151
	v_mul_f32_e32 v148, v153, v153
	v_fmac_f32_e32 v147, v150, v150
	v_fmac_f32_e32 v148, v152, v152
	v_add_f32_e32 v147, v147, v148
	v_add_f32_e32 v146, v147, v146
	v_mul_f32_e32 v147, v169, v169
	v_mul_f32_e32 v148, v167, v167
	v_fmac_f32_e32 v147, v168, v168
	v_fmac_f32_e32 v148, v166, v166
	v_add_f32_e32 v147, v147, v148
	v_add_f32_e32 v146, v147, v146
	v_mov_b32_e32 v147, v146
	s_nop 1
	v_permlane16_swap_b32_e32 v146, v147
	v_add_f32_e32 v146, v146, v147
	v_mov_b32_e32 v147, v146
	s_nop 1
	v_permlane32_swap_b32_e32 v146, v147
	v_add_f32_e32 v146, v146, v147
	v_fmamk_f32 v146, v146, 0x3c800000, v223
	v_rsq_f32_e32 v170, v146
	s_and_b64 vcc, exec, s[44:45]
	v_mov_b32_e32 v226, 0x260
	v_cvt_pk_bf16_f32 v234, v162, v163
	v_pk_mul_f32 v[146:147], v[158:159], v[170:171] op_sel_hi:[1,0]
	v_pk_mul_f32 v[148:149], v[160:161], v[170:171] op_sel_hi:[1,0]
	v_pk_mul_f32 v[146:147], v[130:131], v[146:147]
	v_pk_mul_f32 v[148:149], v[132:133], v[148:149]
	v_pk_mul_f32 v[130:131], v[154:155], v[170:171] op_sel_hi:[1,0]
	v_pk_mul_f32 v[132:133], v[156:157], v[170:171] op_sel_hi:[1,0]
	v_pk_mul_f32 v[134:135], v[134:135], v[130:131]
	v_pk_mul_f32 v[136:137], v[136:137], v[132:133]
	v_pk_mul_f32 v[130:131], v[150:151], v[170:171] op_sel_hi:[1,0]
	v_pk_mul_f32 v[132:133], v[152:153], v[170:171] op_sel_hi:[1,0]
	v_pk_mul_f32 v[130:131], v[138:139], v[130:131]
	v_pk_mul_f32 v[132:133], v[140:141], v[132:133]
	v_pk_mul_f32 v[138:139], v[168:169], v[170:171] op_sel_hi:[1,0]
	v_pk_mul_f32 v[140:141], v[166:167], v[170:171] op_sel_hi:[1,0]
	v_pk_mul_f32 v[138:139], v[142:143], v[138:139]
	v_pk_mul_f32 v[140:141], v[144:145], v[140:141]
	v_cvt_pk_bf16_f32 v235, v164, v165
	s_nop 1
	v_permlane16_swap_b32_e32 v232, v234
	v_permlane16_swap_b32_e32 v233, v235
	global_store_dwordx4 v[236:237], v[232:235], off offset:64
	s_cbranch_vccnz .LBB0_656
	v_add_u32_e32 v142, 0xb0, v216
	v_ashrrev_i32_e32 v142, 6, v142
	v_cvt_f32_i32_e32 v153, v142
	v_mul_f32_e32 v142, v220, v153
	v_mul_f32_e32 v143, v219, v153
	v_mul_f32_e32 v150, v218, v153
	v_floor_f32_e32 v142, v142
	v_floor_f32_e32 v143, v143
	v_floor_f32_e32 v150, v150
	v_mul_f32_e32 v156, v197, v153
	v_fma_f32 v144, v220, v153, -v142
	v_fma_f32 v145, v219, v153, -v143
	v_fma_f32 v150, v218, v153, -v150
	v_floor_f32_e32 v156, v156
	v_sin_f32_e32 v142, v144
	v_sin_f32_e32 v143, v145
	v_cos_f32_e32 v155, v150
	v_sin_f32_e32 v158, v150
	v_fma_f32 v153, v197, v153, -v156
	v_cos_f32_e32 v144, v144
	v_cos_f32_e32 v145, v145
	v_sin_f32_e32 v157, v153
	v_cos_f32_e32 v156, v153
	v_pk_mul_f32 v[150:151], v[142:143], v[134:135]
	v_mul_f32_e32 v154, v158, v136
	v_mul_f32_e32 v160, v155, v136
	v_mov_b32_e32 v136, v149
	v_pk_mul_f32 v[134:135], v[144:145], v[134:135]
	v_mul_f32_e32 v152, v155, v148
	v_mul_f32_e32 v158, v158, v148
	v_pk_mul_f32 v[148:149], v[156:157], v[136:137]
	v_pk_fma_f32 v[144:145], v[144:145], v[146:147], v[150:151] neg_lo:[0,0,1] neg_hi:[0,0,1]
	v_floor_f32_e32 v150, v244
	v_mov_b32_e32 v153, v148
	v_mov_b32_e32 v155, v149
	v_mov_b32_e32 v148, v157
	v_mov_b32_e32 v149, v156
	v_pk_fma_f32 v[134:135], v[142:143], v[146:147], v[134:135]
	v_floor_f32_e32 v142, v249
	v_fma_f32 v150, v218, v208, -v150
	v_floor_f32_e32 v156, v209
	v_pk_mul_f32 v[136:137], v[148:149], v[136:137]
	v_pk_add_f32 v[148:149], v[152:153], v[154:155] neg_lo:[0,1] neg_hi:[0,1]
	v_fma_f32 v143, v220, v208, -v142
	v_cos_f32_e32 v153, v150
	v_sin_f32_e32 v155, v150
	v_fma_f32 v156, v197, v208, -v156
	v_sin_f32_e32 v142, v143
	v_cos_f32_e32 v146, v143
	v_floor_f32_e32 v143, v248
	v_sin_f32_e32 v157, v156
	v_cos_f32_e32 v156, v156
	v_fma_f32 v147, v219, v208, -v143
	v_mov_b32_e32 v159, v136
	v_mov_b32_e32 v161, v137
	v_sin_f32_e32 v143, v147
	v_pk_add_f32 v[136:137], v[158:159], v[160:161]
	v_cos_f32_e32 v147, v147
	v_mul_f32_e32 v154, v155, v140
	v_mul_f32_e32 v160, v153, v140
	v_mov_b32_e32 v140, v133
	v_mul_f32_e32 v152, v153, v132
	v_mul_f32_e32 v158, v155, v132
	v_pk_mul_f32 v[132:133], v[156:157], v[140:141]
	v_pk_mul_f32 v[150:151], v[142:143], v[138:139]
	v_mov_b32_e32 v153, v132
	v_mov_b32_e32 v155, v133
	v_mov_b32_e32 v132, v157
	v_mov_b32_e32 v133, v156
	v_pk_mul_f32 v[132:133], v[132:133], v[140:141]
	v_pk_mul_f32 v[138:139], v[146:147], v[138:139]
	v_mov_b32_e32 v159, v132
	v_mov_b32_e32 v161, v133
	v_pk_fma_f32 v[150:151], v[146:147], v[130:131], v[150:151] neg_lo:[0,0,1] neg_hi:[0,0,1]
	v_pk_add_f32 v[132:133], v[152:153], v[154:155] neg_lo:[0,1] neg_hi:[0,1]
	v_pk_fma_f32 v[138:139], v[142:143], v[130:131], v[138:139]
	v_pk_add_f32 v[140:141], v[158:159], v[160:161]
	v_mov_b32_e32 v146, v144
	v_mov_b32_e32 v147, v145
	v_mov_b32_e32 v130, v150
	v_mov_b32_e32 v131, v151

.LBB0_658:
	v_add_co_u32_e32 v144, vcc, 0xb000, v192
	v_cvt_pk_bf16_f32 v228, v146, v147
	v_cvt_pk_bf16_f32 v229, v148, v149
	s_nop 1
	v_addc_co_u32_e32 v145, vcc, 0, v193, vcc
	v_mbcnt_lo_u32_b32 v0, -1, 0
	v_mbcnt_hi_u32_b32 v0, -1, v0
	v_bfe_u32 v0, v0, 4, 1
	v_mul_u32_u24_e32 v0, 24, v0
	v_lshl_add_u64 v[236:237], v[144:145], 0, v[0:1]
	v_cvt_pk_bf16_f32 v230, v134, v135
	v_cvt_pk_bf16_f32 v231, v136, v137
	s_nop 1
	v_permlane16_swap_b32_e32 v228, v230
	v_permlane16_swap_b32_e32 v229, v231
	global_store_dwordx4 v[236:237], v[228:231], off
	v_cvt_pk_bf16_f32 v232, v130, v131
	v_cvt_pk_bf16_f32 v233, v132, v133
	s_nop 0
	v_cvt_pk_bf16_f32 v234, v138, v139
	v_cvt_pk_bf16_f32 v235, v140, v141
	s_nop 1
	v_permlane16_swap_b32_e32 v232, v234
	v_permlane16_swap_b32_e32 v233, v235
	global_store_dwordx4 v[236:237], v[232:235], off offset:64

.LBB0_662:
	v_pk_mul_f32 v[120:121], v[120:121], s[12:13] op_sel_hi:[1,0]
	v_pk_mul_f32 v[128:129], v[128:129], s[12:13] op_sel_hi:[1,0]
	v_pk_mul_f32 v[116:117], v[116:117], s[12:13] op_sel_hi:[1,0]
	v_pk_mul_f32 v[126:127], v[126:127], s[12:13] op_sel_hi:[1,0]
	v_cvt_pk_bf16_f32 v240, v128, v129
	v_cvt_pk_bf16_f32 v241, v120, v121
	v_mbcnt_lo_u32_b32 v252, -1, 0
	v_mbcnt_hi_u32_b32 v252, -1, v252
	v_bfe_u32 v252, v252, 4, 1
	v_mul_u32_u24_e32 v252, 24, v252
	v_mov_b32_e32 v253, 0
	v_lshl_add_u64 v[248:249], v[186:187], 0, v[252:253]
	v_cvt_pk_bf16_f32 v242, v126, v127
	v_cvt_pk_bf16_f32 v243, v116, v117
	v_pk_fma_f32 v[112:113], v[112:113], v[176:177], v[160:161] op_sel_hi:[1,0,1]
	v_pk_fma_f32 v[110:111], v[110:111], v[176:177], v[158:159] op_sel_hi:[1,0,1]
	s_nop 1
	v_permlane16_swap_b32_e32 v240, v242
	v_permlane16_swap_b32_e32 v241, v243
	global_store_dwordx4 v[248:249], v[240:243], off
	v_pk_fma_f32 v[120:121], v[98:99], v[176:177], v[146:147] op_sel_hi:[1,0,1]
	v_mul_f32_e32 v98, v111, v111
	v_mul_f32_e32 v99, v113, v113
	v_pk_mul_f32 v[118:119], v[118:119], s[12:13] op_sel_hi:[1,0]
	v_pk_fma_f32 v[108:109], v[108:109], v[176:177], v[156:157] op_sel_hi:[1,0,1]
	v_pk_fma_f32 v[106:107], v[106:107], v[176:177], v[154:155] op_sel_hi:[1,0,1]
	v_fmac_f32_e32 v98, v110, v110
	v_fmac_f32_e32 v99, v112, v112
	v_pk_mul_f32 v[122:123], v[122:123], s[12:13] op_sel_hi:[1,0]
	v_add_f32_e32 v98, v98, v99
	v_cvt_pk_bf16_f32 v244, v122, v123
	v_cvt_pk_bf16_f32 v245, v118, v119
	v_pk_fma_f32 v[118:119], v[100:101], v[176:177], v[148:149] op_sel_hi:[1,0,1]
	v_mul_f32_e32 v99, v107, v107
	v_mul_f32_e32 v100, v109, v109
	v_pk_mul_f32 v[114:115], v[114:115], s[12:13] op_sel_hi:[1,0]
	v_pk_mul_f32 v[124:125], v[124:125], s[12:13] op_sel_hi:[1,0]
	s_nop 0
	v_cvt_pk_bf16_f32 v246, v124, v125
	v_cvt_pk_bf16_f32 v247, v114, v115
	v_fmac_f32_e32 v99, v106, v106
	v_fmac_f32_e32 v100, v108, v108
	s_nop 1
	v_permlane16_swap_b32_e32 v244, v246
	v_permlane16_swap_b32_e32 v245, v247
	global_store_dwordx4 v[248:249], v[244:247], off offset:64
	v_pk_fma_f32 v[116:117], v[104:105], v[176:177], v[152:153] op_sel_hi:[1,0,1]
	v_pk_fma_f32 v[102:103], v[102:103], v[176:177], v[150:151] op_sel_hi:[1,0,1]
	v_add_f32_e32 v99, v99, v100
	v_add_f32_e32 v98, v98, v99
	v_mul_f32_e32 v99, v103, v103
	v_mul_f32_e32 v100, v117, v117
	v_fmac_f32_e32 v99, v102, v102
	v_fmac_f32_e32 v100, v116, v116
	v_add_f32_e32 v99, v99, v100
	v_add_f32_e32 v98, v98, v99
	v_mul_f32_e32 v99, v121, v121
	v_mul_f32_e32 v100, v119, v119
	v_fmac_f32_e32 v99, v120, v120
	v_fmac_f32_e32 v100, v118, v118
	v_add_f32_e32 v99, v99, v100
	v_add_f32_e32 v98, v98, v99
	v_mov_b32_e32 v99, v98
	s_nop 1
	v_permlane16_swap_b32_e32 v98, v99
	v_add_f32_e32 v98, v98, v99
	v_mov_b32_e32 v99, v98
	s_nop 1
	v_permlane32_swap_b32_e32 v98, v99
	v_add_f32_e32 v98, v98, v99
	v_fmamk_f32 v98, v98, 0x3c800000, v223
	v_rsq_f32_e32 v122, v98
	v_mov_b64_e32 v[100:101], 0
	v_mov_b64_e32 v[98:99], v[162:163]
	v_add_u32_e32 v190, 16, v216
	v_and_b32_e32 v191, 63, v190
	v_pk_mul_f32 v[100:101], v[110:111], v[122:123] op_sel_hi:[1,0]
	v_pk_mul_f32 v[106:107], v[106:107], v[122:123] op_sel_hi:[1,0]
	v_pk_mul_f32 v[102:103], v[102:103], v[122:123] op_sel_hi:[1,0]
	v_pk_mul_f32 v[104:105], v[112:113], v[122:123] op_sel_hi:[1,0]
	v_pk_mul_f32 v[114:115], v[142:143], v[100:101]
	v_pk_mul_f32 v[100:101], v[108:109], v[122:123] op_sel_hi:[1,0]
	v_pk_mul_f32 v[110:111], v[138:139], v[106:107]
	v_pk_mul_f32 v[106:107], v[116:117], v[122:123] op_sel_hi:[1,0]
	v_pk_mul_f32 v[108:109], v[134:135], v[102:103]
	v_pk_mul_f32 v[112:113], v[120:121], v[122:123] op_sel_hi:[1,0]
	v_pk_mul_f32 v[102:103], v[118:119], v[122:123] op_sel_hi:[1,0]
	v_cvt_f32_ubyte0_e32 v116, v191
	v_pk_mul_f32 v[104:105], v[144:145], v[104:105]
	v_pk_mul_f32 v[100:101], v[140:141], v[100:101]
	v_pk_mul_f32 v[106:107], v[136:137], v[106:107]
	v_pk_mul_f32 v[102:103], v[132:133], v[102:103]
	v_pk_mul_f32 v[112:113], v[130:131], v[112:113]
	s_and_b64 vcc, exec, s[42:43]
	v_mul_f32_e32 v120, v0, v116
	v_mul_f32_e32 v119, v165, v116
	v_mul_f32_e32 v118, v167, v116
	v_mul_f32_e32 v117, v169, v116
	s_cbranch_vccnz .LBB0_664
	v_ashrrev_i32_e32 v121, 6, v190
	v_cvt_f32_i32_e32 v121, v121
	v_mul_f32_e32 v122, v0, v121
	v_mul_f32_e32 v123, v165, v121
	v_floor_f32_e32 v122, v122
	v_floor_f32_e32 v123, v123
	v_fma_f32 v124, v0, v121, -v122
	v_fma_f32 v125, v165, v121, -v123
	v_sin_f32_e32 v122, v124
	v_cos_f32_e32 v124, v124
	v_sin_f32_e32 v123, v125
	v_cos_f32_e32 v125, v125
	v_mul_f32_e32 v126, v167, v121
	v_floor_f32_e32 v126, v126
	v_mul_f32_e32 v187, v169, v121
	v_fma_f32 v126, v167, v121, -v126
	v_floor_f32_e32 v187, v187
	v_cos_f32_e32 v129, v126
	v_sin_f32_e32 v176, v126
	v_pk_mul_f32 v[126:127], v[122:123], v[110:111]
	v_pk_mul_f32 v[110:111], v[124:125], v[110:111]
	v_fma_f32 v121, v169, v121, -v187
	v_sin_f32_e32 v191, v121
	v_cos_f32_e32 v190, v121
	v_pk_fma_f32 v[124:125], v[124:125], v[114:115], v[126:127] neg_lo:[0,0,1] neg_hi:[0,0,1]
	v_pk_fma_f32 v[110:111], v[122:123], v[114:115], v[110:111]
	v_floor_f32_e32 v114, v120
	v_fma_f32 v115, v0, v116, -v114
	v_sin_f32_e32 v114, v115
	v_cos_f32_e32 v122, v115
	v_floor_f32_e32 v115, v119
	v_mul_f32_e32 v186, v176, v100
	v_mul_f32_e32 v194, v129, v100
	v_mov_b32_e32 v100, v105
	v_fma_f32 v121, v165, v116, -v115
	v_mul_f32_e32 v128, v129, v104
	v_mul_f32_e32 v192, v176, v104
	v_pk_mul_f32 v[104:105], v[190:191], v[100:101]
	v_sin_f32_e32 v115, v121
	v_cos_f32_e32 v123, v121
	v_floor_f32_e32 v121, v118
	v_mov_b32_e32 v129, v104
	v_mov_b32_e32 v187, v105
	v_mov_b32_e32 v104, v191
	v_mov_b32_e32 v105, v190
	v_fma_f32 v121, v167, v116, -v121
	v_floor_f32_e32 v176, v117
	v_pk_mul_f32 v[100:101], v[104:105], v[100:101]
	v_pk_add_f32 v[104:105], v[128:129], v[186:187] neg_lo:[0,1] neg_hi:[0,1]
	v_cos_f32_e32 v129, v121
	v_sin_f32_e32 v121, v121
	v_fma_f32 v176, v169, v116, -v176
	v_sin_f32_e32 v191, v176
	v_cos_f32_e32 v190, v176
	v_mov_b32_e32 v193, v100
	v_mov_b32_e32 v195, v101
	v_pk_add_f32 v[100:101], v[192:193], v[194:195]
	v_mul_f32_e32 v186, v121, v102
	v_mul_f32_e32 v194, v129, v102
	v_mov_b32_e32 v102, v107
	v_mul_f32_e32 v128, v129, v106
	v_mul_f32_e32 v192, v121, v106
	v_pk_mul_f32 v[106:107], v[190:191], v[102:103]
	v_pk_mul_f32 v[126:127], v[114:115], v[112:113]
	v_mov_b32_e32 v129, v106
	v_mov_b32_e32 v187, v107
	v_mov_b32_e32 v106, v191
	v_mov_b32_e32 v107, v190
	v_pk_mul_f32 v[102:103], v[106:107], v[102:103]
	v_pk_mul_f32 v[112:113], v[122:123], v[112:113]
	v_mov_b32_e32 v193, v102
	v_mov_b32_e32 v195, v103
	v_pk_fma_f32 v[122:123], v[122:123], v[108:109], v[126:127] neg_lo:[0,0,1] neg_hi:[0,0,1]
	v_pk_add_f32 v[106:107], v[128:129], v[186:187] neg_lo:[0,1] neg_hi:[0,1]
	v_pk_fma_f32 v[112:113], v[114:115], v[108:109], v[112:113]
	v_pk_add_f32 v[102:103], v[192:193], v[194:195]
	v_mov_b32_e32 v114, v124
	v_mov_b32_e32 v115, v125
	v_mov_b32_e32 v108, v122
	v_mov_b32_e32 v109, v123
.LBB0_664:
	s_movk_i32 s2, 0x4000
	v_add_co_u32_e32 v98, vcc, s2, v98
	v_pk_mul_f32 v[104:105], v[104:105], s[12:13] op_sel_hi:[1,0]
	v_pk_mul_f32 v[114:115], v[114:115], s[12:13] op_sel_hi:[1,0]
	v_pk_mul_f32 v[100:101], v[100:101], s[12:13] op_sel_hi:[1,0]
	v_addc_co_u32_e32 v99, vcc, 0, v99, vcc
	v_pk_mul_f32 v[110:111], v[110:111], s[12:13] op_sel_hi:[1,0]
	v_pk_mul_f32 v[106:107], v[106:107], s[12:13] op_sel_hi:[1,0]
	v_pk_mul_f32 v[108:109], v[108:109], s[12:13] op_sel_hi:[1,0]
	v_pk_mul_f32 v[102:103], v[102:103], s[12:13] op_sel_hi:[1,0]
	v_cvt_pk_bf16_f32 v240, v114, v115
	v_cvt_pk_bf16_f32 v241, v104, v105
	v_mbcnt_lo_u32_b32 v252, -1, 0
	v_mbcnt_hi_u32_b32 v252, -1, v252
	v_bfe_u32 v252, v252, 4, 1
	v_mul_u32_u24_e32 v252, 24, v252
	v_mov_b32_e32 v253, 0
	v_lshl_add_u64 v[248:249], v[98:99], 0, v[252:253]
	v_cvt_pk_bf16_f32 v242, v110, v111
	v_cvt_pk_bf16_f32 v243, v100, v101
	s_nop 1
	v_permlane16_swap_b32_e32 v240, v242
	v_permlane16_swap_b32_e32 v241, v243
	global_store_dwordx4 v[248:249], v[240:243], off
	v_cvt_pk_bf16_f32 v244, v108, v109
	v_cvt_pk_bf16_f32 v245, v106, v107
	v_xor_b32_e32 v121, 32, v189
	v_pk_mul_f32 v[112:113], v[112:113], s[12:13] op_sel_hi:[1,0]
	s_nop 0
	v_cvt_pk_bf16_f32 v246, v112, v113
	v_cvt_pk_bf16_f32 v247, v102, v103
	s_nop 1
	v_permlane16_swap_b32_e32 v244, v246
	v_permlane16_swap_b32_e32 v245, v247
	global_store_dwordx4 v[248:249], v[244:247], off offset:64
	v_pk_fma_f32 v[96:97], v[96:97], v[174:175], v[160:161] op_sel_hi:[1,0,1]
	v_pk_fma_f32 v[94:95], v[94:95], v[174:175], v[158:159] op_sel_hi:[1,0,1]
	v_pk_fma_f32 v[104:105], v[82:83], v[174:175], v[146:147] op_sel_hi:[1,0,1]
	v_mul_f32_e32 v82, v95, v95
	v_mul_f32_e32 v83, v97, v97
	v_pk_fma_f32 v[92:93], v[92:93], v[174:175], v[156:157] op_sel_hi:[1,0,1]
	v_pk_fma_f32 v[90:91], v[90:91], v[174:175], v[154:155] op_sel_hi:[1,0,1]
	v_fmac_f32_e32 v82, v94, v94
	v_fmac_f32_e32 v83, v96, v96
	v_pk_fma_f32 v[102:103], v[84:85], v[174:175], v[148:149] op_sel_hi:[1,0,1]
	v_add_f32_e32 v82, v82, v83
	v_mul_f32_e32 v83, v91, v91
	v_mul_f32_e32 v84, v93, v93
	v_fmac_f32_e32 v83, v90, v90
	v_fmac_f32_e32 v84, v92, v92
	v_pk_fma_f32 v[88:89], v[88:89], v[174:175], v[152:153] op_sel_hi:[1,0,1]
	v_pk_fma_f32 v[100:101], v[86:87], v[174:175], v[150:151] op_sel_hi:[1,0,1]
	v_add_f32_e32 v83, v83, v84
	v_add_f32_e32 v82, v82, v83
	v_mul_f32_e32 v83, v101, v101
	v_mul_f32_e32 v84, v89, v89
	v_fmac_f32_e32 v83, v100, v100
	v_fmac_f32_e32 v84, v88, v88
	v_add_f32_e32 v83, v83, v84
	v_add_f32_e32 v82, v82, v83
	v_mul_f32_e32 v83, v105, v105
	v_mul_f32_e32 v84, v103, v103
	v_fmac_f32_e32 v83, v104, v104
	v_fmac_f32_e32 v84, v102, v102
	v_add_f32_e32 v83, v83, v84
	v_add_f32_e32 v82, v82, v83
	v_mov_b32_e32 v83, v82
	s_nop 1
	v_permlane16_swap_b32_e32 v82, v83
	v_add_f32_e32 v82, v82, v83
	v_mov_b32_e32 v83, v82
	s_nop 1
	v_permlane32_swap_b32_e32 v82, v83
	v_add_f32_e32 v82, v82, v83
	v_fmamk_f32 v82, v82, 0x3c800000, v223
	v_rsq_f32_e32 v106, v82
	v_mov_b64_e32 v[82:83], v[162:163]
	v_mov_b64_e32 v[84:85], 0
	v_pk_mul_f32 v[90:91], v[90:91], v[106:107] op_sel_hi:[1,0]
	v_pk_mul_f32 v[84:85], v[94:95], v[106:107] op_sel_hi:[1,0]
	v_pk_mul_f32 v[88:89], v[88:89], v[106:107] op_sel_hi:[1,0]
	v_pk_mul_f32 v[86:87], v[96:97], v[106:107] op_sel_hi:[1,0]
	v_pk_mul_f32 v[98:99], v[142:143], v[84:85]
	v_pk_mul_f32 v[84:85], v[92:93], v[106:107] op_sel_hi:[1,0]
	v_pk_mul_f32 v[94:95], v[138:139], v[90:91]
	v_pk_mul_f32 v[92:93], v[100:101], v[106:107] op_sel_hi:[1,0]
	v_pk_mul_f32 v[90:91], v[136:137], v[88:89]
	v_pk_mul_f32 v[96:97], v[104:105], v[106:107] op_sel_hi:[1,0]
	v_pk_mul_f32 v[88:89], v[102:103], v[106:107] op_sel_hi:[1,0]
	v_cvt_f32_ubyte0_e32 v100, v121
	v_pk_mul_f32 v[86:87], v[144:145], v[86:87]
	v_pk_mul_f32 v[84:85], v[140:141], v[84:85]
	v_pk_mul_f32 v[92:93], v[134:135], v[92:93]
	v_pk_mul_f32 v[88:89], v[132:133], v[88:89]
	v_pk_mul_f32 v[96:97], v[130:131], v[96:97]
	s_and_b64 vcc, exec, s[42:43]
	v_mul_f32_e32 v104, v0, v100
	v_mul_f32_e32 v103, v165, v100
	v_mul_f32_e32 v102, v167, v100
	v_mul_f32_e32 v101, v169, v100
	s_cbranch_vccnz .LBB0_666
	v_add_u32_e32 v105, 32, v216
	v_ashrrev_i32_e32 v105, 6, v105
	v_cvt_f32_i32_e32 v105, v105
	v_mul_f32_e32 v106, v0, v105
	v_mul_f32_e32 v107, v165, v105
	v_floor_f32_e32 v106, v106
	v_floor_f32_e32 v107, v107
	v_fma_f32 v108, v0, v105, -v106
	v_fma_f32 v109, v165, v105, -v107
	v_sin_f32_e32 v106, v108
	v_cos_f32_e32 v108, v108
	v_sin_f32_e32 v107, v109
	v_cos_f32_e32 v109, v109
	v_mul_f32_e32 v110, v167, v105
	v_floor_f32_e32 v110, v110
	v_mul_f32_e32 v121, v169, v105
	v_fma_f32 v110, v167, v105, -v110
	v_floor_f32_e32 v121, v121
	v_cos_f32_e32 v113, v110
	v_sin_f32_e32 v115, v110
	v_fma_f32 v105, v169, v105, -v121
	v_pk_mul_f32 v[110:111], v[106:107], v[94:95]
	v_pk_mul_f32 v[94:95], v[108:109], v[94:95]
	v_sin_f32_e32 v123, v105
	v_cos_f32_e32 v122, v105
	v_pk_fma_f32 v[108:109], v[108:109], v[98:99], v[110:111] neg_lo:[0,0,1] neg_hi:[0,0,1]
	v_pk_fma_f32 v[94:95], v[106:107], v[98:99], v[94:95]
	v_floor_f32_e32 v98, v104
	v_fma_f32 v99, v0, v100, -v98
	v_mul_f32_e32 v114, v115, v84
	v_mul_f32_e32 v126, v113, v84
	v_mov_b32_e32 v84, v87
	v_sin_f32_e32 v98, v99
	v_cos_f32_e32 v106, v99
	v_floor_f32_e32 v99, v103
	v_mul_f32_e32 v112, v113, v86
	v_mul_f32_e32 v124, v115, v86
	v_pk_mul_f32 v[86:87], v[122:123], v[84:85]
	v_fma_f32 v105, v165, v100, -v99
	v_mov_b32_e32 v113, v86
	v_mov_b32_e32 v115, v87
	v_mov_b32_e32 v86, v123
	v_mov_b32_e32 v87, v122
	v_sin_f32_e32 v99, v105
	v_cos_f32_e32 v107, v105
	v_floor_f32_e32 v105, v102
	v_pk_mul_f32 v[84:85], v[86:87], v[84:85]
	v_pk_add_f32 v[86:87], v[112:113], v[114:115] neg_lo:[0,1] neg_hi:[0,1]
	v_fma_f32 v105, v167, v100, -v105
	v_floor_f32_e32 v115, v101
	v_cos_f32_e32 v113, v105
	v_sin_f32_e32 v105, v105
	v_fma_f32 v115, v169, v100, -v115
	v_sin_f32_e32 v123, v115
	v_cos_f32_e32 v122, v115
	v_mov_b32_e32 v125, v84
	v_mov_b32_e32 v127, v85
	v_pk_add_f32 v[84:85], v[124:125], v[126:127]
	v_mul_f32_e32 v114, v105, v88
	v_mul_f32_e32 v126, v113, v88
	v_mov_b32_e32 v88, v91
	v_mul_f32_e32 v112, v113, v90
	v_mul_f32_e32 v124, v105, v90
	v_pk_mul_f32 v[90:91], v[122:123], v[88:89]
	v_pk_mul_f32 v[110:111], v[98:99], v[96:97]
	v_mov_b32_e32 v113, v90
	v_mov_b32_e32 v115, v91
	v_mov_b32_e32 v90, v123
	v_mov_b32_e32 v91, v122
	v_pk_mul_f32 v[88:89], v[90:91], v[88:89]
	v_pk_mul_f32 v[96:97], v[106:107], v[96:97]
	v_mov_b32_e32 v125, v88
	v_mov_b32_e32 v127, v89
	v_pk_fma_f32 v[106:107], v[106:107], v[92:93], v[110:111] neg_lo:[0,0,1] neg_hi:[0,0,1]
	v_pk_add_f32 v[90:91], v[112:113], v[114:115] neg_lo:[0,1] neg_hi:[0,1]
	v_pk_fma_f32 v[96:97], v[98:99], v[92:93], v[96:97]
	v_pk_add_f32 v[88:89], v[124:125], v[126:127]
	v_mov_b32_e32 v98, v108
	v_mov_b32_e32 v99, v109
	v_mov_b32_e32 v92, v106
	v_mov_b32_e32 v93, v107
.LBB0_666:
	s_mov_b32 s2, 0x8000
	v_add_co_u32_e32 v82, vcc, s2, v82
	v_pk_mul_f32 v[86:87], v[86:87], s[12:13] op_sel_hi:[1,0]
	v_pk_mul_f32 v[98:99], v[98:99], s[12:13] op_sel_hi:[1,0]
	v_pk_mul_f32 v[84:85], v[84:85], s[12:13] op_sel_hi:[1,0]
	v_addc_co_u32_e32 v83, vcc, 0, v83, vcc
	v_pk_mul_f32 v[94:95], v[94:95], s[12:13] op_sel_hi:[1,0]
	v_pk_mul_f32 v[90:91], v[90:91], s[12:13] op_sel_hi:[1,0]
	v_pk_mul_f32 v[92:93], v[92:93], s[12:13] op_sel_hi:[1,0]
	v_pk_mul_f32 v[88:89], v[88:89], s[12:13] op_sel_hi:[1,0]
	v_cvt_pk_bf16_f32 v240, v98, v99
	v_cvt_pk_bf16_f32 v241, v86, v87
	v_mbcnt_lo_u32_b32 v252, -1, 0
	v_mbcnt_hi_u32_b32 v252, -1, v252
	v_bfe_u32 v252, v252, 4, 1
	v_mul_u32_u24_e32 v252, 24, v252
	v_mov_b32_e32 v253, 0
	v_lshl_add_u64 v[248:249], v[82:83], 0, v[252:253]
	v_cvt_pk_bf16_f32 v242, v94, v95
	v_cvt_pk_bf16_f32 v243, v84, v85
	s_nop 1
	v_permlane16_swap_b32_e32 v240, v242
	v_permlane16_swap_b32_e32 v241, v243
	global_store_dwordx4 v[248:249], v[240:243], off
	v_cvt_pk_bf16_f32 v244, v92, v93
	v_cvt_pk_bf16_f32 v245, v90, v91
	v_pk_fma_f32 v[80:81], v[80:81], v[172:173], v[160:161] op_sel_hi:[1,0,1]
	v_pk_fma_f32 v[78:79], v[78:79], v[172:173], v[158:159] op_sel_hi:[1,0,1]
	v_pk_mul_f32 v[96:97], v[96:97], s[12:13] op_sel_hi:[1,0]
	s_nop 0
	v_cvt_pk_bf16_f32 v246, v96, v97
	v_cvt_pk_bf16_f32 v247, v88, v89
	v_pk_fma_f32 v[88:89], v[66:67], v[172:173], v[146:147] op_sel_hi:[1,0,1]
	v_mul_f32_e32 v66, v79, v79
	v_mul_f32_e32 v67, v81, v81
	v_pk_fma_f32 v[76:77], v[76:77], v[172:173], v[156:157] op_sel_hi:[1,0,1]
	v_pk_fma_f32 v[74:75], v[74:75], v[172:173], v[154:155] op_sel_hi:[1,0,1]
	v_fmac_f32_e32 v66, v78, v78
	v_fmac_f32_e32 v67, v80, v80
	v_pk_fma_f32 v[86:87], v[68:69], v[172:173], v[148:149] op_sel_hi:[1,0,1]
	v_add_f32_e32 v66, v66, v67
	v_mul_f32_e32 v67, v75, v75
	v_mul_f32_e32 v68, v77, v77
	v_fmac_f32_e32 v67, v74, v74
	v_fmac_f32_e32 v68, v76, v76
	s_nop 1
	v_permlane16_swap_b32_e32 v244, v246
	v_permlane16_swap_b32_e32 v245, v247
	global_store_dwordx4 v[248:249], v[244:247], off offset:64
	v_pk_fma_f32 v[84:85], v[72:73], v[172:173], v[152:153] op_sel_hi:[1,0,1]
	v_pk_fma_f32 v[70:71], v[70:71], v[172:173], v[150:151] op_sel_hi:[1,0,1]
	v_add_f32_e32 v67, v67, v68
	v_add_f32_e32 v66, v66, v67
	v_mul_f32_e32 v67, v71, v71
	v_mul_f32_e32 v68, v85, v85
	v_fmac_f32_e32 v67, v70, v70
	v_fmac_f32_e32 v68, v84, v84
	v_add_f32_e32 v67, v67, v68
	v_add_f32_e32 v66, v66, v67
	v_mul_f32_e32 v67, v89, v89
	v_mul_f32_e32 v68, v87, v87
	v_fmac_f32_e32 v67, v88, v88
	v_fmac_f32_e32 v68, v86, v86
	v_add_f32_e32 v67, v67, v68
	v_add_f32_e32 v66, v66, v67
	v_mov_b32_e32 v67, v66
	s_nop 1
	v_permlane16_swap_b32_e32 v66, v67
	v_add_f32_e32 v66, v66, v67
	v_mov_b32_e32 v67, v66
	s_nop 1
	v_permlane32_swap_b32_e32 v66, v67
	v_add_f32_e32 v66, v66, v67
	v_fmamk_f32 v66, v66, 0x3c800000, v223
	v_rsq_f32_e32 v90, v66
	v_mov_b64_e32 v[66:67], v[162:163]
	v_mov_b64_e32 v[68:69], 0
	v_add_u32_e32 v105, 48, v216
	v_and_b32_e32 v106, 63, v105
	v_pk_mul_f32 v[68:69], v[78:79], v[90:91] op_sel_hi:[1,0]
	v_pk_mul_f32 v[74:75], v[74:75], v[90:91] op_sel_hi:[1,0]
	v_pk_mul_f32 v[70:71], v[70:71], v[90:91] op_sel_hi:[1,0]
	v_pk_mul_f32 v[72:73], v[80:81], v[90:91] op_sel_hi:[1,0]
	v_pk_mul_f32 v[82:83], v[142:143], v[68:69]
	v_pk_mul_f32 v[68:69], v[76:77], v[90:91] op_sel_hi:[1,0]
	v_pk_mul_f32 v[78:79], v[138:139], v[74:75]
	v_pk_mul_f32 v[74:75], v[84:85], v[90:91] op_sel_hi:[1,0]
	v_pk_mul_f32 v[76:77], v[134:135], v[70:71]
	v_pk_mul_f32 v[80:81], v[88:89], v[90:91] op_sel_hi:[1,0]
	v_pk_mul_f32 v[70:71], v[86:87], v[90:91] op_sel_hi:[1,0]
	v_cvt_f32_ubyte0_e32 v84, v106
	v_pk_mul_f32 v[72:73], v[144:145], v[72:73]
	v_pk_mul_f32 v[68:69], v[140:141], v[68:69]
	v_pk_mul_f32 v[74:75], v[136:137], v[74:75]
	v_pk_mul_f32 v[70:71], v[132:133], v[70:71]
	v_pk_mul_f32 v[80:81], v[130:131], v[80:81]
	s_and_b64 vcc, exec, s[42:43]
	v_mul_f32_e32 v88, v0, v84
	v_mul_f32_e32 v87, v165, v84
	v_mul_f32_e32 v86, v167, v84
	v_mul_f32_e32 v85, v169, v84
	s_cbranch_vccnz .LBB0_668
	v_ashrrev_i32_e32 v89, 6, v105
	v_cvt_f32_i32_e32 v89, v89
	v_mul_f32_e32 v90, v0, v89
	v_mul_f32_e32 v91, v165, v89
	v_floor_f32_e32 v90, v90
	v_floor_f32_e32 v91, v91
	v_fma_f32 v92, v0, v89, -v90
	v_fma_f32 v93, v165, v89, -v91
	v_sin_f32_e32 v90, v92
	v_cos_f32_e32 v92, v92
	v_sin_f32_e32 v91, v93
	v_cos_f32_e32 v93, v93
	v_mul_f32_e32 v94, v167, v89
	v_floor_f32_e32 v94, v94
	v_mul_f32_e32 v105, v169, v89
	v_fma_f32 v94, v167, v89, -v94
	v_floor_f32_e32 v105, v105
	v_cos_f32_e32 v97, v94
	v_sin_f32_e32 v99, v94
	v_fma_f32 v89, v169, v89, -v105
	v_pk_mul_f32 v[94:95], v[90:91], v[78:79]
	v_pk_mul_f32 v[78:79], v[92:93], v[78:79]
	v_sin_f32_e32 v107, v89
	v_cos_f32_e32 v106, v89
	v_pk_fma_f32 v[92:93], v[92:93], v[82:83], v[94:95] neg_lo:[0,0,1] neg_hi:[0,0,1]
	v_pk_fma_f32 v[78:79], v[90:91], v[82:83], v[78:79]
	v_floor_f32_e32 v82, v88
	v_fma_f32 v83, v0, v84, -v82
	v_mul_f32_e32 v98, v99, v68
	v_mul_f32_e32 v110, v97, v68
	v_mov_b32_e32 v68, v73
	v_sin_f32_e32 v82, v83
	v_cos_f32_e32 v90, v83
	v_floor_f32_e32 v83, v87
	v_mul_f32_e32 v96, v97, v72
	v_mul_f32_e32 v108, v99, v72
	v_pk_mul_f32 v[72:73], v[106:107], v[68:69]
	v_fma_f32 v89, v165, v84, -v83
	v_mov_b32_e32 v97, v72
	v_mov_b32_e32 v99, v73
	v_mov_b32_e32 v72, v107
	v_mov_b32_e32 v73, v106
	v_sin_f32_e32 v83, v89
	v_cos_f32_e32 v91, v89
	v_floor_f32_e32 v89, v86
	v_pk_mul_f32 v[68:69], v[72:73], v[68:69]
	v_pk_add_f32 v[72:73], v[96:97], v[98:99] neg_lo:[0,1] neg_hi:[0,1]
	v_fma_f32 v89, v167, v84, -v89
	v_floor_f32_e32 v99, v85
	v_cos_f32_e32 v97, v89
	v_sin_f32_e32 v89, v89
	v_fma_f32 v99, v169, v84, -v99
	v_sin_f32_e32 v107, v99
	v_cos_f32_e32 v106, v99
	v_mov_b32_e32 v109, v68
	v_mov_b32_e32 v111, v69
	v_pk_add_f32 v[68:69], v[108:109], v[110:111]
	v_mul_f32_e32 v98, v89, v70
	v_mul_f32_e32 v110, v97, v70
	v_mov_b32_e32 v70, v75
	v_mul_f32_e32 v96, v97, v74
	v_mul_f32_e32 v108, v89, v74
	v_pk_mul_f32 v[74:75], v[106:107], v[70:71]
	v_pk_mul_f32 v[94:95], v[82:83], v[80:81]
	v_mov_b32_e32 v97, v74
	v_mov_b32_e32 v99, v75
	v_mov_b32_e32 v74, v107
	v_mov_b32_e32 v75, v106
	v_pk_mul_f32 v[70:71], v[74:75], v[70:71]
	v_pk_mul_f32 v[80:81], v[90:91], v[80:81]
	v_mov_b32_e32 v109, v70
	v_mov_b32_e32 v111, v71
	v_pk_fma_f32 v[90:91], v[90:91], v[76:77], v[94:95] neg_lo:[0,0,1] neg_hi:[0,0,1]
	v_pk_add_f32 v[74:75], v[96:97], v[98:99] neg_lo:[0,1] neg_hi:[0,1]
	v_pk_fma_f32 v[80:81], v[82:83], v[76:77], v[80:81]
	v_pk_add_f32 v[70:71], v[108:109], v[110:111]
	v_mov_b32_e32 v82, v92
	v_mov_b32_e32 v83, v93
	v_mov_b32_e32 v76, v90
	v_mov_b32_e32 v77, v91
.LBB0_668:
	s_mov_b32 s2, 0xc000
	v_add_co_u32_e32 v66, vcc, s2, v66
	v_pk_mul_f32 v[72:73], v[72:73], s[12:13] op_sel_hi:[1,0]
	v_pk_mul_f32 v[82:83], v[82:83], s[12:13] op_sel_hi:[1,0]
	v_pk_mul_f32 v[68:69], v[68:69], s[12:13] op_sel_hi:[1,0]
	v_addc_co_u32_e32 v67, vcc, 0, v67, vcc
	v_pk_mul_f32 v[78:79], v[78:79], s[12:13] op_sel_hi:[1,0]
	v_pk_mul_f32 v[74:75], v[74:75], s[12:13] op_sel_hi:[1,0]
	v_pk_mul_f32 v[76:77], v[76:77], s[12:13] op_sel_hi:[1,0]
	v_cvt_pk_bf16_f32 v240, v82, v83
	v_cvt_pk_bf16_f32 v241, v72, v73
	v_mbcnt_lo_u32_b32 v252, -1, 0
	v_mbcnt_hi_u32_b32 v252, -1, v252
	v_bfe_u32 v252, v252, 4, 1
	v_mul_u32_u24_e32 v252, 24, v252
	v_mov_b32_e32 v253, 0
	v_lshl_add_u64 v[248:249], v[66:67], 0, v[252:253]
	v_cvt_pk_bf16_f32 v242, v78, v79
	v_cvt_pk_bf16_f32 v243, v68, v69
	s_nop 1
	v_permlane16_swap_b32_e32 v240, v242
	v_permlane16_swap_b32_e32 v241, v243
	global_store_dwordx4 v[248:249], v[240:243], off
	v_cvt_pk_bf16_f32 v244, v76, v77
	v_cvt_pk_bf16_f32 v245, v74, v75
	v_pk_mul_f32 v[70:71], v[70:71], s[12:13] op_sel_hi:[1,0]
	v_pk_mul_f32 v[80:81], v[80:81], s[12:13] op_sel_hi:[1,0]
	s_nop 0
	v_cvt_pk_bf16_f32 v246, v80, v81
	v_cvt_pk_bf16_f32 v247, v70, v71
	s_nop 1
	v_permlane16_swap_b32_e32 v244, v246
	v_permlane16_swap_b32_e32 v245, v247
	global_store_dwordx4 v[248:249], v[244:247], off offset:64
	v_pk_fma_f32 v[64:65], v[64:65], v[170:171], v[160:161] op_sel_hi:[1,0,1]
	v_pk_fma_f32 v[62:63], v[62:63], v[170:171], v[158:159] op_sel_hi:[1,0,1]
	v_pk_fma_f32 v[72:73], v[50:51], v[170:171], v[146:147] op_sel_hi:[1,0,1]
	v_mul_f32_e32 v50, v63, v63
	v_mul_f32_e32 v51, v65, v65
	v_pk_fma_f32 v[60:61], v[60:61], v[170:171], v[156:157] op_sel_hi:[1,0,1]
	v_pk_fma_f32 v[58:59], v[58:59], v[170:171], v[154:155] op_sel_hi:[1,0,1]
	v_fmac_f32_e32 v50, v62, v62
	v_fmac_f32_e32 v51, v64, v64
	v_pk_fma_f32 v[70:71], v[52:53], v[170:171], v[148:149] op_sel_hi:[1,0,1]
	v_add_f32_e32 v50, v50, v51
	v_mul_f32_e32 v51, v59, v59
	v_mul_f32_e32 v52, v61, v61
	v_fmac_f32_e32 v51, v58, v58
	v_fmac_f32_e32 v52, v60, v60
	v_pk_fma_f32 v[56:57], v[56:57], v[170:171], v[152:153] op_sel_hi:[1,0,1]
	v_pk_fma_f32 v[68:69], v[54:55], v[170:171], v[150:151] op_sel_hi:[1,0,1]
	v_add_f32_e32 v51, v51, v52
	v_add_f32_e32 v50, v50, v51
	v_mul_f32_e32 v51, v69, v69
	v_mul_f32_e32 v52, v57, v57
	v_fmac_f32_e32 v51, v68, v68
	v_fmac_f32_e32 v52, v56, v56
	v_add_f32_e32 v51, v51, v52
	v_add_f32_e32 v50, v51, v50
	v_mul_f32_e32 v51, v73, v73
	v_mul_f32_e32 v52, v71, v71
	v_fmac_f32_e32 v51, v72, v72
	v_fmac_f32_e32 v52, v70, v70
	v_add_f32_e32 v51, v51, v52
	v_add_f32_e32 v50, v51, v50
	v_mov_b32_e32 v51, v50
	s_nop 1
	v_permlane16_swap_b32_e32 v50, v51
	v_add_f32_e32 v50, v50, v51
	v_mov_b32_e32 v51, v50
	s_nop 1
	v_permlane32_swap_b32_e32 v50, v51
	v_add_f32_e32 v50, v50, v51
	v_fmamk_f32 v50, v50, 0x3c800000, v223
	v_rsq_f32_e32 v74, v50
	v_mov_b64_e32 v[50:51], v[162:163]
	v_mov_b64_e32 v[52:53], 0
	v_pk_mul_f32 v[58:59], v[58:59], v[74:75] op_sel_hi:[1,0]
	v_pk_mul_f32 v[52:53], v[62:63], v[74:75] op_sel_hi:[1,0]
	v_pk_mul_f32 v[56:57], v[56:57], v[74:75] op_sel_hi:[1,0]
	v_pk_mul_f32 v[54:55], v[64:65], v[74:75] op_sel_hi:[1,0]
	v_pk_mul_f32 v[66:67], v[142:143], v[52:53]
	v_pk_mul_f32 v[52:53], v[60:61], v[74:75] op_sel_hi:[1,0]
	v_pk_mul_f32 v[62:63], v[138:139], v[58:59]
	v_pk_mul_f32 v[60:61], v[68:69], v[74:75] op_sel_hi:[1,0]
	v_pk_mul_f32 v[58:59], v[136:137], v[56:57]
	v_pk_mul_f32 v[64:65], v[72:73], v[74:75] op_sel_hi:[1,0]
	v_pk_mul_f32 v[56:57], v[70:71], v[74:75] op_sel_hi:[1,0]
	v_pk_mul_f32 v[54:55], v[144:145], v[54:55]
	v_pk_mul_f32 v[52:53], v[140:141], v[52:53]
	v_pk_mul_f32 v[60:61], v[134:135], v[60:61]
	v_pk_mul_f32 v[56:57], v[132:133], v[56:57]
	s_and_b64 vcc, exec, s[42:43]
	v_pk_mul_f32 v[64:65], v[130:131], v[64:65]
	s_cbranch_vccnz .LBB0_670
	v_add_u32_e32 v68, 0x80, v216
	v_ashrrev_i32_e32 v68, 6, v68
	v_cvt_f32_i32_e32 v75, v68
	v_mul_f32_e32 v68, v0, v75
	v_mul_f32_e32 v69, v165, v75
	v_mul_f32_e32 v72, v167, v75
	v_floor_f32_e32 v68, v68
	v_floor_f32_e32 v69, v69
	v_floor_f32_e32 v72, v72
	v_mul_f32_e32 v78, v169, v75
	v_fma_f32 v70, v0, v75, -v68
	v_fma_f32 v71, v165, v75, -v69
	v_fma_f32 v72, v167, v75, -v72
	v_floor_f32_e32 v78, v78
	v_sin_f32_e32 v68, v70
	v_sin_f32_e32 v69, v71
	v_cos_f32_e32 v77, v72
	v_sin_f32_e32 v80, v72
	v_fma_f32 v75, v169, v75, -v78
	v_cos_f32_e32 v70, v70
	v_cos_f32_e32 v71, v71
	v_sin_f32_e32 v79, v75
	v_cos_f32_e32 v78, v75
	v_pk_mul_f32 v[72:73], v[68:69], v[62:63]
	v_mul_f32_e32 v76, v80, v52
	v_mul_f32_e32 v82, v77, v52
	v_mov_b32_e32 v52, v55
	v_pk_mul_f32 v[62:63], v[70:71], v[62:63]
	v_mul_f32_e32 v74, v77, v54
	v_mul_f32_e32 v80, v80, v54
	v_pk_mul_f32 v[54:55], v[78:79], v[52:53]
	v_pk_fma_f32 v[70:71], v[70:71], v[66:67], v[72:73] neg_lo:[0,0,1] neg_hi:[0,0,1]
	v_floor_f32_e32 v72, v175
	v_mov_b32_e32 v75, v54
	v_mov_b32_e32 v77, v55
	v_mov_b32_e32 v54, v79
	v_mov_b32_e32 v55, v78
	v_pk_fma_f32 v[62:63], v[68:69], v[66:67], v[62:63]
	v_floor_f32_e32 v66, v173
	v_fma_f32 v72, v167, v171, -v72
	v_floor_f32_e32 v78, v188
	v_pk_mul_f32 v[52:53], v[54:55], v[52:53]
	v_pk_add_f32 v[54:55], v[74:75], v[76:77] neg_lo:[0,1] neg_hi:[0,1]
	v_fma_f32 v67, v0, v171, -v66
	v_cos_f32_e32 v75, v72
	v_sin_f32_e32 v77, v72
	v_fma_f32 v78, v169, v171, -v78
	v_sin_f32_e32 v66, v67
	v_cos_f32_e32 v68, v67
	v_floor_f32_e32 v67, v177
	v_sin_f32_e32 v79, v78
	v_cos_f32_e32 v78, v78
	v_fma_f32 v69, v165, v171, -v67
	v_mov_b32_e32 v81, v52
	v_mov_b32_e32 v83, v53
	v_sin_f32_e32 v67, v69
	v_pk_add_f32 v[52:53], v[80:81], v[82:83]
	v_cos_f32_e32 v69, v69
	v_mul_f32_e32 v76, v77, v56
	v_mul_f32_e32 v82, v75, v56
	v_mov_b32_e32 v56, v59
	v_mul_f32_e32 v74, v75, v58
	v_mul_f32_e32 v80, v77, v58
	v_pk_mul_f32 v[58:59], v[78:79], v[56:57]
	v_pk_mul_f32 v[72:73], v[66:67], v[64:65]
	v_mov_b32_e32 v75, v58
	v_mov_b32_e32 v77, v59
	v_mov_b32_e32 v58, v79
	v_mov_b32_e32 v59, v78
	v_pk_mul_f32 v[56:57], v[58:59], v[56:57]
	v_pk_mul_f32 v[64:65], v[68:69], v[64:65]
	v_mov_b32_e32 v81, v56
	v_mov_b32_e32 v83, v57
	v_pk_fma_f32 v[68:69], v[68:69], v[60:61], v[72:73] neg_lo:[0,0,1] neg_hi:[0,0,1]
	v_pk_add_f32 v[58:59], v[74:75], v[76:77] neg_lo:[0,1] neg_hi:[0,1]
	v_pk_fma_f32 v[64:65], v[66:67], v[60:61], v[64:65]
	v_pk_add_f32 v[56:57], v[80:81], v[82:83]
	v_mov_b32_e32 v66, v70
	v_mov_b32_e32 v67, v71
	v_mov_b32_e32 v60, v68
	v_mov_b32_e32 v61, v69
.LBB0_670:
	s_mov_b32 s2, 0x20000
	v_add_co_u32_e32 v50, vcc, s2, v50
	v_pk_mul_f32 v[54:55], v[54:55], s[12:13] op_sel_hi:[1,0]
	v_pk_mul_f32 v[66:67], v[66:67], s[12:13] op_sel_hi:[1,0]
	v_pk_mul_f32 v[52:53], v[52:53], s[12:13] op_sel_hi:[1,0]
	v_addc_co_u32_e32 v51, vcc, 0, v51, vcc
	v_pk_mul_f32 v[62:63], v[62:63], s[12:13] op_sel_hi:[1,0]
	v_pk_mul_f32 v[58:59], v[58:59], s[12:13] op_sel_hi:[1,0]
	v_pk_mul_f32 v[60:61], v[60:61], s[12:13] op_sel_hi:[1,0]
	v_pk_mul_f32 v[56:57], v[56:57], s[12:13] op_sel_hi:[1,0]
	v_cvt_pk_bf16_f32 v240, v66, v67
	v_cvt_pk_bf16_f32 v241, v54, v55
	v_mbcnt_lo_u32_b32 v252, -1, 0
	v_mbcnt_hi_u32_b32 v252, -1, v252
	v_bfe_u32 v252, v252, 4, 1
	v_mul_u32_u24_e32 v252, 24, v252
	v_mov_b32_e32 v253, 0
	v_lshl_add_u64 v[248:249], v[50:51], 0, v[252:253]
	v_cvt_pk_bf16_f32 v242, v62, v63
	v_cvt_pk_bf16_f32 v243, v52, v53
	s_nop 1
	v_permlane16_swap_b32_e32 v240, v242
	v_permlane16_swap_b32_e32 v241, v243
	global_store_dwordx4 v[248:249], v[240:243], off
	v_cvt_pk_bf16_f32 v244, v60, v61
	v_cvt_pk_bf16_f32 v245, v58, v59
	v_pk_fma_f32 v[48:49], v[48:49], v[168:169], v[160:161] op_sel_hi:[1,0,1]
	v_pk_fma_f32 v[46:47], v[46:47], v[168:169], v[158:159] op_sel_hi:[1,0,1]
	v_pk_mul_f32 v[64:65], v[64:65], s[12:13] op_sel_hi:[1,0]
	s_nop 0
	v_cvt_pk_bf16_f32 v246, v64, v65
	v_cvt_pk_bf16_f32 v247, v56, v57
	v_pk_fma_f32 v[56:57], v[34:35], v[168:169], v[146:147] op_sel_hi:[1,0,1]
	v_mul_f32_e32 v34, v47, v47
	v_mul_f32_e32 v35, v49, v49
	v_pk_fma_f32 v[44:45], v[44:45], v[168:169], v[156:157] op_sel_hi:[1,0,1]
	v_pk_fma_f32 v[42:43], v[42:43], v[168:169], v[154:155] op_sel_hi:[1,0,1]
	v_fmac_f32_e32 v34, v46, v46
	v_fmac_f32_e32 v35, v48, v48
	v_pk_fma_f32 v[54:55], v[36:37], v[168:169], v[148:149] op_sel_hi:[1,0,1]
	v_add_f32_e32 v34, v34, v35
	v_mul_f32_e32 v35, v43, v43
	v_mul_f32_e32 v36, v45, v45
	v_fmac_f32_e32 v35, v42, v42
	v_fmac_f32_e32 v36, v44, v44
	s_nop 1
	v_permlane16_swap_b32_e32 v244, v246
	v_permlane16_swap_b32_e32 v245, v247
	global_store_dwordx4 v[248:249], v[244:247], off offset:64
	v_pk_fma_f32 v[52:53], v[40:41], v[168:169], v[152:153] op_sel_hi:[1,0,1]
	v_pk_fma_f32 v[38:39], v[38:39], v[168:169], v[150:151] op_sel_hi:[1,0,1]
	v_add_f32_e32 v35, v35, v36
	v_add_f32_e32 v34, v34, v35
	v_mul_f32_e32 v35, v39, v39
	v_mul_f32_e32 v36, v53, v53
	v_fmac_f32_e32 v35, v38, v38
	v_fmac_f32_e32 v36, v52, v52
	v_add_f32_e32 v35, v35, v36
	v_add_f32_e32 v34, v35, v34
	v_mul_f32_e32 v35, v57, v57
	v_mul_f32_e32 v36, v55, v55
	v_fmac_f32_e32 v35, v56, v56
	v_fmac_f32_e32 v36, v54, v54
	v_add_f32_e32 v35, v35, v36
	v_add_f32_e32 v34, v35, v34
	v_mov_b32_e32 v35, v34
	s_nop 1
	v_permlane16_swap_b32_e32 v34, v35
	v_add_f32_e32 v34, v34, v35
	v_mov_b32_e32 v35, v34
	s_nop 1
	v_permlane32_swap_b32_e32 v34, v35
	v_add_f32_e32 v34, v34, v35
	v_fmamk_f32 v34, v34, 0x3c800000, v223
	v_rsq_f32_e32 v58, v34
	v_mov_b64_e32 v[36:37], 0
	v_mov_b64_e32 v[34:35], v[162:163]
	v_pk_mul_f32 v[42:43], v[42:43], v[58:59] op_sel_hi:[1,0]
	v_pk_mul_f32 v[36:37], v[46:47], v[58:59] op_sel_hi:[1,0]
	v_pk_mul_f32 v[38:39], v[38:39], v[58:59] op_sel_hi:[1,0]
	v_pk_mul_f32 v[40:41], v[48:49], v[58:59] op_sel_hi:[1,0]
	v_pk_mul_f32 v[50:51], v[142:143], v[36:37]
	v_pk_mul_f32 v[36:37], v[44:45], v[58:59] op_sel_hi:[1,0]
	v_pk_mul_f32 v[46:47], v[138:139], v[42:43]
	v_pk_mul_f32 v[42:43], v[52:53], v[58:59] op_sel_hi:[1,0]
	v_pk_mul_f32 v[44:45], v[134:135], v[38:39]
	v_pk_mul_f32 v[48:49], v[56:57], v[58:59] op_sel_hi:[1,0]
	v_pk_mul_f32 v[38:39], v[54:55], v[58:59] op_sel_hi:[1,0]
	v_pk_mul_f32 v[40:41], v[144:145], v[40:41]
	v_pk_mul_f32 v[36:37], v[140:141], v[36:37]
	v_pk_mul_f32 v[42:43], v[136:137], v[42:43]
	v_pk_mul_f32 v[38:39], v[132:133], v[38:39]
	s_and_b64 vcc, exec, s[42:43]
	v_pk_mul_f32 v[48:49], v[130:131], v[48:49]
	s_cbranch_vccnz .LBB0_672
	v_add_u32_e32 v52, 0x90, v216
	v_ashrrev_i32_e32 v52, 6, v52
	v_cvt_f32_i32_e32 v59, v52
	v_mul_f32_e32 v52, v0, v59
	v_mul_f32_e32 v53, v165, v59
	v_mul_f32_e32 v56, v167, v59
	v_floor_f32_e32 v52, v52
	v_floor_f32_e32 v53, v53
	v_floor_f32_e32 v56, v56
	v_mul_f32_e32 v62, v169, v59
	v_fma_f32 v54, v0, v59, -v52
	v_fma_f32 v55, v165, v59, -v53
	v_fma_f32 v56, v167, v59, -v56
	v_floor_f32_e32 v62, v62
	v_sin_f32_e32 v52, v54
	v_sin_f32_e32 v53, v55
	v_cos_f32_e32 v61, v56
	v_sin_f32_e32 v64, v56
	v_fma_f32 v59, v169, v59, -v62
	v_cos_f32_e32 v54, v54
	v_cos_f32_e32 v55, v55
	v_sin_f32_e32 v63, v59
	v_cos_f32_e32 v62, v59
	v_pk_mul_f32 v[56:57], v[52:53], v[46:47]
	v_mul_f32_e32 v60, v64, v36
	v_mul_f32_e32 v66, v61, v36
	v_mov_b32_e32 v36, v41
	v_pk_mul_f32 v[46:47], v[54:55], v[46:47]
	v_mul_f32_e32 v58, v61, v40
	v_mul_f32_e32 v64, v64, v40
	v_pk_mul_f32 v[40:41], v[62:63], v[36:37]
	v_pk_fma_f32 v[54:55], v[54:55], v[50:51], v[56:57] neg_lo:[0,0,1] neg_hi:[0,0,1]
	v_floor_f32_e32 v56, v118
	v_mov_b32_e32 v59, v40
	v_mov_b32_e32 v61, v41
	v_mov_b32_e32 v40, v63
	v_mov_b32_e32 v41, v62
	v_pk_fma_f32 v[46:47], v[52:53], v[50:51], v[46:47]
	v_floor_f32_e32 v50, v120
	v_fma_f32 v56, v167, v116, -v56
	v_floor_f32_e32 v62, v117
	v_pk_mul_f32 v[36:37], v[40:41], v[36:37]
	v_pk_add_f32 v[40:41], v[58:59], v[60:61] neg_lo:[0,1] neg_hi:[0,1]
	v_fma_f32 v51, v0, v116, -v50
	v_cos_f32_e32 v59, v56
	v_sin_f32_e32 v61, v56
	v_fma_f32 v62, v169, v116, -v62
	v_sin_f32_e32 v50, v51
	v_cos_f32_e32 v52, v51
	v_floor_f32_e32 v51, v119
	v_sin_f32_e32 v63, v62
	v_cos_f32_e32 v62, v62
	v_fma_f32 v53, v165, v116, -v51
	v_mov_b32_e32 v65, v36
	v_mov_b32_e32 v67, v37
	v_sin_f32_e32 v51, v53
	v_pk_add_f32 v[36:37], v[64:65], v[66:67]
	v_cos_f32_e32 v53, v53
	v_mul_f32_e32 v60, v61, v38
	v_mul_f32_e32 v66, v59, v38
	v_mov_b32_e32 v38, v43
	v_mul_f32_e32 v58, v59, v42
	v_mul_f32_e32 v64, v61, v42
	v_pk_mul_f32 v[42:43], v[62:63], v[38:39]
	v_pk_mul_f32 v[56:57], v[50:51], v[48:49]
	v_mov_b32_e32 v59, v42
	v_mov_b32_e32 v61, v43
	v_mov_b32_e32 v42, v63
	v_mov_b32_e32 v43, v62
	v_pk_mul_f32 v[38:39], v[42:43], v[38:39]
	v_pk_mul_f32 v[48:49], v[52:53], v[48:49]
	v_mov_b32_e32 v65, v38
	v_mov_b32_e32 v67, v39
	v_pk_fma_f32 v[52:53], v[52:53], v[44:45], v[56:57] neg_lo:[0,0,1] neg_hi:[0,0,1]
	v_pk_add_f32 v[42:43], v[58:59], v[60:61] neg_lo:[0,1] neg_hi:[0,1]
	v_pk_fma_f32 v[48:49], v[50:51], v[44:45], v[48:49]
	v_pk_add_f32 v[38:39], v[64:65], v[66:67]
	v_mov_b32_e32 v50, v54
	v_mov_b32_e32 v51, v55
	v_mov_b32_e32 v44, v52
	v_mov_b32_e32 v45, v53
.LBB0_672:
	s_mov_b32 s2, 0x24000
	v_add_co_u32_e32 v34, vcc, s2, v34
	v_pk_mul_f32 v[40:41], v[40:41], s[12:13] op_sel_hi:[1,0]
	v_pk_mul_f32 v[50:51], v[50:51], s[12:13] op_sel_hi:[1,0]
	v_pk_mul_f32 v[36:37], v[36:37], s[12:13] op_sel_hi:[1,0]
	v_addc_co_u32_e32 v35, vcc, 0, v35, vcc
	v_pk_mul_f32 v[46:47], v[46:47], s[12:13] op_sel_hi:[1,0]
	v_pk_mul_f32 v[42:43], v[42:43], s[12:13] op_sel_hi:[1,0]
	v_pk_mul_f32 v[44:45], v[44:45], s[12:13] op_sel_hi:[1,0]
	v_cvt_pk_bf16_f32 v240, v50, v51
	v_cvt_pk_bf16_f32 v241, v40, v41
	v_mbcnt_lo_u32_b32 v252, -1, 0
	v_mbcnt_hi_u32_b32 v252, -1, v252
	v_bfe_u32 v252, v252, 4, 1
	v_mul_u32_u24_e32 v252, 24, v252
	v_mov_b32_e32 v253, 0
	v_lshl_add_u64 v[248:249], v[34:35], 0, v[252:253]
	v_cvt_pk_bf16_f32 v242, v46, v47
	v_cvt_pk_bf16_f32 v243, v36, v37
	s_nop 1
	v_permlane16_swap_b32_e32 v240, v242
	v_permlane16_swap_b32_e32 v241, v243
	global_store_dwordx4 v[248:249], v[240:243], off
	v_cvt_pk_bf16_f32 v244, v44, v45
	v_cvt_pk_bf16_f32 v245, v42, v43
	v_pk_mul_f32 v[38:39], v[38:39], s[12:13] op_sel_hi:[1,0]
	v_pk_mul_f32 v[48:49], v[48:49], s[12:13] op_sel_hi:[1,0]
	s_nop 0
	v_cvt_pk_bf16_f32 v246, v48, v49
	v_cvt_pk_bf16_f32 v247, v38, v39
	s_nop 1
	v_permlane16_swap_b32_e32 v244, v246
	v_permlane16_swap_b32_e32 v245, v247
	global_store_dwordx4 v[248:249], v[244:247], off offset:64
	v_pk_fma_f32 v[32:33], v[32:33], v[166:167], v[160:161] op_sel_hi:[1,0,1]
	v_pk_fma_f32 v[30:31], v[30:31], v[166:167], v[158:159] op_sel_hi:[1,0,1]
	v_pk_fma_f32 v[40:41], v[18:19], v[166:167], v[146:147] op_sel_hi:[1,0,1]
	v_mul_f32_e32 v18, v31, v31
	v_mul_f32_e32 v19, v33, v33
	v_pk_fma_f32 v[28:29], v[28:29], v[166:167], v[156:157] op_sel_hi:[1,0,1]
	v_pk_fma_f32 v[26:27], v[26:27], v[166:167], v[154:155] op_sel_hi:[1,0,1]
	v_fmac_f32_e32 v18, v30, v30
	v_fmac_f32_e32 v19, v32, v32
	v_pk_fma_f32 v[38:39], v[20:21], v[166:167], v[148:149] op_sel_hi:[1,0,1]
	v_add_f32_e32 v18, v18, v19
	v_mul_f32_e32 v19, v27, v27
	v_mul_f32_e32 v20, v29, v29
	v_fmac_f32_e32 v19, v26, v26
	v_fmac_f32_e32 v20, v28, v28
	v_pk_fma_f32 v[24:25], v[24:25], v[166:167], v[152:153] op_sel_hi:[1,0,1]
	v_pk_fma_f32 v[36:37], v[22:23], v[166:167], v[150:151] op_sel_hi:[1,0,1]
	v_add_f32_e32 v19, v19, v20
	v_add_f32_e32 v18, v18, v19
	v_mul_f32_e32 v19, v37, v37
	v_mul_f32_e32 v20, v25, v25
	v_fmac_f32_e32 v19, v36, v36
	v_fmac_f32_e32 v20, v24, v24
	v_add_f32_e32 v19, v19, v20
	v_add_f32_e32 v18, v19, v18
	v_mul_f32_e32 v19, v41, v41
	v_mul_f32_e32 v20, v39, v39
	v_fmac_f32_e32 v19, v40, v40
	v_fmac_f32_e32 v20, v38, v38
	v_add_f32_e32 v19, v19, v20
	v_add_f32_e32 v18, v19, v18
	v_mov_b32_e32 v19, v18
	s_nop 1
	v_permlane16_swap_b32_e32 v18, v19
	v_add_f32_e32 v18, v18, v19
	v_mov_b32_e32 v19, v18
	s_nop 1
	v_permlane32_swap_b32_e32 v18, v19
	v_add_f32_e32 v18, v18, v19
	v_fmamk_f32 v18, v18, 0x3c800000, v223
	v_rsq_f32_e32 v42, v18
	v_mov_b64_e32 v[18:19], v[162:163]
	v_mov_b64_e32 v[20:21], 0
	v_pk_mul_f32 v[26:27], v[26:27], v[42:43] op_sel_hi:[1,0]
	v_pk_mul_f32 v[20:21], v[30:31], v[42:43] op_sel_hi:[1,0]
	v_pk_mul_f32 v[24:25], v[24:25], v[42:43] op_sel_hi:[1,0]
	v_pk_mul_f32 v[22:23], v[32:33], v[42:43] op_sel_hi:[1,0]
	v_pk_mul_f32 v[34:35], v[142:143], v[20:21]
	v_pk_mul_f32 v[20:21], v[28:29], v[42:43] op_sel_hi:[1,0]
	v_pk_mul_f32 v[30:31], v[138:139], v[26:27]
	v_pk_mul_f32 v[28:29], v[36:37], v[42:43] op_sel_hi:[1,0]
	v_pk_mul_f32 v[26:27], v[136:137], v[24:25]
	v_pk_mul_f32 v[32:33], v[40:41], v[42:43] op_sel_hi:[1,0]
	v_pk_mul_f32 v[24:25], v[38:39], v[42:43] op_sel_hi:[1,0]
	v_pk_mul_f32 v[22:23], v[144:145], v[22:23]
	v_pk_mul_f32 v[20:21], v[140:141], v[20:21]
	v_pk_mul_f32 v[28:29], v[134:135], v[28:29]
	v_pk_mul_f32 v[24:25], v[132:133], v[24:25]
	s_and_b64 vcc, exec, s[42:43]
	v_pk_mul_f32 v[32:33], v[130:131], v[32:33]
	s_cbranch_vccnz .LBB0_674
	v_add_u32_e32 v36, 0xa0, v216
	v_ashrrev_i32_e32 v36, 6, v36
	v_cvt_f32_i32_e32 v43, v36
	v_mul_f32_e32 v36, v0, v43
	v_mul_f32_e32 v37, v165, v43
	v_mul_f32_e32 v40, v167, v43
	v_floor_f32_e32 v36, v36
	v_floor_f32_e32 v37, v37
	v_floor_f32_e32 v40, v40
	v_mul_f32_e32 v46, v169, v43
	v_fma_f32 v38, v0, v43, -v36
	v_fma_f32 v39, v165, v43, -v37
	v_fma_f32 v40, v167, v43, -v40
	v_floor_f32_e32 v46, v46
	v_sin_f32_e32 v36, v38
	v_sin_f32_e32 v37, v39
	v_cos_f32_e32 v45, v40
	v_sin_f32_e32 v48, v40
	v_fma_f32 v43, v169, v43, -v46
	v_cos_f32_e32 v38, v38
	v_cos_f32_e32 v39, v39
	v_sin_f32_e32 v47, v43
	v_cos_f32_e32 v46, v43
	v_pk_mul_f32 v[40:41], v[36:37], v[30:31]
	v_mul_f32_e32 v44, v48, v20
	v_mul_f32_e32 v50, v45, v20
	v_mov_b32_e32 v20, v23
	v_pk_mul_f32 v[30:31], v[38:39], v[30:31]
	v_mul_f32_e32 v42, v45, v22
	v_mul_f32_e32 v48, v48, v22
	v_pk_mul_f32 v[22:23], v[46:47], v[20:21]
	v_pk_fma_f32 v[38:39], v[38:39], v[34:35], v[40:41] neg_lo:[0,0,1] neg_hi:[0,0,1]
	v_floor_f32_e32 v40, v102
	v_mov_b32_e32 v43, v22
	v_mov_b32_e32 v45, v23
	v_mov_b32_e32 v22, v47
	v_mov_b32_e32 v23, v46
	v_pk_fma_f32 v[30:31], v[36:37], v[34:35], v[30:31]
	v_floor_f32_e32 v34, v104
	v_fma_f32 v40, v167, v100, -v40
	v_floor_f32_e32 v46, v101
	v_pk_mul_f32 v[20:21], v[22:23], v[20:21]
	v_pk_add_f32 v[22:23], v[42:43], v[44:45] neg_lo:[0,1] neg_hi:[0,1]
	v_fma_f32 v35, v0, v100, -v34
	v_cos_f32_e32 v43, v40
	v_sin_f32_e32 v45, v40
	v_fma_f32 v46, v169, v100, -v46
	v_sin_f32_e32 v34, v35
	v_cos_f32_e32 v36, v35
	v_floor_f32_e32 v35, v103
	v_sin_f32_e32 v47, v46
	v_cos_f32_e32 v46, v46
	v_fma_f32 v37, v165, v100, -v35
	v_mov_b32_e32 v49, v20
	v_mov_b32_e32 v51, v21
	v_sin_f32_e32 v35, v37
	v_pk_add_f32 v[20:21], v[48:49], v[50:51]
	v_cos_f32_e32 v37, v37
	v_mul_f32_e32 v44, v45, v24
	v_mul_f32_e32 v50, v43, v24
	v_mov_b32_e32 v24, v27
	v_mul_f32_e32 v42, v43, v26
	v_mul_f32_e32 v48, v45, v26
	v_pk_mul_f32 v[26:27], v[46:47], v[24:25]
	v_pk_mul_f32 v[40:41], v[34:35], v[32:33]
	v_mov_b32_e32 v43, v26
	v_mov_b32_e32 v45, v27
	v_mov_b32_e32 v26, v47
	v_mov_b32_e32 v27, v46
	v_pk_mul_f32 v[24:25], v[26:27], v[24:25]
	v_pk_mul_f32 v[32:33], v[36:37], v[32:33]
	v_mov_b32_e32 v49, v24
	v_mov_b32_e32 v51, v25
	v_pk_fma_f32 v[36:37], v[36:37], v[28:29], v[40:41] neg_lo:[0,0,1] neg_hi:[0,0,1]
	v_pk_add_f32 v[26:27], v[42:43], v[44:45] neg_lo:[0,1] neg_hi:[0,1]
	v_pk_fma_f32 v[32:33], v[34:35], v[28:29], v[32:33]
	v_pk_add_f32 v[24:25], v[48:49], v[50:51]
	v_mov_b32_e32 v34, v38
	v_mov_b32_e32 v35, v39
	v_mov_b32_e32 v28, v36
	v_mov_b32_e32 v29, v37
.LBB0_674:
	s_mov_b32 s2, 0x28000
	v_add_co_u32_e32 v18, vcc, s2, v18
	v_pk_mul_f32 v[22:23], v[22:23], s[12:13] op_sel_hi:[1,0]
	v_pk_mul_f32 v[34:35], v[34:35], s[12:13] op_sel_hi:[1,0]
	v_pk_mul_f32 v[20:21], v[20:21], s[12:13] op_sel_hi:[1,0]
	v_addc_co_u32_e32 v19, vcc, 0, v19, vcc
	v_pk_mul_f32 v[30:31], v[30:31], s[12:13] op_sel_hi:[1,0]
	v_pk_mul_f32 v[26:27], v[26:27], s[12:13] op_sel_hi:[1,0]
	v_pk_mul_f32 v[28:29], v[28:29], s[12:13] op_sel_hi:[1,0]
	v_pk_mul_f32 v[24:25], v[24:25], s[12:13] op_sel_hi:[1,0]
	v_cvt_pk_bf16_f32 v240, v34, v35
	v_cvt_pk_bf16_f32 v241, v22, v23
	v_mbcnt_lo_u32_b32 v252, -1, 0
	v_mbcnt_hi_u32_b32 v252, -1, v252
	v_bfe_u32 v252, v252, 4, 1
	v_mul_u32_u24_e32 v252, 24, v252
	v_mov_b32_e32 v253, 0
	v_lshl_add_u64 v[248:249], v[18:19], 0, v[252:253]
	v_cvt_pk_bf16_f32 v242, v30, v31
	v_cvt_pk_bf16_f32 v243, v20, v21
	s_nop 1
	v_permlane16_swap_b32_e32 v240, v242
	v_permlane16_swap_b32_e32 v241, v243
	global_store_dwordx4 v[248:249], v[240:243], off
	v_cvt_pk_bf16_f32 v244, v28, v29
	v_cvt_pk_bf16_f32 v245, v26, v27
	v_pk_fma_f32 v[16:17], v[16:17], v[164:165], v[160:161] op_sel_hi:[1,0,1]
	v_pk_fma_f32 v[14:15], v[14:15], v[164:165], v[158:159] op_sel_hi:[1,0,1]
	v_pk_mul_f32 v[32:33], v[32:33], s[12:13] op_sel_hi:[1,0]
	s_nop 0
	v_cvt_pk_bf16_f32 v246, v32, v33
	v_cvt_pk_bf16_f32 v247, v24, v25
	v_pk_fma_f32 v[24:25], v[2:3], v[164:165], v[146:147] op_sel_hi:[1,0,1]
	v_mul_f32_e32 v2, v15, v15
	v_mul_f32_e32 v3, v17, v17
	v_pk_fma_f32 v[12:13], v[12:13], v[164:165], v[156:157] op_sel_hi:[1,0,1]
	v_pk_fma_f32 v[10:11], v[10:11], v[164:165], v[154:155] op_sel_hi:[1,0,1]
	v_fmac_f32_e32 v2, v14, v14
	v_fmac_f32_e32 v3, v16, v16
	v_pk_fma_f32 v[22:23], v[6:7], v[164:165], v[150:151] op_sel_hi:[1,0,1]
	v_add_f32_e32 v2, v2, v3
	v_mul_f32_e32 v3, v11, v11
	v_mul_f32_e32 v6, v13, v13
	v_fmac_f32_e32 v3, v10, v10
	v_fmac_f32_e32 v6, v12, v12
	v_pk_fma_f32 v[8:9], v[8:9], v[164:165], v[152:153] op_sel_hi:[1,0,1]
	v_add_f32_e32 v3, v3, v6
	v_add_f32_e32 v2, v2, v3
	v_mul_f32_e32 v3, v23, v23
	v_mul_f32_e32 v6, v9, v9
	v_fmac_f32_e32 v3, v22, v22
	v_fmac_f32_e32 v6, v8, v8
	v_pk_fma_f32 v[4:5], v[4:5], v[164:165], v[148:149] op_sel_hi:[1,0,1]
	v_add_f32_e32 v3, v3, v6
	v_add_f32_e32 v2, v3, v2
	v_mul_f32_e32 v3, v25, v25
	v_mul_f32_e32 v6, v5, v5
	v_fmac_f32_e32 v3, v24, v24
	v_fmac_f32_e32 v6, v4, v4
	v_add_f32_e32 v3, v3, v6
	v_add_f32_e32 v2, v3, v2
	v_mov_b32_e32 v3, v2
	s_nop 1
	v_permlane16_swap_b32_e32 v2, v3
	v_add_f32_e32 v2, v2, v3
	v_mov_b32_e32 v3, v2
	s_nop 1
	v_permlane32_swap_b32_e32 v2, v3
	v_add_f32_e32 v2, v2, v3
	v_fmamk_f32 v2, v2, 0x3c800000, v223
	v_rsq_f32_e32 v26, v2
	v_mov_b64_e32 v[2:3], 0
	s_nop 1
	v_permlane16_swap_b32_e32 v244, v246
	v_permlane16_swap_b32_e32 v245, v247
	global_store_dwordx4 v[248:249], v[244:247], off offset:64
	v_pk_mul_f32 v[10:11], v[10:11], v[26:27] op_sel_hi:[1,0]
	v_pk_mul_f32 v[2:3], v[14:15], v[26:27] op_sel_hi:[1,0]
	v_pk_mul_f32 v[6:7], v[16:17], v[26:27] op_sel_hi:[1,0]
	v_pk_mul_f32 v[16:17], v[142:143], v[2:3]
	v_pk_mul_f32 v[2:3], v[12:13], v[26:27] op_sel_hi:[1,0]
	v_pk_mul_f32 v[12:13], v[138:139], v[10:11]
	v_pk_mul_f32 v[10:11], v[22:23], v[26:27] op_sel_hi:[1,0]
	v_pk_mul_f32 v[8:9], v[8:9], v[26:27] op_sel_hi:[1,0]
	v_pk_mul_f32 v[14:15], v[24:25], v[26:27] op_sel_hi:[1,0]
	v_pk_mul_f32 v[4:5], v[4:5], v[26:27] op_sel_hi:[1,0]
	v_pk_mul_f32 v[6:7], v[144:145], v[6:7]
	v_pk_mul_f32 v[2:3], v[140:141], v[2:3]
	v_pk_mul_f32 v[8:9], v[136:137], v[8:9]
	v_pk_mul_f32 v[10:11], v[134:135], v[10:11]
	v_pk_mul_f32 v[4:5], v[132:133], v[4:5]
	s_and_b64 vcc, exec, s[42:43]
	v_pk_mul_f32 v[14:15], v[130:131], v[14:15]
	s_cbranch_vccnz .LBB0_676
	v_add_u32_e32 v18, 0xb0, v216
	v_ashrrev_i32_e32 v18, 6, v18
	v_cvt_f32_i32_e32 v25, v18
	v_mul_f32_e32 v18, v0, v25
	v_mul_f32_e32 v19, v165, v25
	v_floor_f32_e32 v18, v18
	v_floor_f32_e32 v19, v19
	v_fma_f32 v20, v0, v25, -v18
	v_fma_f32 v21, v165, v25, -v19
	v_sin_f32_e32 v18, v20
	v_cos_f32_e32 v20, v20
	v_sin_f32_e32 v19, v21
	v_cos_f32_e32 v21, v21
	v_mul_f32_e32 v22, v167, v25
	v_floor_f32_e32 v22, v22
	v_mul_f32_e32 v28, v169, v25
	v_fma_f32 v22, v167, v25, -v22
	v_floor_f32_e32 v28, v28
	v_cos_f32_e32 v27, v22
	v_sin_f32_e32 v30, v22
	v_fma_f32 v25, v169, v25, -v28
	v_pk_mul_f32 v[22:23], v[18:19], v[12:13]
	v_pk_mul_f32 v[12:13], v[20:21], v[12:13]
	v_sin_f32_e32 v29, v25
	v_cos_f32_e32 v28, v25
	v_pk_fma_f32 v[20:21], v[20:21], v[16:17], v[22:23] neg_lo:[0,0,1] neg_hi:[0,0,1]
	v_pk_fma_f32 v[12:13], v[18:19], v[16:17], v[12:13]
	v_floor_f32_e32 v16, v88
	v_fma_f32 v0, v0, v84, -v16
	v_mul_f32_e32 v26, v30, v2
	v_mul_f32_e32 v32, v27, v2
	v_mov_b32_e32 v2, v7
	v_sin_f32_e32 v16, v0
	v_cos_f32_e32 v18, v0
	v_floor_f32_e32 v0, v87
	v_mul_f32_e32 v24, v27, v6
	v_mul_f32_e32 v30, v30, v6
	v_pk_mul_f32 v[6:7], v[28:29], v[2:3]
	v_fma_f32 v0, v165, v84, -v0
	v_mov_b32_e32 v25, v6
	v_mov_b32_e32 v27, v7
	v_mov_b32_e32 v6, v29
	v_mov_b32_e32 v7, v28
	v_sin_f32_e32 v17, v0
	v_cos_f32_e32 v19, v0
	v_floor_f32_e32 v0, v86
	v_pk_mul_f32 v[2:3], v[6:7], v[2:3]
	v_pk_add_f32 v[6:7], v[24:25], v[26:27] neg_lo:[0,1] neg_hi:[0,1]
	v_fma_f32 v0, v167, v84, -v0
	v_floor_f32_e32 v27, v85
	v_cos_f32_e32 v25, v0
	v_sin_f32_e32 v0, v0
	v_fma_f32 v27, v169, v84, -v27
	v_sin_f32_e32 v29, v27
	v_cos_f32_e32 v28, v27
	v_mov_b32_e32 v31, v2
	v_mov_b32_e32 v33, v3
	v_pk_add_f32 v[2:3], v[30:31], v[32:33]
	v_mul_f32_e32 v26, v0, v4
	v_mul_f32_e32 v32, v25, v4
	v_mov_b32_e32 v4, v9
	v_mul_f32_e32 v24, v25, v8
	v_mul_f32_e32 v30, v0, v8
	v_pk_mul_f32 v[8:9], v[28:29], v[4:5]
	v_pk_mul_f32 v[22:23], v[16:17], v[14:15]
	v_mov_b32_e32 v25, v8
	v_mov_b32_e32 v27, v9
	v_mov_b32_e32 v8, v29
	v_mov_b32_e32 v9, v28
	v_pk_mul_f32 v[4:5], v[8:9], v[4:5]
	v_pk_mul_f32 v[14:15], v[18:19], v[14:15]
	v_mov_b32_e32 v31, v4
	v_mov_b32_e32 v33, v5
	v_pk_fma_f32 v[18:19], v[18:19], v[10:11], v[22:23] neg_lo:[0,0,1] neg_hi:[0,0,1]
	v_pk_add_f32 v[8:9], v[24:25], v[26:27] neg_lo:[0,1] neg_hi:[0,1]
	v_pk_fma_f32 v[14:15], v[16:17], v[10:11], v[14:15]
	v_pk_add_f32 v[4:5], v[30:31], v[32:33]
	v_mov_b32_e32 v16, v20
	v_mov_b32_e32 v17, v21
	v_mov_b32_e32 v10, v18
	v_mov_b32_e32 v11, v19
.LBB0_676:
	v_pk_mul_f32 v[6:7], v[6:7], s[12:13] op_sel_hi:[1,0]
	v_pk_mul_f32 v[16:17], v[16:17], s[12:13] op_sel_hi:[1,0]
	s_mov_b32 s2, 0x2c000
	v_cvt_pk_bf16_f32 v240, v16, v17
	v_cvt_pk_bf16_f32 v241, v6, v7
	v_add_co_u32_e32 v6, vcc, s2, v162
	v_pk_mul_f32 v[2:3], v[2:3], s[12:13] op_sel_hi:[1,0]
	v_pk_mul_f32 v[12:13], v[12:13], s[12:13] op_sel_hi:[1,0]
	v_addc_co_u32_e32 v7, vcc, 0, v163, vcc
	v_pk_mul_f32 v[8:9], v[8:9], s[12:13] op_sel_hi:[1,0]
	v_pk_mul_f32 v[10:11], v[10:11], s[12:13] op_sel_hi:[1,0]
	v_mbcnt_lo_u32_b32 v252, -1, 0
	v_mbcnt_hi_u32_b32 v252, -1, v252
	v_bfe_u32 v252, v252, 4, 1
	v_mul_u32_u24_e32 v252, 24, v252
	v_mov_b32_e32 v253, 0
	v_lshl_add_u64 v[248:249], v[6:7], 0, v[252:253]
	v_cvt_pk_bf16_f32 v242, v12, v13
	v_cvt_pk_bf16_f32 v243, v2, v3
	s_nop 1
	v_permlane16_swap_b32_e32 v240, v242
	v_permlane16_swap_b32_e32 v241, v243
	global_store_dwordx4 v[248:249], v[240:243], off
	v_cvt_pk_bf16_f32 v244, v10, v11
	v_cvt_pk_bf16_f32 v245, v8, v9
	v_pk_mul_f32 v[4:5], v[4:5], s[12:13] op_sel_hi:[1,0]
	v_pk_mul_f32 v[14:15], v[14:15], s[12:13] op_sel_hi:[1,0]
	s_nop 0
	v_cvt_pk_bf16_f32 v246, v14, v15
	v_cvt_pk_bf16_f32 v247, v4, v5
	s_nop 1
	v_permlane16_swap_b32_e32 v244, v246
	v_permlane16_swap_b32_e32 v245, v247
	global_store_dwordx4 v[248:249], v[244:247], off offset:64
	s_andn2_b64 vcc, exec, s[40:41]
	s_mov_b64 s[2:3], -1
	s_cbranch_vccnz .LBB0_592
